# MFMA order variant N8 (n-major snake: accumulator pairs, SrcA reuse between pairs), all 12 loops
# speedup vs baseline: 1.0235x; 1.0002x over previous
.LBB0_272:
	s_add_u32 s58, s22, 0xfff00000
	s_addc_u32 s59, s23, -1
	s_mov_b32 m0, s36
	ds_read_b128 v[154:157], v148
	global_load_lds_dwordx4 v130, s[58:59]
	s_mov_b32 m0, s37
	ds_read_b128 v[158:161], v148 offset:1024
	global_load_lds_dwordx4 v134, s[58:59]
	s_mov_b32 m0, s40
	ds_read_b128 v[164:167], v148 offset:2048
	global_load_lds_dwordx4 v142, s[22:23]
	s_mov_b32 m0, s41
	ds_read_b128 v[168:171], v148 offset:3072
	global_load_lds_dwordx4 v144, s[22:23]
	ds_read_b128 v[172:175], v149
	ds_read_b128 v[176:179], v149 offset:1024
	ds_read_b128 v[180:183], v149 offset:2048
	ds_read_b128 v[184:187], v149 offset:3072
	s_add_u32 s24, s22, 0xfff00080
	s_addc_u32 s25, s23, -1
	s_cmp_eq_u32 s56, 60
	s_cselect_b32 s27, s51, s25
	s_cselect_b32 s26, s52, s24
	s_cselect_b32 s25, s7, s55
	s_cselect_b32 s24, s53, s54
	ds_read_b128 v[188:191], v150
	ds_read_b128 v[192:195], v150 offset:1024
	ds_read_b128 v[196:199], v150 offset:2048
	ds_read_b128 v[200:203], v150 offset:3072
	ds_read_b128 v[204:207], v150 offset:4096
	ds_read_b128 v[208:211], v150 offset:5120
	ds_read_b128 v[212:215], v150 offset:6144
	ds_read_b128 v[216:219], v150 offset:7168
	s_waitcnt vmcnt(8)
	s_waitcnt lgkmcnt(0)
	s_barrier
	s_setprio 1
	s_waitcnt lgkmcnt(0)
	v_mfma_f32_16x16x32_bf16 v[126:129], v[154:157], v[188:191], v[126:129]
	v_mfma_f32_16x16x32_bf16 v[126:129], v[158:161], v[192:195], v[126:129]
	v_mfma_f32_16x16x32_bf16 v[118:121], v[158:161], v[200:203], v[118:121]
	v_mfma_f32_16x16x32_bf16 v[118:121], v[154:157], v[196:199], v[118:121]
	v_mfma_f32_16x16x32_bf16 v[102:105], v[154:157], v[204:207], v[102:105]
	v_mfma_f32_16x16x32_bf16 v[102:105], v[158:161], v[208:211], v[102:105]
	v_mfma_f32_16x16x32_bf16 v[86:89], v[158:161], v[216:219], v[86:89]
	v_mfma_f32_16x16x32_bf16 v[86:89], v[154:157], v[212:215], v[86:89]
	v_mfma_f32_16x16x32_bf16 v[82:85], v[164:167], v[212:215], v[82:85]
	v_mfma_f32_16x16x32_bf16 v[82:85], v[168:171], v[216:219], v[82:85]
	v_mfma_f32_16x16x32_bf16 v[98:101], v[168:171], v[208:211], v[98:101]
	v_mfma_f32_16x16x32_bf16 v[98:101], v[164:167], v[204:207], v[98:101]
	v_mfma_f32_16x16x32_bf16 v[114:117], v[164:167], v[196:199], v[114:117]
	v_mfma_f32_16x16x32_bf16 v[114:117], v[168:171], v[200:203], v[114:117]
	v_mfma_f32_16x16x32_bf16 v[122:125], v[168:171], v[192:195], v[122:125]
	v_mfma_f32_16x16x32_bf16 v[122:125], v[164:167], v[188:191], v[122:125]
	v_mfma_f32_16x16x32_bf16 v[110:113], v[172:175], v[188:191], v[110:113]
	v_mfma_f32_16x16x32_bf16 v[110:113], v[176:179], v[192:195], v[110:113]
	v_mfma_f32_16x16x32_bf16 v[94:97], v[176:179], v[200:203], v[94:97]
	v_mfma_f32_16x16x32_bf16 v[94:97], v[172:175], v[196:199], v[94:97]
	v_mfma_f32_16x16x32_bf16 v[78:81], v[172:175], v[204:207], v[78:81]
	v_mfma_f32_16x16x32_bf16 v[78:81], v[176:179], v[208:211], v[78:81]
	v_mfma_f32_16x16x32_bf16 v[70:73], v[176:179], v[216:219], v[70:73]
	v_mfma_f32_16x16x32_bf16 v[70:73], v[172:175], v[212:215], v[70:73]
	v_mfma_f32_16x16x32_bf16 v[66:69], v[180:183], v[212:215], v[66:69]
	v_mfma_f32_16x16x32_bf16 v[66:69], v[184:187], v[216:219], v[66:69]
	v_mfma_f32_16x16x32_bf16 v[74:77], v[184:187], v[208:211], v[74:77]
	v_mfma_f32_16x16x32_bf16 v[74:77], v[180:183], v[204:207], v[74:77]
	v_mfma_f32_16x16x32_bf16 v[90:93], v[180:183], v[196:199], v[90:93]
	v_mfma_f32_16x16x32_bf16 v[90:93], v[184:187], v[200:203], v[90:93]
	v_mfma_f32_16x16x32_bf16 v[106:109], v[184:187], v[192:195], v[106:109]
	v_mfma_f32_16x16x32_bf16 v[106:109], v[180:183], v[188:191], v[106:109]
	s_setprio 0
	s_barrier
	s_mov_b32 m0, s42
	s_add_u32 s58, s24, 0x100000
	global_load_lds_dwordx4 v132, s[24:25]
	s_mov_b32 m0, s43
	s_addc_u32 s59, s25, 0
	global_load_lds_dwordx4 v136, s[24:25]
	s_mov_b32 m0, s44
	ds_read_b128 v[188:191], v150 offset:16384
	global_load_lds_dwordx4 v132, s[58:59]
	s_mov_b32 m0, s45
	ds_read_b128 v[192:195], v150 offset:17408
	global_load_lds_dwordx4 v136, s[58:59]
	ds_read_b128 v[196:199], v150 offset:18432
	ds_read_b128 v[200:203], v150 offset:19456
	ds_read_b128 v[204:207], v150 offset:20480
	ds_read_b128 v[208:211], v150 offset:21504
	ds_read_b128 v[212:215], v150 offset:22528
	ds_read_b128 v[216:219], v150 offset:23552
	s_waitcnt vmcnt(6)
	s_waitcnt lgkmcnt(0)
	s_barrier
	s_setprio 1
	s_waitcnt lgkmcnt(0)
	v_mfma_f32_16x16x32_bf16 v[62:65], v[154:157], v[188:191], v[62:65]
	v_mfma_f32_16x16x32_bf16 v[62:65], v[158:161], v[192:195], v[62:65]
	v_mfma_f32_16x16x32_bf16 v[54:57], v[158:161], v[200:203], v[54:57]
	v_mfma_f32_16x16x32_bf16 v[54:57], v[154:157], v[196:199], v[54:57]
	v_mfma_f32_16x16x32_bf16 v[38:41], v[154:157], v[204:207], v[38:41]
	v_mfma_f32_16x16x32_bf16 v[38:41], v[158:161], v[208:211], v[38:41]
	v_mfma_f32_16x16x32_bf16 v[22:25], v[158:161], v[216:219], v[22:25]
	v_mfma_f32_16x16x32_bf16 v[22:25], v[154:157], v[212:215], v[22:25]
	v_mfma_f32_16x16x32_bf16 v[18:21], v[164:167], v[212:215], v[18:21]
	v_mfma_f32_16x16x32_bf16 v[18:21], v[168:171], v[216:219], v[18:21]
	v_mfma_f32_16x16x32_bf16 v[34:37], v[168:171], v[208:211], v[34:37]
	v_mfma_f32_16x16x32_bf16 v[34:37], v[164:167], v[204:207], v[34:37]
	v_mfma_f32_16x16x32_bf16 v[50:53], v[164:167], v[196:199], v[50:53]
	v_mfma_f32_16x16x32_bf16 v[50:53], v[168:171], v[200:203], v[50:53]
	v_mfma_f32_16x16x32_bf16 v[58:61], v[168:171], v[192:195], v[58:61]
	v_mfma_f32_16x16x32_bf16 v[58:61], v[164:167], v[188:191], v[58:61]
	v_mfma_f32_16x16x32_bf16 v[46:49], v[172:175], v[188:191], v[46:49]
	v_mfma_f32_16x16x32_bf16 v[46:49], v[176:179], v[192:195], v[46:49]
	v_mfma_f32_16x16x32_bf16 v[30:33], v[176:179], v[200:203], v[30:33]
	v_mfma_f32_16x16x32_bf16 v[30:33], v[172:175], v[196:199], v[30:33]
	v_mfma_f32_16x16x32_bf16 v[14:17], v[172:175], v[204:207], v[14:17]
	v_mfma_f32_16x16x32_bf16 v[14:17], v[176:179], v[208:211], v[14:17]
	v_mfma_f32_16x16x32_bf16 v[6:9], v[176:179], v[216:219], v[6:9]
	v_mfma_f32_16x16x32_bf16 v[6:9], v[172:175], v[212:215], v[6:9]
	v_mfma_f32_16x16x32_bf16 v[2:5], v[180:183], v[212:215], v[2:5]
	v_mfma_f32_16x16x32_bf16 v[2:5], v[184:187], v[216:219], v[2:5]
	v_mfma_f32_16x16x32_bf16 v[10:13], v[184:187], v[208:211], v[10:13]
	v_mfma_f32_16x16x32_bf16 v[10:13], v[180:183], v[204:207], v[10:13]
	v_mfma_f32_16x16x32_bf16 v[26:29], v[180:183], v[196:199], v[26:29]
	v_mfma_f32_16x16x32_bf16 v[26:29], v[184:187], v[200:203], v[26:29]
	v_mfma_f32_16x16x32_bf16 v[42:45], v[184:187], v[192:195], v[42:45]
	v_mfma_f32_16x16x32_bf16 v[42:45], v[180:183], v[188:191], v[42:45]
	s_setprio 0
	s_barrier
	s_mov_b32 m0, s30
	ds_read_b128 v[154:157], v151
	global_load_lds_dwordx4 v130, s[26:27]
	s_mov_b32 m0, s31
	ds_read_b128 v[158:161], v151 offset:1024
	global_load_lds_dwordx4 v134, s[26:27]
	s_add_u32 s26, s26, 0x100000
	s_addc_u32 s27, s27, 0
	s_mov_b32 m0, s33
	ds_read_b128 v[164:167], v151 offset:2048
	global_load_lds_dwordx4 v130, s[26:27]
	s_mov_b32 m0, s34
	ds_read_b128 v[168:171], v151 offset:3072
	global_load_lds_dwordx4 v134, s[26:27]
	ds_read_b128 v[172:175], v152
	ds_read_b128 v[176:179], v152 offset:1024
	ds_read_b128 v[180:183], v152 offset:2048
	ds_read_b128 v[184:187], v152 offset:3072
	ds_read_b128 v[188:191], v150 offset:32768
	ds_read_b128 v[192:195], v150 offset:33792
	ds_read_b128 v[196:199], v150 offset:34816
	ds_read_b128 v[200:203], v150 offset:35840
	ds_read_b128 v[204:207], v150 offset:36864
	ds_read_b128 v[208:211], v150 offset:37888
	ds_read_b128 v[212:215], v150 offset:38912
	ds_read_b128 v[216:219], v150 offset:39936
	s_waitcnt vmcnt(8)
	s_waitcnt lgkmcnt(0)
	s_barrier
	s_setprio 1
	s_waitcnt lgkmcnt(0)
	v_mfma_f32_16x16x32_bf16 v[126:129], v[154:157], v[188:191], v[126:129]
	v_mfma_f32_16x16x32_bf16 v[126:129], v[158:161], v[192:195], v[126:129]
	v_mfma_f32_16x16x32_bf16 v[118:121], v[158:161], v[200:203], v[118:121]
	v_mfma_f32_16x16x32_bf16 v[118:121], v[154:157], v[196:199], v[118:121]
	v_mfma_f32_16x16x32_bf16 v[102:105], v[154:157], v[204:207], v[102:105]
	v_mfma_f32_16x16x32_bf16 v[102:105], v[158:161], v[208:211], v[102:105]
	v_mfma_f32_16x16x32_bf16 v[86:89], v[158:161], v[216:219], v[86:89]
	v_mfma_f32_16x16x32_bf16 v[86:89], v[154:157], v[212:215], v[86:89]
	v_mfma_f32_16x16x32_bf16 v[82:85], v[164:167], v[212:215], v[82:85]
	v_mfma_f32_16x16x32_bf16 v[82:85], v[168:171], v[216:219], v[82:85]
	v_mfma_f32_16x16x32_bf16 v[98:101], v[168:171], v[208:211], v[98:101]
	v_mfma_f32_16x16x32_bf16 v[98:101], v[164:167], v[204:207], v[98:101]
	v_mfma_f32_16x16x32_bf16 v[114:117], v[164:167], v[196:199], v[114:117]
	v_mfma_f32_16x16x32_bf16 v[114:117], v[168:171], v[200:203], v[114:117]
	v_mfma_f32_16x16x32_bf16 v[122:125], v[168:171], v[192:195], v[122:125]
	v_mfma_f32_16x16x32_bf16 v[122:125], v[164:167], v[188:191], v[122:125]
	v_mfma_f32_16x16x32_bf16 v[110:113], v[172:175], v[188:191], v[110:113]
	v_mfma_f32_16x16x32_bf16 v[110:113], v[176:179], v[192:195], v[110:113]
	v_mfma_f32_16x16x32_bf16 v[94:97], v[176:179], v[200:203], v[94:97]
	v_mfma_f32_16x16x32_bf16 v[94:97], v[172:175], v[196:199], v[94:97]
	v_mfma_f32_16x16x32_bf16 v[78:81], v[172:175], v[204:207], v[78:81]
	v_mfma_f32_16x16x32_bf16 v[78:81], v[176:179], v[208:211], v[78:81]
	v_mfma_f32_16x16x32_bf16 v[70:73], v[176:179], v[216:219], v[70:73]
	v_mfma_f32_16x16x32_bf16 v[70:73], v[172:175], v[212:215], v[70:73]
	v_mfma_f32_16x16x32_bf16 v[66:69], v[180:183], v[212:215], v[66:69]
	v_mfma_f32_16x16x32_bf16 v[66:69], v[184:187], v[216:219], v[66:69]
	v_mfma_f32_16x16x32_bf16 v[74:77], v[184:187], v[208:211], v[74:77]
	v_mfma_f32_16x16x32_bf16 v[74:77], v[180:183], v[204:207], v[74:77]
	v_mfma_f32_16x16x32_bf16 v[90:93], v[180:183], v[196:199], v[90:93]
	v_mfma_f32_16x16x32_bf16 v[90:93], v[184:187], v[200:203], v[90:93]
	v_mfma_f32_16x16x32_bf16 v[106:109], v[184:187], v[192:195], v[106:109]
	v_mfma_f32_16x16x32_bf16 v[106:109], v[180:183], v[188:191], v[106:109]
	s_setprio 0
	s_barrier
	s_mov_b32 m0, s47
	s_add_u32 s24, s24, 0x80
	s_addc_u32 s25, s25, 0
	global_load_lds_dwordx4 v132, s[24:25]
	s_mov_b32 m0, s48
	ds_read_b128 v[188:191], v150 offset:49152
	global_load_lds_dwordx4 v136, s[24:25]
	s_add_i32 s26, s46, s29
	s_mov_b32 m0, s26
	s_add_u32 s24, s24, 0x100000
	s_addc_u32 s25, s25, 0
	global_load_lds_dwordx4 v132, s[24:25]
	s_add_i32 m0, s26, 0x2000
	ds_read_b128 v[192:195], v150 offset:50176
	global_load_lds_dwordx4 v136, s[24:25]
	ds_read_b128 v[196:199], v150 offset:51200
	ds_read_b128 v[200:203], v150 offset:52224
	ds_read_b128 v[204:207], v150 offset:53248
	ds_read_b128 v[208:211], v150 offset:54272
	ds_read_b128 v[212:215], v150 offset:55296
	ds_read_b128 v[216:219], v150 offset:56320
	s_waitcnt vmcnt(6)
	s_waitcnt lgkmcnt(0)
	s_barrier
	s_setprio 1
	s_waitcnt lgkmcnt(0)
	v_mfma_f32_16x16x32_bf16 v[62:65], v[154:157], v[188:191], v[62:65]
	v_mfma_f32_16x16x32_bf16 v[62:65], v[158:161], v[192:195], v[62:65]
	v_mfma_f32_16x16x32_bf16 v[54:57], v[158:161], v[200:203], v[54:57]
	v_mfma_f32_16x16x32_bf16 v[54:57], v[154:157], v[196:199], v[54:57]
	v_mfma_f32_16x16x32_bf16 v[38:41], v[154:157], v[204:207], v[38:41]
	v_mfma_f32_16x16x32_bf16 v[38:41], v[158:161], v[208:211], v[38:41]
	v_mfma_f32_16x16x32_bf16 v[22:25], v[158:161], v[216:219], v[22:25]
	v_mfma_f32_16x16x32_bf16 v[22:25], v[154:157], v[212:215], v[22:25]
	v_mfma_f32_16x16x32_bf16 v[18:21], v[164:167], v[212:215], v[18:21]
	v_mfma_f32_16x16x32_bf16 v[18:21], v[168:171], v[216:219], v[18:21]
	v_mfma_f32_16x16x32_bf16 v[34:37], v[168:171], v[208:211], v[34:37]
	v_mfma_f32_16x16x32_bf16 v[34:37], v[164:167], v[204:207], v[34:37]
	v_mfma_f32_16x16x32_bf16 v[50:53], v[164:167], v[196:199], v[50:53]
	v_mfma_f32_16x16x32_bf16 v[50:53], v[168:171], v[200:203], v[50:53]
	v_mfma_f32_16x16x32_bf16 v[58:61], v[168:171], v[192:195], v[58:61]
	v_mfma_f32_16x16x32_bf16 v[58:61], v[164:167], v[188:191], v[58:61]
	v_mfma_f32_16x16x32_bf16 v[46:49], v[172:175], v[188:191], v[46:49]
	v_mfma_f32_16x16x32_bf16 v[46:49], v[176:179], v[192:195], v[46:49]
	v_mfma_f32_16x16x32_bf16 v[30:33], v[176:179], v[200:203], v[30:33]
	v_mfma_f32_16x16x32_bf16 v[30:33], v[172:175], v[196:199], v[30:33]
	v_mfma_f32_16x16x32_bf16 v[14:17], v[172:175], v[204:207], v[14:17]
	v_mfma_f32_16x16x32_bf16 v[14:17], v[176:179], v[208:211], v[14:17]
	v_mfma_f32_16x16x32_bf16 v[6:9], v[176:179], v[216:219], v[6:9]
	v_mfma_f32_16x16x32_bf16 v[6:9], v[172:175], v[212:215], v[6:9]
	v_mfma_f32_16x16x32_bf16 v[2:5], v[180:183], v[212:215], v[2:5]
	v_mfma_f32_16x16x32_bf16 v[2:5], v[184:187], v[216:219], v[2:5]
	v_mfma_f32_16x16x32_bf16 v[10:13], v[184:187], v[208:211], v[10:13]
	v_mfma_f32_16x16x32_bf16 v[10:13], v[180:183], v[204:207], v[10:13]
	v_mfma_f32_16x16x32_bf16 v[26:29], v[180:183], v[196:199], v[26:29]
	v_mfma_f32_16x16x32_bf16 v[26:29], v[184:187], v[200:203], v[26:29]
	v_mfma_f32_16x16x32_bf16 v[42:45], v[184:187], v[192:195], v[42:45]
	v_mfma_f32_16x16x32_bf16 v[42:45], v[180:183], v[188:191], v[42:45]
	s_setprio 0
	s_barrier
	s_add_i32 s56, s56, 2
	s_add_u32 s22, s22, 0x100
	s_addc_u32 s23, s23, 0
	s_add_u32 s54, s54, 0x100
	s_addc_u32 s55, s55, 0
	s_cmp_gt_u32 s56, 61
	s_cbranch_scc0 .LBB0_272
	s_and_b64 vcc, exec, s[16:17]
	s_cbranch_vccz .LBB0_277
	s_barrier
	v_lshl_add_u32 v138, s50, 8, v1
	s_cmp_gt_i32 s49, 63
	s_mov_b64 s[22:23], -1
	s_cbranch_scc1 .LBB0_278

.LBB0_1009:
	ds_read_b128 v[142:145], v155
	ds_read_b128 v[158:161], v155 offset:1024
	ds_read_b128 v[168:171], v155 offset:2048
	ds_read_b128 v[176:179], v155 offset:3072
	ds_read_b128 v[180:183], v156
	ds_read_b128 v[184:187], v156 offset:1024
	ds_read_b128 v[188:191], v156 offset:2048
	ds_read_b128 v[192:195], v156 offset:3072
	s_add_u32 s24, s22, 0xfff00080
	s_addc_u32 s25, s23, -1
	s_cmp_eq_u32 s51, 60
	s_cselect_b32 s27, s19, s25
	s_cselect_b32 s26, s47, s24
	s_cselect_b32 s25, s7, s50
	s_cselect_b32 s24, s48, s49
	s_mov_b32 m0, s40
	v_lshl_add_u64 v[146:147], s[22:23], 0, v[138:139]
	ds_read_b128 v[202:205], v157
	ds_read_b128 v[206:209], v157 offset:1024
	ds_read_b128 v[210:213], v157 offset:2048
	ds_read_b128 v[214:217], v157 offset:3072
	ds_read_b128 v[218:221], v157 offset:4096
	ds_read_b128 v[222:225], v157 offset:5120
	ds_read_b128 v[226:229], v157 offset:6144
	ds_read_b128 v[230:233], v157 offset:7168
	global_load_lds_dwordx4 v[146:147], off
	v_lshl_add_u64 v[146:147], s[22:23], 0, v[140:141]
	s_mov_b32 m0, s41
	s_nop 0
	global_load_lds_dwordx4 v[146:147], off
	s_waitcnt vmcnt(8)
	s_waitcnt lgkmcnt(0)
	s_barrier
	s_setprio 1
	s_waitcnt lgkmcnt(0)
	v_mfma_f32_16x16x32_bf16 v[126:129], v[142:145], v[202:205], v[126:129]
	v_mfma_f32_16x16x32_bf16 v[126:129], v[158:161], v[206:209], v[126:129]
	v_mfma_f32_16x16x32_bf16 v[110:113], v[158:161], v[214:217], v[110:113]
	v_mfma_f32_16x16x32_bf16 v[110:113], v[142:145], v[210:213], v[110:113]
	v_mfma_f32_16x16x32_bf16 v[94:97], v[142:145], v[218:221], v[94:97]
	v_mfma_f32_16x16x32_bf16 v[94:97], v[158:161], v[222:225], v[94:97]
	v_mfma_f32_16x16x32_bf16 v[78:81], v[158:161], v[230:233], v[78:81]
	v_mfma_f32_16x16x32_bf16 v[78:81], v[142:145], v[226:229], v[78:81]
	v_mfma_f32_16x16x32_bf16 v[74:77], v[168:171], v[226:229], v[74:77]
	v_mfma_f32_16x16x32_bf16 v[74:77], v[176:179], v[230:233], v[74:77]
	v_mfma_f32_16x16x32_bf16 v[90:93], v[176:179], v[222:225], v[90:93]
	v_mfma_f32_16x16x32_bf16 v[90:93], v[168:171], v[218:221], v[90:93]
	v_mfma_f32_16x16x32_bf16 v[106:109], v[168:171], v[210:213], v[106:109]
	v_mfma_f32_16x16x32_bf16 v[106:109], v[176:179], v[214:217], v[106:109]
	v_mfma_f32_16x16x32_bf16 v[122:125], v[176:179], v[206:209], v[122:125]
	v_mfma_f32_16x16x32_bf16 v[122:125], v[168:171], v[202:205], v[122:125]
	v_mfma_f32_16x16x32_bf16 v[118:121], v[180:183], v[202:205], v[118:121]
	v_mfma_f32_16x16x32_bf16 v[118:121], v[184:187], v[206:209], v[118:121]
	v_mfma_f32_16x16x32_bf16 v[102:105], v[184:187], v[214:217], v[102:105]
	v_mfma_f32_16x16x32_bf16 v[102:105], v[180:183], v[210:213], v[102:105]
	v_mfma_f32_16x16x32_bf16 v[86:89], v[180:183], v[218:221], v[86:89]
	v_mfma_f32_16x16x32_bf16 v[86:89], v[184:187], v[222:225], v[86:89]
	v_mfma_f32_16x16x32_bf16 v[70:73], v[184:187], v[230:233], v[70:73]
	v_mfma_f32_16x16x32_bf16 v[70:73], v[180:183], v[226:229], v[70:73]
	v_mfma_f32_16x16x32_bf16 v[66:69], v[188:191], v[226:229], v[66:69]
	v_mfma_f32_16x16x32_bf16 v[66:69], v[192:195], v[230:233], v[66:69]
	v_mfma_f32_16x16x32_bf16 v[82:85], v[192:195], v[222:225], v[82:85]
	v_mfma_f32_16x16x32_bf16 v[82:85], v[188:191], v[218:221], v[82:85]
	v_mfma_f32_16x16x32_bf16 v[98:101], v[188:191], v[210:213], v[98:101]
	v_mfma_f32_16x16x32_bf16 v[98:101], v[192:195], v[214:217], v[98:101]
	v_mfma_f32_16x16x32_bf16 v[114:117], v[192:195], v[206:209], v[114:117]
	v_mfma_f32_16x16x32_bf16 v[114:117], v[188:191], v[202:205], v[114:117]
	s_setprio 0
	s_barrier
	s_mov_b32 m0, s42
	v_lshl_add_u64 v[146:147], s[24:25], 0, v[132:133]
	s_add_u32 s52, s24, 0x100000
	ds_read_b128 v[202:205], v157 offset:16384
	ds_read_b128 v[206:209], v157 offset:17408
	ds_read_b128 v[210:213], v157 offset:18432
	ds_read_b128 v[214:217], v157 offset:19456
	ds_read_b128 v[218:221], v157 offset:20480
	ds_read_b128 v[222:225], v157 offset:21504
	ds_read_b128 v[226:229], v157 offset:22528
	ds_read_b128 v[230:233], v157 offset:23552
	global_load_lds_dwordx4 v[146:147], off
	v_lshl_add_u64 v[172:173], s[24:25], 0, v[136:137]
	s_mov_b32 m0, s43
	s_addc_u32 s53, s25, 0
	global_load_lds_dwordx4 v[172:173], off
	v_lshl_add_u64 v[196:197], s[52:53], 0, v[132:133]
	s_mov_b32 m0, s44
	v_lshl_add_u64 v[234:235], s[26:27], 0, v[134:135]
	global_load_lds_dwordx4 v[196:197], off
	v_lshl_add_u64 v[196:197], s[52:53], 0, v[136:137]
	s_add_i32 m0, s44, 0x2000
	s_nop 0
	global_load_lds_dwordx4 v[196:197], off
	v_lshl_add_u64 v[196:197], s[26:27], 0, v[130:131]
	s_mov_b32 m0, s33
	s_nop 0
	global_load_lds_dwordx4 v[196:197], off
	s_mov_b32 m0, s34
	s_nop 0
	global_load_lds_dwordx4 v[234:235], off
	s_waitcnt vmcnt(8)
	s_waitcnt lgkmcnt(0)
	s_barrier
	s_setprio 1
	s_waitcnt lgkmcnt(0)
	v_mfma_f32_16x16x32_bf16 v[62:65], v[142:145], v[202:205], v[62:65]
	v_mfma_f32_16x16x32_bf16 v[62:65], v[158:161], v[206:209], v[62:65]
	v_mfma_f32_16x16x32_bf16 v[46:49], v[158:161], v[214:217], v[46:49]
	v_mfma_f32_16x16x32_bf16 v[46:49], v[142:145], v[210:213], v[46:49]
	v_mfma_f32_16x16x32_bf16 v[30:33], v[142:145], v[218:221], v[30:33]
	v_mfma_f32_16x16x32_bf16 v[30:33], v[158:161], v[222:225], v[30:33]
	v_mfma_f32_16x16x32_bf16 v[14:17], v[158:161], v[230:233], v[14:17]
	v_mfma_f32_16x16x32_bf16 v[14:17], v[142:145], v[226:229], v[14:17]
	v_mfma_f32_16x16x32_bf16 v[10:13], v[168:171], v[226:229], v[10:13]
	v_mfma_f32_16x16x32_bf16 v[10:13], v[176:179], v[230:233], v[10:13]
	v_mfma_f32_16x16x32_bf16 v[26:29], v[176:179], v[222:225], v[26:29]
	v_mfma_f32_16x16x32_bf16 v[26:29], v[168:171], v[218:221], v[26:29]
	v_mfma_f32_16x16x32_bf16 v[42:45], v[168:171], v[210:213], v[42:45]
	v_mfma_f32_16x16x32_bf16 v[42:45], v[176:179], v[214:217], v[42:45]
	v_mfma_f32_16x16x32_bf16 v[58:61], v[176:179], v[206:209], v[58:61]
	v_mfma_f32_16x16x32_bf16 v[58:61], v[168:171], v[202:205], v[58:61]
	v_mfma_f32_16x16x32_bf16 v[54:57], v[180:183], v[202:205], v[54:57]
	v_mfma_f32_16x16x32_bf16 v[54:57], v[184:187], v[206:209], v[54:57]
	v_mfma_f32_16x16x32_bf16 v[38:41], v[184:187], v[214:217], v[38:41]
	v_mfma_f32_16x16x32_bf16 v[38:41], v[180:183], v[210:213], v[38:41]
	v_mfma_f32_16x16x32_bf16 v[22:25], v[180:183], v[218:221], v[22:25]
	v_mfma_f32_16x16x32_bf16 v[22:25], v[184:187], v[222:225], v[22:25]
	v_mfma_f32_16x16x32_bf16 v[6:9], v[184:187], v[230:233], v[6:9]
	v_mfma_f32_16x16x32_bf16 v[6:9], v[180:183], v[226:229], v[6:9]
	v_mfma_f32_16x16x32_bf16 v[2:5], v[188:191], v[226:229], v[2:5]
	v_mfma_f32_16x16x32_bf16 v[2:5], v[192:195], v[230:233], v[2:5]
	v_mfma_f32_16x16x32_bf16 v[18:21], v[192:195], v[222:225], v[18:21]
	v_mfma_f32_16x16x32_bf16 v[18:21], v[188:191], v[218:221], v[18:21]
	v_mfma_f32_16x16x32_bf16 v[34:37], v[188:191], v[210:213], v[34:37]
	v_mfma_f32_16x16x32_bf16 v[34:37], v[192:195], v[214:217], v[34:37]
	v_mfma_f32_16x16x32_bf16 v[50:53], v[192:195], v[206:209], v[50:53]
	v_mfma_f32_16x16x32_bf16 v[50:53], v[188:191], v[202:205], v[50:53]
	s_setprio 0
	s_barrier
	s_add_i32 s52, 0, 0x18000
	v_add_u32_e32 v166, s52, v153
	s_add_i32 s53, 0, 0x1c000
	ds_read_b128 v[142:145], v166
	ds_read_b128 v[158:161], v166 offset:1024
	ds_read_b128 v[168:171], v166 offset:2048
	ds_read_b128 v[176:179], v166 offset:3072
	v_add_u32_e32 v166, s53, v153
	ds_read_b128 v[180:183], v166
	ds_read_b128 v[184:187], v166 offset:1024
	ds_read_b128 v[188:191], v166 offset:2048
	ds_read_b128 v[192:195], v166 offset:3072
	s_add_u32 s26, s26, 0x100000
	s_addc_u32 s27, s27, 0
	s_mov_b32 m0, s35
	v_lshl_add_u64 v[236:237], s[26:27], 0, v[130:131]
	ds_read_b128 v[202:205], v157 offset:32768
	ds_read_b128 v[206:209], v157 offset:33792
	ds_read_b128 v[210:213], v157 offset:34816
	ds_read_b128 v[214:217], v157 offset:35840
	ds_read_b128 v[218:221], v157 offset:36864
	ds_read_b128 v[222:225], v157 offset:37888
	ds_read_b128 v[226:229], v157 offset:38912
	ds_read_b128 v[230:233], v157 offset:39936
	global_load_lds_dwordx4 v[236:237], off
	v_lshl_add_u64 v[236:237], s[26:27], 0, v[134:135]
	s_mov_b32 m0, s36
	s_nop 0
	global_load_lds_dwordx4 v[236:237], off
	s_waitcnt vmcnt(8)
	s_waitcnt lgkmcnt(0)
	s_barrier
	s_setprio 1
	s_waitcnt lgkmcnt(0)
	v_mfma_f32_16x16x32_bf16 v[126:129], v[142:145], v[202:205], v[126:129]
	v_mfma_f32_16x16x32_bf16 v[126:129], v[158:161], v[206:209], v[126:129]
	v_mfma_f32_16x16x32_bf16 v[110:113], v[158:161], v[214:217], v[110:113]
	v_mfma_f32_16x16x32_bf16 v[110:113], v[142:145], v[210:213], v[110:113]
	v_mfma_f32_16x16x32_bf16 v[94:97], v[142:145], v[218:221], v[94:97]
	v_mfma_f32_16x16x32_bf16 v[94:97], v[158:161], v[222:225], v[94:97]
	v_mfma_f32_16x16x32_bf16 v[78:81], v[158:161], v[230:233], v[78:81]
	v_mfma_f32_16x16x32_bf16 v[78:81], v[142:145], v[226:229], v[78:81]
	v_mfma_f32_16x16x32_bf16 v[74:77], v[168:171], v[226:229], v[74:77]
	v_mfma_f32_16x16x32_bf16 v[74:77], v[176:179], v[230:233], v[74:77]
	v_mfma_f32_16x16x32_bf16 v[90:93], v[176:179], v[222:225], v[90:93]
	v_mfma_f32_16x16x32_bf16 v[90:93], v[168:171], v[218:221], v[90:93]
	v_mfma_f32_16x16x32_bf16 v[106:109], v[168:171], v[210:213], v[106:109]
	v_mfma_f32_16x16x32_bf16 v[106:109], v[176:179], v[214:217], v[106:109]
	v_mfma_f32_16x16x32_bf16 v[122:125], v[176:179], v[206:209], v[122:125]
	v_mfma_f32_16x16x32_bf16 v[122:125], v[168:171], v[202:205], v[122:125]
	v_mfma_f32_16x16x32_bf16 v[118:121], v[180:183], v[202:205], v[118:121]
	v_mfma_f32_16x16x32_bf16 v[118:121], v[184:187], v[206:209], v[118:121]
	v_mfma_f32_16x16x32_bf16 v[102:105], v[184:187], v[214:217], v[102:105]
	v_mfma_f32_16x16x32_bf16 v[102:105], v[180:183], v[210:213], v[102:105]
	v_mfma_f32_16x16x32_bf16 v[86:89], v[180:183], v[218:221], v[86:89]
	v_mfma_f32_16x16x32_bf16 v[86:89], v[184:187], v[222:225], v[86:89]
	v_mfma_f32_16x16x32_bf16 v[70:73], v[184:187], v[230:233], v[70:73]
	v_mfma_f32_16x16x32_bf16 v[70:73], v[180:183], v[226:229], v[70:73]
	v_mfma_f32_16x16x32_bf16 v[66:69], v[188:191], v[226:229], v[66:69]
	v_mfma_f32_16x16x32_bf16 v[66:69], v[192:195], v[230:233], v[66:69]
	v_mfma_f32_16x16x32_bf16 v[82:85], v[192:195], v[222:225], v[82:85]
	v_mfma_f32_16x16x32_bf16 v[82:85], v[188:191], v[218:221], v[82:85]
	v_mfma_f32_16x16x32_bf16 v[98:101], v[188:191], v[210:213], v[98:101]
	v_mfma_f32_16x16x32_bf16 v[98:101], v[192:195], v[214:217], v[98:101]
	v_mfma_f32_16x16x32_bf16 v[114:117], v[192:195], v[206:209], v[114:117]
	v_mfma_f32_16x16x32_bf16 v[114:117], v[188:191], v[202:205], v[114:117]
	s_setprio 0
	s_barrier
	s_add_i32 s26, s52, s30
	v_lshl_add_u64 v[146:147], v[146:147], 0, s[14:15]
	s_mov_b32 m0, s26
	ds_read_b128 v[202:205], v157 offset:49152
	ds_read_b128 v[206:209], v157 offset:50176
	ds_read_b128 v[210:213], v157 offset:51200
	ds_read_b128 v[214:217], v157 offset:52224
	ds_read_b128 v[218:221], v157 offset:53248
	ds_read_b128 v[222:225], v157 offset:54272
	ds_read_b128 v[226:229], v157 offset:55296
	ds_read_b128 v[230:233], v157 offset:56320
	global_load_lds_dwordx4 v[146:147], off
	s_add_i32 m0, s26, 0x2000
	s_add_u32 s24, s24, 0x100080
	v_lshl_add_u64 v[146:147], v[172:173], 0, s[14:15]
	s_addc_u32 s25, s25, 0
	s_add_i32 s26, s53, s30
	global_load_lds_dwordx4 v[146:147], off
	v_lshl_add_u64 v[146:147], s[24:25], 0, v[132:133]
	s_mov_b32 m0, s26
	s_nop 0
	global_load_lds_dwordx4 v[146:147], off
	v_lshl_add_u64 v[146:147], s[24:25], 0, v[136:137]
	s_add_i32 m0, s26, 0x2000
	s_nop 0
	global_load_lds_dwordx4 v[146:147], off
	v_lshl_add_u64 v[146:147], v[196:197], 0, s[14:15]
	s_mov_b32 m0, s38
	s_nop 0
	global_load_lds_dwordx4 v[146:147], off
	v_lshl_add_u64 v[146:147], v[234:235], 0, s[14:15]
	s_mov_b32 m0, s39
	s_nop 0
	global_load_lds_dwordx4 v[146:147], off
	s_waitcnt vmcnt(8)
	s_waitcnt lgkmcnt(0)
	s_barrier
	s_setprio 1
	s_waitcnt lgkmcnt(0)
	v_mfma_f32_16x16x32_bf16 v[62:65], v[142:145], v[202:205], v[62:65]
	v_mfma_f32_16x16x32_bf16 v[62:65], v[158:161], v[206:209], v[62:65]
	v_mfma_f32_16x16x32_bf16 v[46:49], v[158:161], v[214:217], v[46:49]
	v_mfma_f32_16x16x32_bf16 v[46:49], v[142:145], v[210:213], v[46:49]
	v_mfma_f32_16x16x32_bf16 v[30:33], v[142:145], v[218:221], v[30:33]
	v_mfma_f32_16x16x32_bf16 v[30:33], v[158:161], v[222:225], v[30:33]
	v_mfma_f32_16x16x32_bf16 v[14:17], v[158:161], v[230:233], v[14:17]
	v_mfma_f32_16x16x32_bf16 v[14:17], v[142:145], v[226:229], v[14:17]
	v_mfma_f32_16x16x32_bf16 v[10:13], v[168:171], v[226:229], v[10:13]
	v_mfma_f32_16x16x32_bf16 v[10:13], v[176:179], v[230:233], v[10:13]
	v_mfma_f32_16x16x32_bf16 v[26:29], v[176:179], v[222:225], v[26:29]
	v_mfma_f32_16x16x32_bf16 v[26:29], v[168:171], v[218:221], v[26:29]
	v_mfma_f32_16x16x32_bf16 v[42:45], v[168:171], v[210:213], v[42:45]
	v_mfma_f32_16x16x32_bf16 v[42:45], v[176:179], v[214:217], v[42:45]
	v_mfma_f32_16x16x32_bf16 v[58:61], v[176:179], v[206:209], v[58:61]
	v_mfma_f32_16x16x32_bf16 v[58:61], v[168:171], v[202:205], v[58:61]
	v_mfma_f32_16x16x32_bf16 v[54:57], v[180:183], v[202:205], v[54:57]
	v_mfma_f32_16x16x32_bf16 v[54:57], v[184:187], v[206:209], v[54:57]
	v_mfma_f32_16x16x32_bf16 v[38:41], v[184:187], v[214:217], v[38:41]
	v_mfma_f32_16x16x32_bf16 v[38:41], v[180:183], v[210:213], v[38:41]
	v_mfma_f32_16x16x32_bf16 v[22:25], v[180:183], v[218:221], v[22:25]
	v_mfma_f32_16x16x32_bf16 v[22:25], v[184:187], v[222:225], v[22:25]
	v_mfma_f32_16x16x32_bf16 v[6:9], v[184:187], v[230:233], v[6:9]
	v_mfma_f32_16x16x32_bf16 v[6:9], v[180:183], v[226:229], v[6:9]
	v_mfma_f32_16x16x32_bf16 v[2:5], v[188:191], v[226:229], v[2:5]
	v_mfma_f32_16x16x32_bf16 v[2:5], v[192:195], v[230:233], v[2:5]
	v_mfma_f32_16x16x32_bf16 v[18:21], v[192:195], v[222:225], v[18:21]
	v_mfma_f32_16x16x32_bf16 v[18:21], v[188:191], v[218:221], v[18:21]
	v_mfma_f32_16x16x32_bf16 v[34:37], v[188:191], v[210:213], v[34:37]
	v_mfma_f32_16x16x32_bf16 v[34:37], v[192:195], v[214:217], v[34:37]
	v_mfma_f32_16x16x32_bf16 v[50:53], v[192:195], v[206:209], v[50:53]
	v_mfma_f32_16x16x32_bf16 v[50:53], v[188:191], v[202:205], v[50:53]
	s_setprio 0
	s_barrier
	s_add_i32 s51, s51, 2
	s_add_u32 s22, s22, 0x100
	s_addc_u32 s23, s23, 0
	s_add_u32 s49, s49, 0x100
	s_addc_u32 s50, s50, 0
	s_cmp_gt_u32 s51, 61
	s_cbranch_scc0 .LBB0_1009
	s_and_b64 vcc, exec, s[16:17]
	s_cbranch_vccz .LBB0_1012
	s_barrier

.LBB0_1019:
	s_add_i32 s21, s20, 0x100
	s_and_b64 s[18:19], s[18:19], exec
	s_cselect_b32 s19, 0, s21
	s_cselect_b32 s18, 0, 0
	s_add_u32 s22, s8, s19
	s_addc_u32 s23, s9, s18
	ds_read_b128 v[144:147], v139
	ds_read_b128 v[150:153], v139 offset:1024
	ds_read_b128 v[154:157], v139 offset:2048
	ds_read_b128 v[158:161], v139 offset:3072
	ds_read_b128 v[168:171], v140
	ds_read_b128 v[176:179], v140 offset:1024
	ds_read_b128 v[180:183], v140 offset:2048
	ds_read_b128 v[184:187], v140 offset:3072
	s_add_u32 s24, s10, s19
	s_addc_u32 s25, s11, s18
	s_add_u32 s30, s12, s20
	s_addc_u32 s31, s13, 0
	s_add_u32 s26, s24, 0x100000
	s_addc_u32 s27, s25, 0
	s_add_u32 s20, s22, 0x100000
	s_addc_u32 s21, s23, 0
	s_add_u32 s18, s24, 0x100080
	s_addc_u32 s19, s25, 0
	v_lshl_add_u64 v[172:173], s[30:31], 0, v[130:131]
	s_mov_b32 m0, s40
	v_lshl_add_u64 v[172:173], v[172:173], 0, s[14:15]
	ds_read_b128 v[188:191], v141
	ds_read_b128 v[192:195], v141 offset:1024
	ds_read_b128 v[202:205], v141 offset:2048
	ds_read_b128 v[206:209], v141 offset:3072
	ds_read_b128 v[210:213], v141 offset:4096
	ds_read_b128 v[214:217], v141 offset:5120
	ds_read_b128 v[218:221], v141 offset:6144
	ds_read_b128 v[222:225], v141 offset:7168
	global_load_lds_dwordx4 v[172:173], off
	v_lshl_add_u64 v[172:173], s[30:31], 0, v[134:135]
	v_lshl_add_u64 v[172:173], v[172:173], 0, s[14:15]
	s_mov_b32 m0, s41
	s_nop 0
	global_load_lds_dwordx4 v[172:173], off
	s_waitcnt vmcnt(8)
	s_waitcnt lgkmcnt(0)
	s_barrier
	s_setprio 1
	s_waitcnt lgkmcnt(0)
	v_mfma_f32_16x16x32_bf16 v[126:129], v[144:147], v[188:191], v[126:129]
	v_mfma_f32_16x16x32_bf16 v[126:129], v[150:153], v[192:195], v[126:129]
	v_mfma_f32_16x16x32_bf16 v[118:121], v[150:153], v[206:209], v[118:121]
	v_mfma_f32_16x16x32_bf16 v[118:121], v[144:147], v[202:205], v[118:121]
	v_mfma_f32_16x16x32_bf16 v[102:105], v[144:147], v[210:213], v[102:105]
	v_mfma_f32_16x16x32_bf16 v[102:105], v[150:153], v[214:217], v[102:105]
	v_mfma_f32_16x16x32_bf16 v[86:89], v[150:153], v[222:225], v[86:89]
	v_mfma_f32_16x16x32_bf16 v[86:89], v[144:147], v[218:221], v[86:89]
	v_mfma_f32_16x16x32_bf16 v[82:85], v[154:157], v[218:221], v[82:85]
	v_mfma_f32_16x16x32_bf16 v[82:85], v[158:161], v[222:225], v[82:85]
	v_mfma_f32_16x16x32_bf16 v[98:101], v[158:161], v[214:217], v[98:101]
	v_mfma_f32_16x16x32_bf16 v[98:101], v[154:157], v[210:213], v[98:101]
	v_mfma_f32_16x16x32_bf16 v[114:117], v[154:157], v[202:205], v[114:117]
	v_mfma_f32_16x16x32_bf16 v[114:117], v[158:161], v[206:209], v[114:117]
	v_mfma_f32_16x16x32_bf16 v[122:125], v[158:161], v[192:195], v[122:125]
	v_mfma_f32_16x16x32_bf16 v[122:125], v[154:157], v[188:191], v[122:125]
	v_mfma_f32_16x16x32_bf16 v[110:113], v[168:171], v[188:191], v[110:113]
	v_mfma_f32_16x16x32_bf16 v[110:113], v[176:179], v[192:195], v[110:113]
	v_mfma_f32_16x16x32_bf16 v[94:97], v[176:179], v[206:209], v[94:97]
	v_mfma_f32_16x16x32_bf16 v[94:97], v[168:171], v[202:205], v[94:97]
	v_mfma_f32_16x16x32_bf16 v[78:81], v[168:171], v[210:213], v[78:81]
	v_mfma_f32_16x16x32_bf16 v[78:81], v[176:179], v[214:217], v[78:81]
	v_mfma_f32_16x16x32_bf16 v[70:73], v[176:179], v[222:225], v[70:73]
	v_mfma_f32_16x16x32_bf16 v[70:73], v[168:171], v[218:221], v[70:73]
	v_mfma_f32_16x16x32_bf16 v[66:69], v[180:183], v[218:221], v[66:69]
	v_mfma_f32_16x16x32_bf16 v[66:69], v[184:187], v[222:225], v[66:69]
	v_mfma_f32_16x16x32_bf16 v[74:77], v[184:187], v[214:217], v[74:77]
	v_mfma_f32_16x16x32_bf16 v[74:77], v[180:183], v[210:213], v[74:77]
	v_mfma_f32_16x16x32_bf16 v[90:93], v[180:183], v[202:205], v[90:93]
	v_mfma_f32_16x16x32_bf16 v[90:93], v[184:187], v[206:209], v[90:93]
	v_mfma_f32_16x16x32_bf16 v[106:109], v[184:187], v[192:195], v[106:109]
	v_mfma_f32_16x16x32_bf16 v[106:109], v[180:183], v[188:191], v[106:109]
	s_setprio 0
	s_barrier
	s_mov_b32 m0, s42
	v_lshl_add_u64 v[172:173], s[24:25], 0, v[132:133]
	ds_read_b128 v[188:191], v141 offset:16384
	ds_read_b128 v[192:195], v141 offset:17408
	ds_read_b128 v[202:205], v141 offset:18432
	ds_read_b128 v[206:209], v141 offset:19456
	ds_read_b128 v[210:213], v141 offset:20480
	ds_read_b128 v[214:217], v141 offset:21504
	ds_read_b128 v[218:221], v141 offset:22528
	ds_read_b128 v[222:225], v141 offset:23552
	global_load_lds_dwordx4 v[172:173], off
	v_lshl_add_u64 v[196:197], s[24:25], 0, v[136:137]
	s_mov_b32 m0, s43
	v_lshl_add_u64 v[226:227], s[26:27], 0, v[132:133]
	global_load_lds_dwordx4 v[196:197], off
	s_mov_b32 m0, s44
	v_lshl_add_u64 v[228:229], s[22:23], 0, v[134:135]
	global_load_lds_dwordx4 v[226:227], off
	v_lshl_add_u64 v[226:227], s[26:27], 0, v[136:137]
	s_mov_b32 m0, s45
	s_nop 0
	global_load_lds_dwordx4 v[226:227], off
	v_lshl_add_u64 v[226:227], s[22:23], 0, v[130:131]
	s_mov_b32 m0, s7
	s_nop 0
	global_load_lds_dwordx4 v[226:227], off
	s_mov_b32 m0, s34
	s_nop 0
	global_load_lds_dwordx4 v[228:229], off
	s_waitcnt vmcnt(8)
	s_waitcnt lgkmcnt(0)
	s_barrier
	s_setprio 1
	s_waitcnt lgkmcnt(0)
	v_mfma_f32_16x16x32_bf16 v[62:65], v[144:147], v[188:191], v[62:65]
	v_mfma_f32_16x16x32_bf16 v[62:65], v[150:153], v[192:195], v[62:65]
	v_mfma_f32_16x16x32_bf16 v[54:57], v[150:153], v[206:209], v[54:57]
	v_mfma_f32_16x16x32_bf16 v[54:57], v[144:147], v[202:205], v[54:57]
	v_mfma_f32_16x16x32_bf16 v[38:41], v[144:147], v[210:213], v[38:41]
	v_mfma_f32_16x16x32_bf16 v[38:41], v[150:153], v[214:217], v[38:41]
	v_mfma_f32_16x16x32_bf16 v[22:25], v[150:153], v[222:225], v[22:25]
	v_mfma_f32_16x16x32_bf16 v[22:25], v[144:147], v[218:221], v[22:25]
	v_mfma_f32_16x16x32_bf16 v[18:21], v[154:157], v[218:221], v[18:21]
	v_mfma_f32_16x16x32_bf16 v[18:21], v[158:161], v[222:225], v[18:21]
	v_mfma_f32_16x16x32_bf16 v[34:37], v[158:161], v[214:217], v[34:37]
	v_mfma_f32_16x16x32_bf16 v[34:37], v[154:157], v[210:213], v[34:37]
	v_mfma_f32_16x16x32_bf16 v[50:53], v[154:157], v[202:205], v[50:53]
	v_mfma_f32_16x16x32_bf16 v[50:53], v[158:161], v[206:209], v[50:53]
	v_mfma_f32_16x16x32_bf16 v[58:61], v[158:161], v[192:195], v[58:61]
	v_mfma_f32_16x16x32_bf16 v[58:61], v[154:157], v[188:191], v[58:61]
	v_mfma_f32_16x16x32_bf16 v[46:49], v[168:171], v[188:191], v[46:49]
	v_mfma_f32_16x16x32_bf16 v[46:49], v[176:179], v[192:195], v[46:49]
	v_mfma_f32_16x16x32_bf16 v[30:33], v[176:179], v[206:209], v[30:33]
	v_mfma_f32_16x16x32_bf16 v[30:33], v[168:171], v[202:205], v[30:33]
	v_mfma_f32_16x16x32_bf16 v[14:17], v[168:171], v[210:213], v[14:17]
	v_mfma_f32_16x16x32_bf16 v[14:17], v[176:179], v[214:217], v[14:17]
	v_mfma_f32_16x16x32_bf16 v[6:9], v[176:179], v[222:225], v[6:9]
	v_mfma_f32_16x16x32_bf16 v[6:9], v[168:171], v[218:221], v[6:9]
	v_mfma_f32_16x16x32_bf16 v[2:5], v[180:183], v[218:221], v[2:5]
	v_mfma_f32_16x16x32_bf16 v[2:5], v[184:187], v[222:225], v[2:5]
	v_mfma_f32_16x16x32_bf16 v[10:13], v[184:187], v[214:217], v[10:13]
	v_mfma_f32_16x16x32_bf16 v[10:13], v[180:183], v[210:213], v[10:13]
	v_mfma_f32_16x16x32_bf16 v[26:29], v[180:183], v[202:205], v[26:29]
	v_mfma_f32_16x16x32_bf16 v[26:29], v[184:187], v[206:209], v[26:29]
	v_mfma_f32_16x16x32_bf16 v[42:45], v[184:187], v[192:195], v[42:45]
	v_mfma_f32_16x16x32_bf16 v[42:45], v[180:183], v[188:191], v[42:45]
	s_setprio 0
	s_barrier
	ds_read_b128 v[144:147], v142
	ds_read_b128 v[150:153], v142 offset:1024
	ds_read_b128 v[154:157], v142 offset:2048
	ds_read_b128 v[158:161], v142 offset:3072
	ds_read_b128 v[168:171], v143
	ds_read_b128 v[176:179], v143 offset:1024
	ds_read_b128 v[180:183], v143 offset:2048
	ds_read_b128 v[184:187], v143 offset:3072
	s_mov_b32 m0, s35
	v_lshl_add_u64 v[230:231], s[20:21], 0, v[130:131]
	ds_read_b128 v[188:191], v141 offset:32768
	ds_read_b128 v[192:195], v141 offset:33792
	ds_read_b128 v[202:205], v141 offset:34816
	ds_read_b128 v[206:209], v141 offset:35840
	ds_read_b128 v[210:213], v141 offset:36864
	ds_read_b128 v[214:217], v141 offset:37888
	ds_read_b128 v[218:221], v141 offset:38912
	ds_read_b128 v[222:225], v141 offset:39936
	global_load_lds_dwordx4 v[230:231], off
	v_lshl_add_u64 v[230:231], s[20:21], 0, v[134:135]
	s_mov_b32 m0, s36
	s_nop 0
	global_load_lds_dwordx4 v[230:231], off
	s_waitcnt vmcnt(8)
	s_waitcnt lgkmcnt(0)
	s_barrier
	s_setprio 1
	s_waitcnt lgkmcnt(0)
	v_mfma_f32_16x16x32_bf16 v[126:129], v[144:147], v[188:191], v[126:129]
	v_mfma_f32_16x16x32_bf16 v[126:129], v[150:153], v[192:195], v[126:129]
	v_mfma_f32_16x16x32_bf16 v[118:121], v[150:153], v[206:209], v[118:121]
	v_mfma_f32_16x16x32_bf16 v[118:121], v[144:147], v[202:205], v[118:121]
	v_mfma_f32_16x16x32_bf16 v[102:105], v[144:147], v[210:213], v[102:105]
	v_mfma_f32_16x16x32_bf16 v[102:105], v[150:153], v[214:217], v[102:105]
	v_mfma_f32_16x16x32_bf16 v[86:89], v[150:153], v[222:225], v[86:89]
	v_mfma_f32_16x16x32_bf16 v[86:89], v[144:147], v[218:221], v[86:89]
	v_mfma_f32_16x16x32_bf16 v[82:85], v[154:157], v[218:221], v[82:85]
	v_mfma_f32_16x16x32_bf16 v[82:85], v[158:161], v[222:225], v[82:85]
	v_mfma_f32_16x16x32_bf16 v[98:101], v[158:161], v[214:217], v[98:101]
	v_mfma_f32_16x16x32_bf16 v[98:101], v[154:157], v[210:213], v[98:101]
	v_mfma_f32_16x16x32_bf16 v[114:117], v[154:157], v[202:205], v[114:117]
	v_mfma_f32_16x16x32_bf16 v[114:117], v[158:161], v[206:209], v[114:117]
	v_mfma_f32_16x16x32_bf16 v[122:125], v[158:161], v[192:195], v[122:125]
	v_mfma_f32_16x16x32_bf16 v[122:125], v[154:157], v[188:191], v[122:125]
	v_mfma_f32_16x16x32_bf16 v[110:113], v[168:171], v[188:191], v[110:113]
	v_mfma_f32_16x16x32_bf16 v[110:113], v[176:179], v[192:195], v[110:113]
	v_mfma_f32_16x16x32_bf16 v[94:97], v[176:179], v[206:209], v[94:97]
	v_mfma_f32_16x16x32_bf16 v[94:97], v[168:171], v[202:205], v[94:97]
	v_mfma_f32_16x16x32_bf16 v[78:81], v[168:171], v[210:213], v[78:81]
	v_mfma_f32_16x16x32_bf16 v[78:81], v[176:179], v[214:217], v[78:81]
	v_mfma_f32_16x16x32_bf16 v[70:73], v[176:179], v[222:225], v[70:73]
	v_mfma_f32_16x16x32_bf16 v[70:73], v[168:171], v[218:221], v[70:73]
	v_mfma_f32_16x16x32_bf16 v[66:69], v[180:183], v[218:221], v[66:69]
	v_mfma_f32_16x16x32_bf16 v[66:69], v[184:187], v[222:225], v[66:69]
	v_mfma_f32_16x16x32_bf16 v[74:77], v[184:187], v[214:217], v[74:77]
	v_mfma_f32_16x16x32_bf16 v[74:77], v[180:183], v[210:213], v[74:77]
	v_mfma_f32_16x16x32_bf16 v[90:93], v[180:183], v[202:205], v[90:93]
	v_mfma_f32_16x16x32_bf16 v[90:93], v[184:187], v[206:209], v[90:93]
	v_mfma_f32_16x16x32_bf16 v[106:109], v[184:187], v[192:195], v[106:109]
	v_mfma_f32_16x16x32_bf16 v[106:109], v[180:183], v[188:191], v[106:109]
	s_setprio 0
	s_barrier
	s_mov_b32 m0, s46
	v_lshl_add_u64 v[172:173], v[172:173], 0, s[14:15]
	ds_read_b128 v[188:191], v141 offset:49152
	ds_read_b128 v[192:195], v141 offset:50176
	ds_read_b128 v[202:205], v141 offset:51200
	ds_read_b128 v[206:209], v141 offset:52224
	ds_read_b128 v[210:213], v141 offset:53248
	ds_read_b128 v[214:217], v141 offset:54272
	ds_read_b128 v[218:221], v141 offset:55296
	ds_read_b128 v[222:225], v141 offset:56320
	global_load_lds_dwordx4 v[172:173], off
	v_lshl_add_u64 v[172:173], v[196:197], 0, s[14:15]
	s_mov_b32 m0, s47
	s_nop 0
	global_load_lds_dwordx4 v[172:173], off
	v_lshl_add_u64 v[172:173], s[18:19], 0, v[132:133]
	s_mov_b32 m0, s48
	s_nop 0
	global_load_lds_dwordx4 v[172:173], off
	v_lshl_add_u64 v[172:173], s[18:19], 0, v[136:137]
	s_mov_b32 m0, s49
	s_nop 0
	global_load_lds_dwordx4 v[172:173], off
	v_lshl_add_u64 v[172:173], v[226:227], 0, s[14:15]
	s_mov_b32 m0, s38
	s_nop 0
	global_load_lds_dwordx4 v[172:173], off
	v_lshl_add_u64 v[172:173], v[228:229], 0, s[14:15]
	s_mov_b32 m0, s39
	s_nop 0
	global_load_lds_dwordx4 v[172:173], off
	s_waitcnt vmcnt(8)
	s_waitcnt lgkmcnt(0)
	s_barrier
	s_setprio 1
	s_waitcnt lgkmcnt(0)
	v_mfma_f32_16x16x32_bf16 v[62:65], v[144:147], v[188:191], v[62:65]
	v_mfma_f32_16x16x32_bf16 v[62:65], v[150:153], v[192:195], v[62:65]
	v_mfma_f32_16x16x32_bf16 v[54:57], v[150:153], v[206:209], v[54:57]
	v_mfma_f32_16x16x32_bf16 v[54:57], v[144:147], v[202:205], v[54:57]
	v_mfma_f32_16x16x32_bf16 v[38:41], v[144:147], v[210:213], v[38:41]
	v_mfma_f32_16x16x32_bf16 v[38:41], v[150:153], v[214:217], v[38:41]
	v_mfma_f32_16x16x32_bf16 v[22:25], v[150:153], v[222:225], v[22:25]
	v_mfma_f32_16x16x32_bf16 v[22:25], v[144:147], v[218:221], v[22:25]
	v_mfma_f32_16x16x32_bf16 v[18:21], v[154:157], v[218:221], v[18:21]
	v_mfma_f32_16x16x32_bf16 v[18:21], v[158:161], v[222:225], v[18:21]
	v_mfma_f32_16x16x32_bf16 v[34:37], v[158:161], v[214:217], v[34:37]
	v_mfma_f32_16x16x32_bf16 v[34:37], v[154:157], v[210:213], v[34:37]
	v_mfma_f32_16x16x32_bf16 v[50:53], v[154:157], v[202:205], v[50:53]
	v_mfma_f32_16x16x32_bf16 v[50:53], v[158:161], v[206:209], v[50:53]
	v_mfma_f32_16x16x32_bf16 v[58:61], v[158:161], v[192:195], v[58:61]
	v_mfma_f32_16x16x32_bf16 v[58:61], v[154:157], v[188:191], v[58:61]
	v_mfma_f32_16x16x32_bf16 v[46:49], v[168:171], v[188:191], v[46:49]
	v_mfma_f32_16x16x32_bf16 v[46:49], v[176:179], v[192:195], v[46:49]
	v_mfma_f32_16x16x32_bf16 v[30:33], v[176:179], v[206:209], v[30:33]
	v_mfma_f32_16x16x32_bf16 v[30:33], v[168:171], v[202:205], v[30:33]
	v_mfma_f32_16x16x32_bf16 v[14:17], v[168:171], v[210:213], v[14:17]
	v_mfma_f32_16x16x32_bf16 v[14:17], v[176:179], v[214:217], v[14:17]
	v_mfma_f32_16x16x32_bf16 v[6:9], v[176:179], v[222:225], v[6:9]
	v_mfma_f32_16x16x32_bf16 v[6:9], v[168:171], v[218:221], v[6:9]
	v_mfma_f32_16x16x32_bf16 v[2:5], v[180:183], v[218:221], v[2:5]
	v_mfma_f32_16x16x32_bf16 v[2:5], v[184:187], v[222:225], v[2:5]
	v_mfma_f32_16x16x32_bf16 v[10:13], v[184:187], v[214:217], v[10:13]
	v_mfma_f32_16x16x32_bf16 v[10:13], v[180:183], v[210:213], v[10:13]
	v_mfma_f32_16x16x32_bf16 v[26:29], v[180:183], v[202:205], v[26:29]
	v_mfma_f32_16x16x32_bf16 v[26:29], v[184:187], v[206:209], v[26:29]
	v_mfma_f32_16x16x32_bf16 v[42:45], v[184:187], v[192:195], v[42:45]
	v_mfma_f32_16x16x32_bf16 v[42:45], v[180:183], v[188:191], v[42:45]
	s_setprio 0
	s_barrier
	s_andn2_b64 vcc, exec, s[16:17]
	s_mov_b64 s[18:19], -1
	s_mov_b64 s[16:17], 0
	s_movk_i32 s20, 0x100
	s_cbranch_vccz .LBB0_1019
	s_lshl_b32 s7, s33, 21
	v_readlane_b32 s0, v249, 29
	v_lshl_or_b32 v130, s6, 8, v148
	v_mov_b32_e32 v139, 0
	s_add_u32 s8, s0, s7
	v_readlane_b32 s0, v249, 31
	v_or_b32_e32 v130, s37, v130
	v_cvt_pk_bf16_f32 v70, v70, v71
	v_cvt_pk_bf16_f32 v71, v72, v73
	v_cvt_pk_bf16_f32 v72, v66, v67
	v_add_u32_e32 v66, 0x80, v138
	v_mov_b32_e32 v67, v139
	s_addc_u32 s9, s0, 0
	v_ashrrev_i32_e32 v131, 31, v130
	v_lshlrev_b64 v[132:133], 13, v[138:139]
	v_cvt_pk_bf16_f32 v110, v110, v111
	v_cvt_pk_bf16_f32 v111, v112, v113
	v_cvt_pk_bf16_f32 v112, v106, v107
	v_or_b32_e32 v106, 16, v138
	v_mov_b32_e32 v107, v139
	v_lshlrev_b64 v[66:67], 13, v[66:67]
	v_cvt_pk_bf16_f32 v46, v46, v47
	v_cvt_pk_bf16_f32 v47, v48, v49
	v_cvt_pk_bf16_f32 v48, v42, v43
	v_add_u32_e32 v42, 0x90, v138
	v_mov_b32_e32 v43, v139
	v_lshl_add_u64 v[132:133], s[8:9], 0, v[132:133]
	v_lshlrev_b64 v[130:131], 1, v[130:131]
	v_lshlrev_b64 v[106:107], 13, v[106:107]
	v_cvt_pk_bf16_f32 v94, v94, v95
	v_cvt_pk_bf16_f32 v95, v96, v97
	v_cvt_pk_bf16_f32 v96, v90, v91
	v_or_b32_e32 v90, 32, v138
	v_mov_b32_e32 v91, v139
	v_lshl_add_u64 v[66:67], s[8:9], 0, v[66:67]
	v_lshlrev_b64 v[42:43], 13, v[42:43]
	v_cvt_pk_bf16_f32 v30, v30, v31
	v_cvt_pk_bf16_f32 v31, v32, v33
	v_cvt_pk_bf16_f32 v32, v26, v27
	v_add_u32_e32 v26, 0xa0, v138
	v_mov_b32_e32 v27, v139
	v_lshl_add_u64 v[132:133], v[132:133], 0, v[130:131]
	v_cvt_pk_bf16_f32 v113, v108, v109
	v_lshl_add_u64 v[106:107], s[8:9], 0, v[106:107]
	v_lshlrev_b64 v[90:91], 13, v[90:91]
	v_cvt_pk_bf16_f32 v78, v78, v79
	v_cvt_pk_bf16_f32 v79, v80, v81
	v_cvt_pk_bf16_f32 v80, v74, v75
	v_or_b32_e32 v74, 48, v138
	v_mov_b32_e32 v75, v139
	v_lshl_add_u64 v[66:67], v[66:67], 0, v[130:131]
	v_cvt_pk_bf16_f32 v49, v44, v45
	v_lshl_add_u64 v[42:43], s[8:9], 0, v[42:43]
	v_lshlrev_b64 v[26:27], 13, v[26:27]
	v_add_u32_e32 v138, 0xb0, v138
	global_store_dwordx4 v[132:133], v[110:113], off offset:256
	v_cvt_pk_bf16_f32 v97, v92, v93
	v_lshl_add_u64 v[90:91], s[8:9], 0, v[90:91]
	v_lshl_add_u64 v[110:111], v[106:107], 0, v[130:131]
	v_lshlrev_b64 v[74:75], 13, v[74:75]
	global_store_dwordx4 v[66:67], v[46:49], off offset:256
	v_cvt_pk_bf16_f32 v33, v28, v29
	v_lshl_add_u64 v[26:27], s[8:9], 0, v[26:27]
	v_lshl_add_u64 v[46:47], v[42:43], 0, v[130:131]
	v_cvt_pk_bf16_f32 v14, v14, v15
	v_cvt_pk_bf16_f32 v15, v16, v17
	v_cvt_pk_bf16_f32 v16, v10, v11
	v_lshlrev_b64 v[10:11], 13, v[138:139]
	global_store_dwordx4 v[110:111], v[94:97], off offset:256
	v_cvt_pk_bf16_f32 v81, v76, v77
	v_lshl_add_u64 v[74:75], s[8:9], 0, v[74:75]
	v_lshl_add_u64 v[94:95], v[90:91], 0, v[130:131]
	global_store_dwordx4 v[46:47], v[30:33], off offset:256
	v_cvt_pk_bf16_f32 v17, v12, v13
	v_lshl_add_u64 v[10:11], s[8:9], 0, v[10:11]
	v_lshl_add_u64 v[30:31], v[26:27], 0, v[130:131]
	v_cvt_pk_bf16_f32 v126, v126, v127
	v_cvt_pk_bf16_f32 v127, v128, v129
	v_cvt_pk_bf16_f32 v128, v122, v123
	v_cvt_pk_bf16_f32 v129, v124, v125
	v_cvt_pk_bf16_f32 v106, v118, v119
	v_cvt_pk_bf16_f32 v107, v120, v121
	v_cvt_pk_bf16_f32 v108, v114, v115
	v_cvt_pk_bf16_f32 v109, v116, v117
	v_cvt_pk_bf16_f32 v90, v102, v103
	v_cvt_pk_bf16_f32 v91, v104, v105
	v_cvt_pk_bf16_f32 v92, v98, v99
	v_cvt_pk_bf16_f32 v93, v100, v101
	global_store_dwordx4 v[94:95], v[78:81], off offset:256
	v_cvt_pk_bf16_f32 v76, v82, v83
	v_cvt_pk_bf16_f32 v77, v84, v85
	v_lshl_add_u64 v[78:79], v[74:75], 0, v[130:131]
	v_cvt_pk_bf16_f32 v74, v86, v87
	v_cvt_pk_bf16_f32 v75, v88, v89
	v_cvt_pk_bf16_f32 v73, v68, v69
	v_cvt_pk_bf16_f32 v62, v62, v63
	v_cvt_pk_bf16_f32 v63, v64, v65
	v_cvt_pk_bf16_f32 v64, v58, v59
	v_cvt_pk_bf16_f32 v65, v60, v61
	v_cvt_pk_bf16_f32 v42, v54, v55
	v_cvt_pk_bf16_f32 v43, v56, v57
	v_cvt_pk_bf16_f32 v44, v50, v51
	v_cvt_pk_bf16_f32 v45, v52, v53
	v_cvt_pk_bf16_f32 v26, v38, v39
	v_cvt_pk_bf16_f32 v27, v40, v41
	v_cvt_pk_bf16_f32 v28, v34, v35
	v_cvt_pk_bf16_f32 v29, v36, v37
	global_store_dwordx4 v[30:31], v[14:17], off offset:256
	v_cvt_pk_bf16_f32 v12, v18, v19
	v_cvt_pk_bf16_f32 v13, v20, v21
	v_lshl_add_u64 v[14:15], v[10:11], 0, v[130:131]
	v_cvt_pk_bf16_f32 v10, v22, v23
	v_cvt_pk_bf16_f32 v11, v24, v25
	v_cvt_pk_bf16_f32 v6, v6, v7
	v_cvt_pk_bf16_f32 v7, v8, v9
	v_cvt_pk_bf16_f32 v8, v2, v3
	v_cvt_pk_bf16_f32 v9, v4, v5
	global_store_dwordx4 v[132:133], v[126:129], off
	global_store_dwordx4 v[110:111], v[106:109], off
	global_store_dwordx4 v[94:95], v[90:93], off
	global_store_dwordx4 v[78:79], v[74:77], off
	global_store_dwordx4 v[78:79], v[70:73], off offset:256
	global_store_dwordx4 v[66:67], v[62:65], off
	global_store_dwordx4 v[46:47], v[42:45], off
	global_store_dwordx4 v[30:31], v[26:29], off
	global_store_dwordx4 v[14:15], v[10:13], off
	global_store_dwordx4 v[14:15], v[6:9], off offset:256
	s_waitcnt vmcnt(0)
	s_cmpk_lt_u32 s3, 0x100
	s_cbranch_scc0 .LBB0_1022
	s_barrier

.LBB0_1172:
	s_add_u32 s62, s20, 0xfff00000
	s_addc_u32 s63, s21, -1
	s_mov_b32 m0, s37
	ds_read_b128 v[142:145], v148
	global_load_lds_dwordx4 v130, s[62:63]
	s_mov_b32 m0, s38
	ds_read_b128 v[154:157], v148 offset:1024
	global_load_lds_dwordx4 v134, s[62:63]
	s_mov_b32 m0, s42
	ds_read_b128 v[158:161], v148 offset:2048
	global_load_lds_dwordx4 v138, s[20:21]
	s_mov_b32 m0, s43
	ds_read_b128 v[168:171], v148 offset:3072
	global_load_lds_dwordx4 v140, s[20:21]
	ds_read_b128 v[176:179], v149
	ds_read_b128 v[180:183], v149 offset:1024
	ds_read_b128 v[184:187], v149 offset:2048
	ds_read_b128 v[188:191], v149 offset:3072
	s_add_u32 s22, s20, 0xfff00080
	s_addc_u32 s23, s21, -1
	s_cmp_eq_u32 s61, 60
	s_cselect_b32 s25, s54, s23
	s_cselect_b32 s24, s55, s22
	s_cselect_b32 s23, s7, s60
	s_cselect_b32 s22, s56, s57
	ds_read_b128 v[192:195], v150
	ds_read_b128 v[202:205], v150 offset:1024
	ds_read_b128 v[206:209], v150 offset:2048
	ds_read_b128 v[210:213], v150 offset:3072
	ds_read_b128 v[214:217], v150 offset:4096
	ds_read_b128 v[218:221], v150 offset:5120
	ds_read_b128 v[222:225], v150 offset:6144
	ds_read_b128 v[226:229], v150 offset:7168
	s_waitcnt vmcnt(8)
	s_waitcnt lgkmcnt(0)
	s_barrier
	s_setprio 1
	s_waitcnt lgkmcnt(0)
	v_mfma_f32_16x16x32_bf16 v[126:129], v[142:145], v[192:195], v[126:129]
	v_mfma_f32_16x16x32_bf16 v[126:129], v[154:157], v[202:205], v[126:129]
	v_mfma_f32_16x16x32_bf16 v[110:113], v[154:157], v[210:213], v[110:113]
	v_mfma_f32_16x16x32_bf16 v[110:113], v[142:145], v[206:209], v[110:113]
	v_mfma_f32_16x16x32_bf16 v[94:97], v[142:145], v[214:217], v[94:97]
	v_mfma_f32_16x16x32_bf16 v[94:97], v[154:157], v[218:221], v[94:97]
	v_mfma_f32_16x16x32_bf16 v[78:81], v[154:157], v[226:229], v[78:81]
	v_mfma_f32_16x16x32_bf16 v[78:81], v[142:145], v[222:225], v[78:81]
	v_mfma_f32_16x16x32_bf16 v[70:73], v[158:161], v[222:225], v[70:73]
	v_mfma_f32_16x16x32_bf16 v[70:73], v[168:171], v[226:229], v[70:73]
	v_mfma_f32_16x16x32_bf16 v[86:89], v[168:171], v[218:221], v[86:89]
	v_mfma_f32_16x16x32_bf16 v[86:89], v[158:161], v[214:217], v[86:89]
	v_mfma_f32_16x16x32_bf16 v[102:105], v[158:161], v[206:209], v[102:105]
	v_mfma_f32_16x16x32_bf16 v[102:105], v[168:171], v[210:213], v[102:105]
	v_mfma_f32_16x16x32_bf16 v[118:121], v[168:171], v[202:205], v[118:121]
	v_mfma_f32_16x16x32_bf16 v[118:121], v[158:161], v[192:195], v[118:121]
	v_mfma_f32_16x16x32_bf16 v[122:125], v[176:179], v[192:195], v[122:125]
	v_mfma_f32_16x16x32_bf16 v[122:125], v[180:183], v[202:205], v[122:125]
	v_mfma_f32_16x16x32_bf16 v[106:109], v[180:183], v[210:213], v[106:109]
	v_mfma_f32_16x16x32_bf16 v[106:109], v[176:179], v[206:209], v[106:109]
	v_mfma_f32_16x16x32_bf16 v[90:93], v[176:179], v[214:217], v[90:93]
	v_mfma_f32_16x16x32_bf16 v[90:93], v[180:183], v[218:221], v[90:93]
	v_mfma_f32_16x16x32_bf16 v[74:77], v[180:183], v[226:229], v[74:77]
	v_mfma_f32_16x16x32_bf16 v[74:77], v[176:179], v[222:225], v[74:77]
	v_mfma_f32_16x16x32_bf16 v[66:69], v[184:187], v[222:225], v[66:69]
	v_mfma_f32_16x16x32_bf16 v[66:69], v[188:191], v[226:229], v[66:69]
	v_mfma_f32_16x16x32_bf16 v[82:85], v[188:191], v[218:221], v[82:85]
	v_mfma_f32_16x16x32_bf16 v[82:85], v[184:187], v[214:217], v[82:85]
	v_mfma_f32_16x16x32_bf16 v[98:101], v[184:187], v[206:209], v[98:101]
	v_mfma_f32_16x16x32_bf16 v[98:101], v[188:191], v[210:213], v[98:101]
	v_mfma_f32_16x16x32_bf16 v[114:117], v[188:191], v[202:205], v[114:117]
	v_mfma_f32_16x16x32_bf16 v[114:117], v[184:187], v[192:195], v[114:117]
	s_setprio 0
	s_barrier
	s_mov_b32 m0, s44
	s_add_u32 s62, s22, 0x100000
	global_load_lds_dwordx4 v132, s[22:23]
	s_mov_b32 m0, s45
	s_addc_u32 s63, s23, 0
	global_load_lds_dwordx4 v136, s[22:23]
	s_mov_b32 m0, s46
	ds_read_b128 v[192:195], v150 offset:16384
	global_load_lds_dwordx4 v132, s[62:63]
	s_mov_b32 m0, s47
	ds_read_b128 v[202:205], v150 offset:17408
	global_load_lds_dwordx4 v136, s[62:63]
	ds_read_b128 v[206:209], v150 offset:18432
	ds_read_b128 v[210:213], v150 offset:19456
	ds_read_b128 v[214:217], v150 offset:20480
	ds_read_b128 v[218:221], v150 offset:21504
	ds_read_b128 v[222:225], v150 offset:22528
	ds_read_b128 v[226:229], v150 offset:23552
	s_waitcnt vmcnt(6)
	s_waitcnt lgkmcnt(0)
	s_barrier
	s_setprio 1
	s_waitcnt lgkmcnt(0)
	v_mfma_f32_16x16x32_bf16 v[62:65], v[142:145], v[192:195], v[62:65]
	v_mfma_f32_16x16x32_bf16 v[62:65], v[154:157], v[202:205], v[62:65]
	v_mfma_f32_16x16x32_bf16 v[46:49], v[154:157], v[210:213], v[46:49]
	v_mfma_f32_16x16x32_bf16 v[46:49], v[142:145], v[206:209], v[46:49]
	v_mfma_f32_16x16x32_bf16 v[30:33], v[142:145], v[214:217], v[30:33]
	v_mfma_f32_16x16x32_bf16 v[30:33], v[154:157], v[218:221], v[30:33]
	v_mfma_f32_16x16x32_bf16 v[14:17], v[154:157], v[226:229], v[14:17]
	v_mfma_f32_16x16x32_bf16 v[14:17], v[142:145], v[222:225], v[14:17]
	v_mfma_f32_16x16x32_bf16 v[6:9], v[158:161], v[222:225], v[6:9]
	v_mfma_f32_16x16x32_bf16 v[6:9], v[168:171], v[226:229], v[6:9]
	v_mfma_f32_16x16x32_bf16 v[22:25], v[168:171], v[218:221], v[22:25]
	v_mfma_f32_16x16x32_bf16 v[22:25], v[158:161], v[214:217], v[22:25]
	v_mfma_f32_16x16x32_bf16 v[38:41], v[158:161], v[206:209], v[38:41]
	v_mfma_f32_16x16x32_bf16 v[38:41], v[168:171], v[210:213], v[38:41]
	v_mfma_f32_16x16x32_bf16 v[54:57], v[168:171], v[202:205], v[54:57]
	v_mfma_f32_16x16x32_bf16 v[54:57], v[158:161], v[192:195], v[54:57]
	v_mfma_f32_16x16x32_bf16 v[58:61], v[176:179], v[192:195], v[58:61]
	v_mfma_f32_16x16x32_bf16 v[58:61], v[180:183], v[202:205], v[58:61]
	v_mfma_f32_16x16x32_bf16 v[42:45], v[180:183], v[210:213], v[42:45]
	v_mfma_f32_16x16x32_bf16 v[42:45], v[176:179], v[206:209], v[42:45]
	v_mfma_f32_16x16x32_bf16 v[26:29], v[176:179], v[214:217], v[26:29]
	v_mfma_f32_16x16x32_bf16 v[26:29], v[180:183], v[218:221], v[26:29]
	v_mfma_f32_16x16x32_bf16 v[10:13], v[180:183], v[226:229], v[10:13]
	v_mfma_f32_16x16x32_bf16 v[10:13], v[176:179], v[222:225], v[10:13]
	v_mfma_f32_16x16x32_bf16 v[2:5], v[184:187], v[222:225], v[2:5]
	v_mfma_f32_16x16x32_bf16 v[2:5], v[188:191], v[226:229], v[2:5]
	v_mfma_f32_16x16x32_bf16 v[18:21], v[188:191], v[218:221], v[18:21]
	v_mfma_f32_16x16x32_bf16 v[18:21], v[184:187], v[214:217], v[18:21]
	v_mfma_f32_16x16x32_bf16 v[34:37], v[184:187], v[206:209], v[34:37]
	v_mfma_f32_16x16x32_bf16 v[34:37], v[188:191], v[210:213], v[34:37]
	v_mfma_f32_16x16x32_bf16 v[50:53], v[188:191], v[202:205], v[50:53]
	v_mfma_f32_16x16x32_bf16 v[50:53], v[184:187], v[192:195], v[50:53]
	s_setprio 0
	s_barrier
	s_mov_b32 m0, s31
	ds_read_b128 v[142:145], v151
	global_load_lds_dwordx4 v130, s[24:25]
	s_mov_b32 m0, s33
	ds_read_b128 v[154:157], v151 offset:1024
	global_load_lds_dwordx4 v134, s[24:25]
	s_add_u32 s24, s24, 0x100000
	s_addc_u32 s25, s25, 0
	s_mov_b32 m0, s34
	ds_read_b128 v[158:161], v151 offset:2048
	global_load_lds_dwordx4 v130, s[24:25]
	s_mov_b32 m0, s35
	ds_read_b128 v[168:171], v151 offset:3072
	global_load_lds_dwordx4 v134, s[24:25]
	ds_read_b128 v[176:179], v152
	ds_read_b128 v[180:183], v152 offset:1024
	ds_read_b128 v[184:187], v152 offset:2048
	ds_read_b128 v[188:191], v152 offset:3072
	ds_read_b128 v[192:195], v150 offset:32768
	ds_read_b128 v[202:205], v150 offset:33792
	ds_read_b128 v[206:209], v150 offset:34816
	ds_read_b128 v[210:213], v150 offset:35840
	ds_read_b128 v[214:217], v150 offset:36864
	ds_read_b128 v[218:221], v150 offset:37888
	ds_read_b128 v[222:225], v150 offset:38912
	ds_read_b128 v[226:229], v150 offset:39936
	s_waitcnt vmcnt(8)
	s_waitcnt lgkmcnt(0)
	s_barrier
	s_setprio 1
	s_waitcnt lgkmcnt(0)
	v_mfma_f32_16x16x32_bf16 v[126:129], v[142:145], v[192:195], v[126:129]
	v_mfma_f32_16x16x32_bf16 v[126:129], v[154:157], v[202:205], v[126:129]
	v_mfma_f32_16x16x32_bf16 v[110:113], v[154:157], v[210:213], v[110:113]
	v_mfma_f32_16x16x32_bf16 v[110:113], v[142:145], v[206:209], v[110:113]
	v_mfma_f32_16x16x32_bf16 v[94:97], v[142:145], v[214:217], v[94:97]
	v_mfma_f32_16x16x32_bf16 v[94:97], v[154:157], v[218:221], v[94:97]
	v_mfma_f32_16x16x32_bf16 v[78:81], v[154:157], v[226:229], v[78:81]
	v_mfma_f32_16x16x32_bf16 v[78:81], v[142:145], v[222:225], v[78:81]
	v_mfma_f32_16x16x32_bf16 v[70:73], v[158:161], v[222:225], v[70:73]
	v_mfma_f32_16x16x32_bf16 v[70:73], v[168:171], v[226:229], v[70:73]
	v_mfma_f32_16x16x32_bf16 v[86:89], v[168:171], v[218:221], v[86:89]
	v_mfma_f32_16x16x32_bf16 v[86:89], v[158:161], v[214:217], v[86:89]
	v_mfma_f32_16x16x32_bf16 v[102:105], v[158:161], v[206:209], v[102:105]
	v_mfma_f32_16x16x32_bf16 v[102:105], v[168:171], v[210:213], v[102:105]
	v_mfma_f32_16x16x32_bf16 v[118:121], v[168:171], v[202:205], v[118:121]
	v_mfma_f32_16x16x32_bf16 v[118:121], v[158:161], v[192:195], v[118:121]
	v_mfma_f32_16x16x32_bf16 v[122:125], v[176:179], v[192:195], v[122:125]
	v_mfma_f32_16x16x32_bf16 v[122:125], v[180:183], v[202:205], v[122:125]
	v_mfma_f32_16x16x32_bf16 v[106:109], v[180:183], v[210:213], v[106:109]
	v_mfma_f32_16x16x32_bf16 v[106:109], v[176:179], v[206:209], v[106:109]
	v_mfma_f32_16x16x32_bf16 v[90:93], v[176:179], v[214:217], v[90:93]
	v_mfma_f32_16x16x32_bf16 v[90:93], v[180:183], v[218:221], v[90:93]
	v_mfma_f32_16x16x32_bf16 v[74:77], v[180:183], v[226:229], v[74:77]
	v_mfma_f32_16x16x32_bf16 v[74:77], v[176:179], v[222:225], v[74:77]
	v_mfma_f32_16x16x32_bf16 v[66:69], v[184:187], v[222:225], v[66:69]
	v_mfma_f32_16x16x32_bf16 v[66:69], v[188:191], v[226:229], v[66:69]
	v_mfma_f32_16x16x32_bf16 v[82:85], v[188:191], v[218:221], v[82:85]
	v_mfma_f32_16x16x32_bf16 v[82:85], v[184:187], v[214:217], v[82:85]
	v_mfma_f32_16x16x32_bf16 v[98:101], v[184:187], v[206:209], v[98:101]
	v_mfma_f32_16x16x32_bf16 v[98:101], v[188:191], v[210:213], v[98:101]
	v_mfma_f32_16x16x32_bf16 v[114:117], v[188:191], v[202:205], v[114:117]
	v_mfma_f32_16x16x32_bf16 v[114:117], v[184:187], v[192:195], v[114:117]
	s_setprio 0
	s_barrier
	s_mov_b32 m0, s48
	s_add_u32 s22, s22, 0x80
	s_addc_u32 s23, s23, 0
	global_load_lds_dwordx4 v132, s[22:23]
	s_mov_b32 m0, s49
	ds_read_b128 v[192:195], v150 offset:49152
	global_load_lds_dwordx4 v136, s[22:23]
	s_mov_b32 m0, s50
	s_add_u32 s22, s22, 0x100000
	s_addc_u32 s23, s23, 0
	global_load_lds_dwordx4 v132, s[22:23]
	s_mov_b32 m0, s51
	ds_read_b128 v[202:205], v150 offset:50176
	global_load_lds_dwordx4 v136, s[22:23]
	ds_read_b128 v[206:209], v150 offset:51200
	ds_read_b128 v[210:213], v150 offset:52224
	ds_read_b128 v[214:217], v150 offset:53248
	ds_read_b128 v[218:221], v150 offset:54272
	ds_read_b128 v[222:225], v150 offset:55296
	ds_read_b128 v[226:229], v150 offset:56320
	s_waitcnt vmcnt(6)
	s_waitcnt lgkmcnt(0)
	s_barrier
	s_setprio 1
	s_waitcnt lgkmcnt(0)
	v_mfma_f32_16x16x32_bf16 v[62:65], v[142:145], v[192:195], v[62:65]
	v_mfma_f32_16x16x32_bf16 v[62:65], v[154:157], v[202:205], v[62:65]
	v_mfma_f32_16x16x32_bf16 v[46:49], v[154:157], v[210:213], v[46:49]
	v_mfma_f32_16x16x32_bf16 v[46:49], v[142:145], v[206:209], v[46:49]
	v_mfma_f32_16x16x32_bf16 v[30:33], v[142:145], v[214:217], v[30:33]
	v_mfma_f32_16x16x32_bf16 v[30:33], v[154:157], v[218:221], v[30:33]
	v_mfma_f32_16x16x32_bf16 v[14:17], v[154:157], v[226:229], v[14:17]
	v_mfma_f32_16x16x32_bf16 v[14:17], v[142:145], v[222:225], v[14:17]
	v_mfma_f32_16x16x32_bf16 v[6:9], v[158:161], v[222:225], v[6:9]
	v_mfma_f32_16x16x32_bf16 v[6:9], v[168:171], v[226:229], v[6:9]
	v_mfma_f32_16x16x32_bf16 v[22:25], v[168:171], v[218:221], v[22:25]
	v_mfma_f32_16x16x32_bf16 v[22:25], v[158:161], v[214:217], v[22:25]
	v_mfma_f32_16x16x32_bf16 v[38:41], v[158:161], v[206:209], v[38:41]
	v_mfma_f32_16x16x32_bf16 v[38:41], v[168:171], v[210:213], v[38:41]
	v_mfma_f32_16x16x32_bf16 v[54:57], v[168:171], v[202:205], v[54:57]
	v_mfma_f32_16x16x32_bf16 v[54:57], v[158:161], v[192:195], v[54:57]
	v_mfma_f32_16x16x32_bf16 v[58:61], v[176:179], v[192:195], v[58:61]
	v_mfma_f32_16x16x32_bf16 v[58:61], v[180:183], v[202:205], v[58:61]
	v_mfma_f32_16x16x32_bf16 v[42:45], v[180:183], v[210:213], v[42:45]
	v_mfma_f32_16x16x32_bf16 v[42:45], v[176:179], v[206:209], v[42:45]
	v_mfma_f32_16x16x32_bf16 v[26:29], v[176:179], v[214:217], v[26:29]
	v_mfma_f32_16x16x32_bf16 v[26:29], v[180:183], v[218:221], v[26:29]
	v_mfma_f32_16x16x32_bf16 v[10:13], v[180:183], v[226:229], v[10:13]
	v_mfma_f32_16x16x32_bf16 v[10:13], v[176:179], v[222:225], v[10:13]
	v_mfma_f32_16x16x32_bf16 v[2:5], v[184:187], v[222:225], v[2:5]
	v_mfma_f32_16x16x32_bf16 v[2:5], v[188:191], v[226:229], v[2:5]
	v_mfma_f32_16x16x32_bf16 v[18:21], v[188:191], v[218:221], v[18:21]
	v_mfma_f32_16x16x32_bf16 v[18:21], v[184:187], v[214:217], v[18:21]
	v_mfma_f32_16x16x32_bf16 v[34:37], v[184:187], v[206:209], v[34:37]
	v_mfma_f32_16x16x32_bf16 v[34:37], v[188:191], v[210:213], v[34:37]
	v_mfma_f32_16x16x32_bf16 v[50:53], v[188:191], v[202:205], v[50:53]
	v_mfma_f32_16x16x32_bf16 v[50:53], v[184:187], v[192:195], v[50:53]
	s_setprio 0
	s_barrier
	s_add_i32 s61, s61, 2
	s_add_u32 s20, s20, 0x100
	s_addc_u32 s21, s21, 0
	s_add_u32 s57, s57, 0x100
	s_addc_u32 s60, s60, 0
	s_cmp_gt_u32 s61, 61
	s_cbranch_scc0 .LBB0_1172
	s_and_b64 vcc, exec, s[16:17]
	s_cbranch_vccz .LBB0_1175
	s_barrier

.LBB0_1418:
	s_add_u32 s56, s22, 0xffd50000
	s_addc_u32 s57, s23, -1
	s_mov_b32 m0, s40
	ds_read_b128 v[142:145], v156
	global_load_lds_dwordx4 v130, s[56:57]
	s_mov_b32 m0, s41
	ds_read_b128 v[168:171], v156 offset:1024
	global_load_lds_dwordx4 v134, s[56:57]
	s_mov_b32 m0, s42
	ds_read_b128 v[176:179], v156 offset:2048
	global_load_lds_dwordx4 v138, s[22:23]
	s_mov_b32 m0, s43
	ds_read_b128 v[180:183], v156 offset:3072
	global_load_lds_dwordx4 v140, s[22:23]
	ds_read_b128 v[184:187], v157
	ds_read_b128 v[188:191], v157 offset:1024
	ds_read_b128 v[192:195], v157 offset:2048
	ds_read_b128 v[204:207], v157 offset:3072
	s_add_u32 s24, s22, 0xffd50080
	s_addc_u32 s25, s23, -1
	s_cmpk_eq_i32 s55, 0xa8
	s_cselect_b32 s27, s19, s25
	s_cselect_b32 s26, s18, s24
	s_cselect_b32 s25, s17, s54
	s_cselect_b32 s24, s16, s53
	ds_read_b128 v[208:211], v158
	ds_read_b128 v[212:215], v158 offset:1024
	ds_read_b128 v[216:219], v158 offset:2048
	ds_read_b128 v[220:223], v158 offset:3072
	ds_read_b128 v[224:227], v158 offset:4096
	ds_read_b128 v[228:231], v158 offset:5120
	ds_read_b128 v[232:235], v158 offset:6144
	ds_read_b128 v[236:239], v158 offset:7168
	s_waitcnt vmcnt(8)
	s_waitcnt lgkmcnt(0)
	s_barrier
	s_setprio 1
	s_waitcnt lgkmcnt(0)
	v_mfma_f32_16x16x32_bf16 v[126:129], v[142:145], v[208:211], v[126:129]
	v_mfma_f32_16x16x32_bf16 v[126:129], v[168:171], v[212:215], v[126:129]
	v_mfma_f32_16x16x32_bf16 v[110:113], v[168:171], v[220:223], v[110:113]
	v_mfma_f32_16x16x32_bf16 v[110:113], v[142:145], v[216:219], v[110:113]
	v_mfma_f32_16x16x32_bf16 v[94:97], v[142:145], v[224:227], v[94:97]
	v_mfma_f32_16x16x32_bf16 v[94:97], v[168:171], v[228:231], v[94:97]
	v_mfma_f32_16x16x32_bf16 v[78:81], v[168:171], v[236:239], v[78:81]
	v_mfma_f32_16x16x32_bf16 v[78:81], v[142:145], v[232:235], v[78:81]
	v_mfma_f32_16x16x32_bf16 v[74:77], v[176:179], v[232:235], v[74:77]
	v_mfma_f32_16x16x32_bf16 v[74:77], v[180:183], v[236:239], v[74:77]
	v_mfma_f32_16x16x32_bf16 v[90:93], v[180:183], v[228:231], v[90:93]
	v_mfma_f32_16x16x32_bf16 v[90:93], v[176:179], v[224:227], v[90:93]
	v_mfma_f32_16x16x32_bf16 v[106:109], v[176:179], v[216:219], v[106:109]
	v_mfma_f32_16x16x32_bf16 v[106:109], v[180:183], v[220:223], v[106:109]
	v_mfma_f32_16x16x32_bf16 v[122:125], v[180:183], v[212:215], v[122:125]
	v_mfma_f32_16x16x32_bf16 v[122:125], v[176:179], v[208:211], v[122:125]
	v_mfma_f32_16x16x32_bf16 v[118:121], v[184:187], v[208:211], v[118:121]
	v_mfma_f32_16x16x32_bf16 v[118:121], v[188:191], v[212:215], v[118:121]
	v_mfma_f32_16x16x32_bf16 v[102:105], v[188:191], v[220:223], v[102:105]
	v_mfma_f32_16x16x32_bf16 v[102:105], v[184:187], v[216:219], v[102:105]
	v_mfma_f32_16x16x32_bf16 v[86:89], v[184:187], v[224:227], v[86:89]
	v_mfma_f32_16x16x32_bf16 v[86:89], v[188:191], v[228:231], v[86:89]
	v_mfma_f32_16x16x32_bf16 v[70:73], v[188:191], v[236:239], v[70:73]
	v_mfma_f32_16x16x32_bf16 v[70:73], v[184:187], v[232:235], v[70:73]
	v_mfma_f32_16x16x32_bf16 v[66:69], v[192:195], v[232:235], v[66:69]
	v_mfma_f32_16x16x32_bf16 v[66:69], v[204:207], v[236:239], v[66:69]
	v_mfma_f32_16x16x32_bf16 v[82:85], v[204:207], v[228:231], v[82:85]
	v_mfma_f32_16x16x32_bf16 v[82:85], v[192:195], v[224:227], v[82:85]
	v_mfma_f32_16x16x32_bf16 v[98:101], v[192:195], v[216:219], v[98:101]
	v_mfma_f32_16x16x32_bf16 v[98:101], v[204:207], v[220:223], v[98:101]
	v_mfma_f32_16x16x32_bf16 v[114:117], v[204:207], v[212:215], v[114:117]
	v_mfma_f32_16x16x32_bf16 v[114:117], v[192:195], v[208:211], v[114:117]
	s_setprio 0
	s_barrier
	s_mov_b32 m0, s44
	s_add_u32 s56, s24, 0x2b0000
	global_load_lds_dwordx4 v132, s[24:25]
	s_mov_b32 m0, s45
	s_addc_u32 s57, s25, 0
	global_load_lds_dwordx4 v136, s[24:25]
	s_mov_b32 m0, s46
	ds_read_b128 v[208:211], v158 offset:16384
	global_load_lds_dwordx4 v132, s[56:57]
	s_mov_b32 m0, s47
	ds_read_b128 v[212:215], v158 offset:17408
	global_load_lds_dwordx4 v136, s[56:57]
	ds_read_b128 v[216:219], v158 offset:18432
	ds_read_b128 v[220:223], v158 offset:19456
	ds_read_b128 v[224:227], v158 offset:20480
	ds_read_b128 v[228:231], v158 offset:21504
	ds_read_b128 v[232:235], v158 offset:22528
	ds_read_b128 v[236:239], v158 offset:23552
	s_waitcnt vmcnt(6)
	s_waitcnt lgkmcnt(0)
	s_barrier
	s_setprio 1
	s_waitcnt lgkmcnt(0)
	v_mfma_f32_16x16x32_bf16 v[62:65], v[142:145], v[208:211], v[62:65]
	v_mfma_f32_16x16x32_bf16 v[62:65], v[168:171], v[212:215], v[62:65]
	v_mfma_f32_16x16x32_bf16 v[46:49], v[168:171], v[220:223], v[46:49]
	v_mfma_f32_16x16x32_bf16 v[46:49], v[142:145], v[216:219], v[46:49]
	v_mfma_f32_16x16x32_bf16 v[30:33], v[142:145], v[224:227], v[30:33]
	v_mfma_f32_16x16x32_bf16 v[30:33], v[168:171], v[228:231], v[30:33]
	v_mfma_f32_16x16x32_bf16 v[14:17], v[168:171], v[236:239], v[14:17]
	v_mfma_f32_16x16x32_bf16 v[14:17], v[142:145], v[232:235], v[14:17]
	v_mfma_f32_16x16x32_bf16 v[10:13], v[176:179], v[232:235], v[10:13]
	v_mfma_f32_16x16x32_bf16 v[10:13], v[180:183], v[236:239], v[10:13]
	v_mfma_f32_16x16x32_bf16 v[26:29], v[180:183], v[228:231], v[26:29]
	v_mfma_f32_16x16x32_bf16 v[26:29], v[176:179], v[224:227], v[26:29]
	v_mfma_f32_16x16x32_bf16 v[42:45], v[176:179], v[216:219], v[42:45]
	v_mfma_f32_16x16x32_bf16 v[42:45], v[180:183], v[220:223], v[42:45]
	v_mfma_f32_16x16x32_bf16 v[58:61], v[180:183], v[212:215], v[58:61]
	v_mfma_f32_16x16x32_bf16 v[58:61], v[176:179], v[208:211], v[58:61]
	v_mfma_f32_16x16x32_bf16 v[54:57], v[184:187], v[208:211], v[54:57]
	v_mfma_f32_16x16x32_bf16 v[54:57], v[188:191], v[212:215], v[54:57]
	v_mfma_f32_16x16x32_bf16 v[38:41], v[188:191], v[220:223], v[38:41]
	v_mfma_f32_16x16x32_bf16 v[38:41], v[184:187], v[216:219], v[38:41]
	v_mfma_f32_16x16x32_bf16 v[22:25], v[184:187], v[224:227], v[22:25]
	v_mfma_f32_16x16x32_bf16 v[22:25], v[188:191], v[228:231], v[22:25]
	v_mfma_f32_16x16x32_bf16 v[6:9], v[188:191], v[236:239], v[6:9]
	v_mfma_f32_16x16x32_bf16 v[6:9], v[184:187], v[232:235], v[6:9]
	v_mfma_f32_16x16x32_bf16 v[2:5], v[192:195], v[232:235], v[2:5]
	v_mfma_f32_16x16x32_bf16 v[2:5], v[204:207], v[236:239], v[2:5]
	v_mfma_f32_16x16x32_bf16 v[18:21], v[204:207], v[228:231], v[18:21]
	v_mfma_f32_16x16x32_bf16 v[18:21], v[192:195], v[224:227], v[18:21]
	v_mfma_f32_16x16x32_bf16 v[34:37], v[192:195], v[216:219], v[34:37]
	v_mfma_f32_16x16x32_bf16 v[34:37], v[204:207], v[220:223], v[34:37]
	v_mfma_f32_16x16x32_bf16 v[50:53], v[204:207], v[212:215], v[50:53]
	v_mfma_f32_16x16x32_bf16 v[50:53], v[192:195], v[208:211], v[50:53]
	s_setprio 0
	s_barrier
	s_mov_b32 m0, s35
	ds_read_b128 v[142:145], v159
	global_load_lds_dwordx4 v130, s[26:27]
	s_mov_b32 m0, s36
	ds_read_b128 v[168:171], v159 offset:1024
	global_load_lds_dwordx4 v134, s[26:27]
	s_add_u32 s26, s26, 0x2b0000
	s_addc_u32 s27, s27, 0
	s_mov_b32 m0, s37
	ds_read_b128 v[176:179], v159 offset:2048
	global_load_lds_dwordx4 v130, s[26:27]
	s_mov_b32 m0, s38
	ds_read_b128 v[180:183], v159 offset:3072
	global_load_lds_dwordx4 v134, s[26:27]
	ds_read_b128 v[184:187], v160
	ds_read_b128 v[188:191], v160 offset:1024
	ds_read_b128 v[192:195], v160 offset:2048
	ds_read_b128 v[204:207], v160 offset:3072
	ds_read_b128 v[208:211], v158 offset:32768
	ds_read_b128 v[212:215], v158 offset:33792
	ds_read_b128 v[216:219], v158 offset:34816
	ds_read_b128 v[220:223], v158 offset:35840
	ds_read_b128 v[224:227], v158 offset:36864
	ds_read_b128 v[228:231], v158 offset:37888
	ds_read_b128 v[232:235], v158 offset:38912
	ds_read_b128 v[236:239], v158 offset:39936
	s_waitcnt vmcnt(8)
	s_waitcnt lgkmcnt(0)
	s_barrier
	s_setprio 1
	s_waitcnt lgkmcnt(0)
	v_mfma_f32_16x16x32_bf16 v[126:129], v[142:145], v[208:211], v[126:129]
	v_mfma_f32_16x16x32_bf16 v[126:129], v[168:171], v[212:215], v[126:129]
	v_mfma_f32_16x16x32_bf16 v[110:113], v[168:171], v[220:223], v[110:113]
	v_mfma_f32_16x16x32_bf16 v[110:113], v[142:145], v[216:219], v[110:113]
	v_mfma_f32_16x16x32_bf16 v[94:97], v[142:145], v[224:227], v[94:97]
	v_mfma_f32_16x16x32_bf16 v[94:97], v[168:171], v[228:231], v[94:97]
	v_mfma_f32_16x16x32_bf16 v[78:81], v[168:171], v[236:239], v[78:81]
	v_mfma_f32_16x16x32_bf16 v[78:81], v[142:145], v[232:235], v[78:81]
	v_mfma_f32_16x16x32_bf16 v[74:77], v[176:179], v[232:235], v[74:77]
	v_mfma_f32_16x16x32_bf16 v[74:77], v[180:183], v[236:239], v[74:77]
	v_mfma_f32_16x16x32_bf16 v[90:93], v[180:183], v[228:231], v[90:93]
	v_mfma_f32_16x16x32_bf16 v[90:93], v[176:179], v[224:227], v[90:93]
	v_mfma_f32_16x16x32_bf16 v[106:109], v[176:179], v[216:219], v[106:109]
	v_mfma_f32_16x16x32_bf16 v[106:109], v[180:183], v[220:223], v[106:109]
	v_mfma_f32_16x16x32_bf16 v[122:125], v[180:183], v[212:215], v[122:125]
	v_mfma_f32_16x16x32_bf16 v[122:125], v[176:179], v[208:211], v[122:125]
	v_mfma_f32_16x16x32_bf16 v[118:121], v[184:187], v[208:211], v[118:121]
	v_mfma_f32_16x16x32_bf16 v[118:121], v[188:191], v[212:215], v[118:121]
	v_mfma_f32_16x16x32_bf16 v[102:105], v[188:191], v[220:223], v[102:105]
	v_mfma_f32_16x16x32_bf16 v[102:105], v[184:187], v[216:219], v[102:105]
	v_mfma_f32_16x16x32_bf16 v[86:89], v[184:187], v[224:227], v[86:89]
	v_mfma_f32_16x16x32_bf16 v[86:89], v[188:191], v[228:231], v[86:89]
	v_mfma_f32_16x16x32_bf16 v[70:73], v[188:191], v[236:239], v[70:73]
	v_mfma_f32_16x16x32_bf16 v[70:73], v[184:187], v[232:235], v[70:73]
	v_mfma_f32_16x16x32_bf16 v[66:69], v[192:195], v[232:235], v[66:69]
	v_mfma_f32_16x16x32_bf16 v[66:69], v[204:207], v[236:239], v[66:69]
	v_mfma_f32_16x16x32_bf16 v[82:85], v[204:207], v[228:231], v[82:85]
	v_mfma_f32_16x16x32_bf16 v[82:85], v[192:195], v[224:227], v[82:85]
	v_mfma_f32_16x16x32_bf16 v[98:101], v[192:195], v[216:219], v[98:101]
	v_mfma_f32_16x16x32_bf16 v[98:101], v[204:207], v[220:223], v[98:101]
	v_mfma_f32_16x16x32_bf16 v[114:117], v[204:207], v[212:215], v[114:117]
	v_mfma_f32_16x16x32_bf16 v[114:117], v[192:195], v[208:211], v[114:117]
	s_setprio 0
	s_barrier
	s_mov_b32 m0, s48
	s_add_u32 s24, s24, 0x80
	s_addc_u32 s25, s25, 0
	global_load_lds_dwordx4 v132, s[24:25]
	s_mov_b32 m0, s49
	ds_read_b128 v[208:211], v158 offset:49152
	global_load_lds_dwordx4 v136, s[24:25]
	s_mov_b32 m0, s50
	s_add_u32 s24, s24, 0x2b0000
	s_addc_u32 s25, s25, 0
	global_load_lds_dwordx4 v132, s[24:25]
	s_add_i32 m0, s50, 0x2000
	ds_read_b128 v[212:215], v158 offset:50176
	global_load_lds_dwordx4 v136, s[24:25]
	ds_read_b128 v[216:219], v158 offset:51200
	ds_read_b128 v[220:223], v158 offset:52224
	ds_read_b128 v[224:227], v158 offset:53248
	ds_read_b128 v[228:231], v158 offset:54272
	ds_read_b128 v[232:235], v158 offset:55296
	ds_read_b128 v[236:239], v158 offset:56320
	s_waitcnt vmcnt(6)
	s_waitcnt lgkmcnt(0)
	s_barrier
	s_setprio 1
	s_waitcnt lgkmcnt(0)
	v_mfma_f32_16x16x32_bf16 v[62:65], v[142:145], v[208:211], v[62:65]
	v_mfma_f32_16x16x32_bf16 v[62:65], v[168:171], v[212:215], v[62:65]
	v_mfma_f32_16x16x32_bf16 v[46:49], v[168:171], v[220:223], v[46:49]
	v_mfma_f32_16x16x32_bf16 v[46:49], v[142:145], v[216:219], v[46:49]
	v_mfma_f32_16x16x32_bf16 v[30:33], v[142:145], v[224:227], v[30:33]
	v_mfma_f32_16x16x32_bf16 v[30:33], v[168:171], v[228:231], v[30:33]
	v_mfma_f32_16x16x32_bf16 v[14:17], v[168:171], v[236:239], v[14:17]
	v_mfma_f32_16x16x32_bf16 v[14:17], v[142:145], v[232:235], v[14:17]
	v_mfma_f32_16x16x32_bf16 v[10:13], v[176:179], v[232:235], v[10:13]
	v_mfma_f32_16x16x32_bf16 v[10:13], v[180:183], v[236:239], v[10:13]
	v_mfma_f32_16x16x32_bf16 v[26:29], v[180:183], v[228:231], v[26:29]
	v_mfma_f32_16x16x32_bf16 v[26:29], v[176:179], v[224:227], v[26:29]
	v_mfma_f32_16x16x32_bf16 v[42:45], v[176:179], v[216:219], v[42:45]
	v_mfma_f32_16x16x32_bf16 v[42:45], v[180:183], v[220:223], v[42:45]
	v_mfma_f32_16x16x32_bf16 v[58:61], v[180:183], v[212:215], v[58:61]
	v_mfma_f32_16x16x32_bf16 v[58:61], v[176:179], v[208:211], v[58:61]
	v_mfma_f32_16x16x32_bf16 v[54:57], v[184:187], v[208:211], v[54:57]
	v_mfma_f32_16x16x32_bf16 v[54:57], v[188:191], v[212:215], v[54:57]
	v_mfma_f32_16x16x32_bf16 v[38:41], v[188:191], v[220:223], v[38:41]
	v_mfma_f32_16x16x32_bf16 v[38:41], v[184:187], v[216:219], v[38:41]
	v_mfma_f32_16x16x32_bf16 v[22:25], v[184:187], v[224:227], v[22:25]
	v_mfma_f32_16x16x32_bf16 v[22:25], v[188:191], v[228:231], v[22:25]
	v_mfma_f32_16x16x32_bf16 v[6:9], v[188:191], v[236:239], v[6:9]
	v_mfma_f32_16x16x32_bf16 v[6:9], v[184:187], v[232:235], v[6:9]
	v_mfma_f32_16x16x32_bf16 v[2:5], v[192:195], v[232:235], v[2:5]
	v_mfma_f32_16x16x32_bf16 v[2:5], v[204:207], v[236:239], v[2:5]
	v_mfma_f32_16x16x32_bf16 v[18:21], v[204:207], v[228:231], v[18:21]
	v_mfma_f32_16x16x32_bf16 v[18:21], v[192:195], v[224:227], v[18:21]
	v_mfma_f32_16x16x32_bf16 v[34:37], v[192:195], v[216:219], v[34:37]
	v_mfma_f32_16x16x32_bf16 v[34:37], v[204:207], v[220:223], v[34:37]
	v_mfma_f32_16x16x32_bf16 v[50:53], v[204:207], v[212:215], v[50:53]
	v_mfma_f32_16x16x32_bf16 v[50:53], v[192:195], v[208:211], v[50:53]
	s_setprio 0
	s_barrier
	s_add_i32 s55, s55, 2
	s_add_u32 s22, s22, 0x100
	s_addc_u32 s23, s23, 0
	s_add_u32 s53, s53, 0x100
	s_addc_u32 s54, s54, 0
	s_cmpk_gt_u32 s55, 0xa9
	s_cbranch_scc0 .LBB0_1418
	s_and_b64 vcc, exec, s[14:15]
	s_cbranch_vccz .LBB0_1421
	s_barrier

.LBB0_1432:
	ds_read_b128 v[150:153], v139
	ds_read_b128 v[154:157], v139 offset:1024
	ds_read_b128 v[158:161], v139 offset:2048
	ds_read_b128 v[168:171], v139 offset:3072
	ds_read_b128 v[176:179], v144
	ds_read_b128 v[180:183], v144 offset:1024
	ds_read_b128 v[184:187], v144 offset:2048
	ds_read_b128 v[188:191], v144 offset:3072
	s_add_i32 s42, s15, 2
	s_add_u32 s14, s12, 0xc2050080
	s_addc_u32 s16, s13, -1
	s_cmp_lg_u32 s30, s15
	s_cselect_b32 s14, s14, 0
	s_cselect_b32 s15, s16, 0
	s_add_u32 s16, s4, s14
	s_addc_u32 s17, s5, s15
	s_add_u32 s14, s8, s14
	s_addc_u32 s15, s9, s15
	s_mov_b32 m0, s31
	v_lshl_add_u64 v[172:173], v[140:141], 0, s[12:13]
	ds_read_b128 v[192:195], v145
	ds_read_b128 v[204:207], v145 offset:1024
	ds_read_b128 v[208:211], v145 offset:2048
	ds_read_b128 v[212:215], v145 offset:3072
	ds_read_b128 v[216:219], v145 offset:4096
	ds_read_b128 v[220:223], v145 offset:5120
	ds_read_b128 v[224:227], v145 offset:6144
	ds_read_b128 v[228:231], v145 offset:7168
	global_load_lds_dwordx4 v[172:173], off
	v_lshl_add_u64 v[172:173], v[142:143], 0, s[12:13]
	s_mov_b32 m0, s33
	s_nop 0
	global_load_lds_dwordx4 v[172:173], off
	s_waitcnt vmcnt(8)
	s_waitcnt lgkmcnt(0)
	s_barrier
	s_setprio 1
	s_waitcnt lgkmcnt(0)
	v_mfma_f32_16x16x32_bf16 v[126:129], v[150:153], v[192:195], v[126:129]
	v_mfma_f32_16x16x32_bf16 v[126:129], v[154:157], v[204:207], v[126:129]
	v_mfma_f32_16x16x32_bf16 v[118:121], v[154:157], v[212:215], v[118:121]
	v_mfma_f32_16x16x32_bf16 v[118:121], v[150:153], v[208:211], v[118:121]
	v_mfma_f32_16x16x32_bf16 v[102:105], v[150:153], v[216:219], v[102:105]
	v_mfma_f32_16x16x32_bf16 v[102:105], v[154:157], v[220:223], v[102:105]
	v_mfma_f32_16x16x32_bf16 v[86:89], v[154:157], v[228:231], v[86:89]
	v_mfma_f32_16x16x32_bf16 v[86:89], v[150:153], v[224:227], v[86:89]
	v_mfma_f32_16x16x32_bf16 v[82:85], v[158:161], v[224:227], v[82:85]
	v_mfma_f32_16x16x32_bf16 v[82:85], v[168:171], v[228:231], v[82:85]
	v_mfma_f32_16x16x32_bf16 v[98:101], v[168:171], v[220:223], v[98:101]
	v_mfma_f32_16x16x32_bf16 v[98:101], v[158:161], v[216:219], v[98:101]
	v_mfma_f32_16x16x32_bf16 v[114:117], v[158:161], v[208:211], v[114:117]
	v_mfma_f32_16x16x32_bf16 v[114:117], v[168:171], v[212:215], v[114:117]
	v_mfma_f32_16x16x32_bf16 v[122:125], v[168:171], v[204:207], v[122:125]
	v_mfma_f32_16x16x32_bf16 v[122:125], v[158:161], v[192:195], v[122:125]
	v_mfma_f32_16x16x32_bf16 v[110:113], v[176:179], v[192:195], v[110:113]
	v_mfma_f32_16x16x32_bf16 v[110:113], v[180:183], v[204:207], v[110:113]
	v_mfma_f32_16x16x32_bf16 v[94:97], v[180:183], v[212:215], v[94:97]
	v_mfma_f32_16x16x32_bf16 v[94:97], v[176:179], v[208:211], v[94:97]
	v_mfma_f32_16x16x32_bf16 v[78:81], v[176:179], v[216:219], v[78:81]
	v_mfma_f32_16x16x32_bf16 v[78:81], v[180:183], v[220:223], v[78:81]
	v_mfma_f32_16x16x32_bf16 v[70:73], v[180:183], v[228:231], v[70:73]
	v_mfma_f32_16x16x32_bf16 v[70:73], v[176:179], v[224:227], v[70:73]
	v_mfma_f32_16x16x32_bf16 v[66:69], v[184:187], v[224:227], v[66:69]
	v_mfma_f32_16x16x32_bf16 v[66:69], v[188:191], v[228:231], v[66:69]
	v_mfma_f32_16x16x32_bf16 v[74:77], v[188:191], v[220:223], v[74:77]
	v_mfma_f32_16x16x32_bf16 v[74:77], v[184:187], v[216:219], v[74:77]
	v_mfma_f32_16x16x32_bf16 v[90:93], v[184:187], v[208:211], v[90:93]
	v_mfma_f32_16x16x32_bf16 v[90:93], v[188:191], v[212:215], v[90:93]
	v_mfma_f32_16x16x32_bf16 v[106:109], v[188:191], v[204:207], v[106:109]
	v_mfma_f32_16x16x32_bf16 v[106:109], v[184:187], v[192:195], v[106:109]
	s_setprio 0
	s_barrier
	s_mov_b32 m0, s34
	v_lshl_add_u64 v[172:173], s[14:15], 0, v[132:133]
	s_add_u32 s44, s14, 0x2b0000
	ds_read_b128 v[192:195], v145 offset:16384
	ds_read_b128 v[204:207], v145 offset:17408
	ds_read_b128 v[208:211], v145 offset:18432
	ds_read_b128 v[212:215], v145 offset:19456
	ds_read_b128 v[216:219], v145 offset:20480
	ds_read_b128 v[220:223], v145 offset:21504
	ds_read_b128 v[224:227], v145 offset:22528
	ds_read_b128 v[228:231], v145 offset:23552
	global_load_lds_dwordx4 v[172:173], off
	v_lshl_add_u64 v[196:197], s[14:15], 0, v[136:137]
	s_mov_b32 m0, s35
	s_addc_u32 s45, s15, 0
	global_load_lds_dwordx4 v[196:197], off
	v_lshl_add_u64 v[232:233], s[44:45], 0, v[132:133]
	s_mov_b32 m0, s36
	v_lshl_add_u64 v[234:235], s[16:17], 0, v[134:135]
	global_load_lds_dwordx4 v[232:233], off
	v_lshl_add_u64 v[232:233], s[44:45], 0, v[136:137]
	s_mov_b32 m0, s37
	s_nop 0
	global_load_lds_dwordx4 v[232:233], off
	v_lshl_add_u64 v[232:233], s[16:17], 0, v[130:131]
	s_mov_b32 m0, s21
	s_nop 0
	global_load_lds_dwordx4 v[232:233], off
	s_mov_b32 m0, s22
	s_nop 0
	global_load_lds_dwordx4 v[234:235], off
	s_waitcnt vmcnt(8)
	s_waitcnt lgkmcnt(0)
	s_barrier
	s_setprio 1
	s_waitcnt lgkmcnt(0)
	v_mfma_f32_16x16x32_bf16 v[62:65], v[150:153], v[192:195], v[62:65]
	v_mfma_f32_16x16x32_bf16 v[62:65], v[154:157], v[204:207], v[62:65]
	v_mfma_f32_16x16x32_bf16 v[54:57], v[154:157], v[212:215], v[54:57]
	v_mfma_f32_16x16x32_bf16 v[54:57], v[150:153], v[208:211], v[54:57]
	v_mfma_f32_16x16x32_bf16 v[38:41], v[150:153], v[216:219], v[38:41]
	v_mfma_f32_16x16x32_bf16 v[38:41], v[154:157], v[220:223], v[38:41]
	v_mfma_f32_16x16x32_bf16 v[22:25], v[154:157], v[228:231], v[22:25]
	v_mfma_f32_16x16x32_bf16 v[22:25], v[150:153], v[224:227], v[22:25]
	v_mfma_f32_16x16x32_bf16 v[18:21], v[158:161], v[224:227], v[18:21]
	v_mfma_f32_16x16x32_bf16 v[18:21], v[168:171], v[228:231], v[18:21]
	v_mfma_f32_16x16x32_bf16 v[34:37], v[168:171], v[220:223], v[34:37]
	v_mfma_f32_16x16x32_bf16 v[34:37], v[158:161], v[216:219], v[34:37]
	v_mfma_f32_16x16x32_bf16 v[50:53], v[158:161], v[208:211], v[50:53]
	v_mfma_f32_16x16x32_bf16 v[50:53], v[168:171], v[212:215], v[50:53]
	v_mfma_f32_16x16x32_bf16 v[58:61], v[168:171], v[204:207], v[58:61]
	v_mfma_f32_16x16x32_bf16 v[58:61], v[158:161], v[192:195], v[58:61]
	v_mfma_f32_16x16x32_bf16 v[46:49], v[176:179], v[192:195], v[46:49]
	v_mfma_f32_16x16x32_bf16 v[46:49], v[180:183], v[204:207], v[46:49]
	v_mfma_f32_16x16x32_bf16 v[30:33], v[180:183], v[212:215], v[30:33]
	v_mfma_f32_16x16x32_bf16 v[30:33], v[176:179], v[208:211], v[30:33]
	v_mfma_f32_16x16x32_bf16 v[14:17], v[176:179], v[216:219], v[14:17]
	v_mfma_f32_16x16x32_bf16 v[14:17], v[180:183], v[220:223], v[14:17]
	v_mfma_f32_16x16x32_bf16 v[6:9], v[180:183], v[228:231], v[6:9]
	v_mfma_f32_16x16x32_bf16 v[6:9], v[176:179], v[224:227], v[6:9]
	v_mfma_f32_16x16x32_bf16 v[2:5], v[184:187], v[224:227], v[2:5]
	v_mfma_f32_16x16x32_bf16 v[2:5], v[188:191], v[228:231], v[2:5]
	v_mfma_f32_16x16x32_bf16 v[10:13], v[188:191], v[220:223], v[10:13]
	v_mfma_f32_16x16x32_bf16 v[10:13], v[184:187], v[216:219], v[10:13]
	v_mfma_f32_16x16x32_bf16 v[26:29], v[184:187], v[208:211], v[26:29]
	v_mfma_f32_16x16x32_bf16 v[26:29], v[188:191], v[212:215], v[26:29]
	v_mfma_f32_16x16x32_bf16 v[42:45], v[188:191], v[204:207], v[42:45]
	v_mfma_f32_16x16x32_bf16 v[42:45], v[184:187], v[192:195], v[42:45]
	s_setprio 0
	s_barrier
	ds_read_b128 v[150:153], v146
	ds_read_b128 v[154:157], v146 offset:1024
	ds_read_b128 v[158:161], v146 offset:2048
	ds_read_b128 v[168:171], v146 offset:3072
	ds_read_b128 v[176:179], v147
	ds_read_b128 v[180:183], v147 offset:1024
	ds_read_b128 v[184:187], v147 offset:2048
	ds_read_b128 v[188:191], v147 offset:3072
	s_add_u32 s16, s16, 0x2b0000
	s_addc_u32 s17, s17, 0
	s_mov_b32 m0, s23
	v_lshl_add_u64 v[236:237], s[16:17], 0, v[130:131]
	ds_read_b128 v[192:195], v145 offset:32768
	ds_read_b128 v[204:207], v145 offset:33792
	ds_read_b128 v[208:211], v145 offset:34816
	ds_read_b128 v[212:215], v145 offset:35840
	ds_read_b128 v[216:219], v145 offset:36864
	ds_read_b128 v[220:223], v145 offset:37888
	ds_read_b128 v[224:227], v145 offset:38912
	ds_read_b128 v[228:231], v145 offset:39936
	global_load_lds_dwordx4 v[236:237], off
	v_lshl_add_u64 v[236:237], s[16:17], 0, v[134:135]
	s_mov_b32 m0, s24
	s_nop 0
	global_load_lds_dwordx4 v[236:237], off
	s_waitcnt vmcnt(8)
	s_waitcnt lgkmcnt(0)
	s_barrier
	s_setprio 1
	s_waitcnt lgkmcnt(0)
	v_mfma_f32_16x16x32_bf16 v[126:129], v[150:153], v[192:195], v[126:129]
	v_mfma_f32_16x16x32_bf16 v[126:129], v[154:157], v[204:207], v[126:129]
	v_mfma_f32_16x16x32_bf16 v[118:121], v[154:157], v[212:215], v[118:121]
	v_mfma_f32_16x16x32_bf16 v[118:121], v[150:153], v[208:211], v[118:121]
	v_mfma_f32_16x16x32_bf16 v[102:105], v[150:153], v[216:219], v[102:105]
	v_mfma_f32_16x16x32_bf16 v[102:105], v[154:157], v[220:223], v[102:105]
	v_mfma_f32_16x16x32_bf16 v[86:89], v[154:157], v[228:231], v[86:89]
	v_mfma_f32_16x16x32_bf16 v[86:89], v[150:153], v[224:227], v[86:89]
	v_mfma_f32_16x16x32_bf16 v[82:85], v[158:161], v[224:227], v[82:85]
	v_mfma_f32_16x16x32_bf16 v[82:85], v[168:171], v[228:231], v[82:85]
	v_mfma_f32_16x16x32_bf16 v[98:101], v[168:171], v[220:223], v[98:101]
	v_mfma_f32_16x16x32_bf16 v[98:101], v[158:161], v[216:219], v[98:101]
	v_mfma_f32_16x16x32_bf16 v[114:117], v[158:161], v[208:211], v[114:117]
	v_mfma_f32_16x16x32_bf16 v[114:117], v[168:171], v[212:215], v[114:117]
	v_mfma_f32_16x16x32_bf16 v[122:125], v[168:171], v[204:207], v[122:125]
	v_mfma_f32_16x16x32_bf16 v[122:125], v[158:161], v[192:195], v[122:125]
	v_mfma_f32_16x16x32_bf16 v[110:113], v[176:179], v[192:195], v[110:113]
	v_mfma_f32_16x16x32_bf16 v[110:113], v[180:183], v[204:207], v[110:113]
	v_mfma_f32_16x16x32_bf16 v[94:97], v[180:183], v[212:215], v[94:97]
	v_mfma_f32_16x16x32_bf16 v[94:97], v[176:179], v[208:211], v[94:97]
	v_mfma_f32_16x16x32_bf16 v[78:81], v[176:179], v[216:219], v[78:81]
	v_mfma_f32_16x16x32_bf16 v[78:81], v[180:183], v[220:223], v[78:81]
	v_mfma_f32_16x16x32_bf16 v[70:73], v[180:183], v[228:231], v[70:73]
	v_mfma_f32_16x16x32_bf16 v[70:73], v[176:179], v[224:227], v[70:73]
	v_mfma_f32_16x16x32_bf16 v[66:69], v[184:187], v[224:227], v[66:69]
	v_mfma_f32_16x16x32_bf16 v[66:69], v[188:191], v[228:231], v[66:69]
	v_mfma_f32_16x16x32_bf16 v[74:77], v[188:191], v[220:223], v[74:77]
	v_mfma_f32_16x16x32_bf16 v[74:77], v[184:187], v[216:219], v[74:77]
	v_mfma_f32_16x16x32_bf16 v[90:93], v[184:187], v[208:211], v[90:93]
	v_mfma_f32_16x16x32_bf16 v[90:93], v[188:191], v[212:215], v[90:93]
	v_mfma_f32_16x16x32_bf16 v[106:109], v[188:191], v[204:207], v[106:109]
	v_mfma_f32_16x16x32_bf16 v[106:109], v[184:187], v[192:195], v[106:109]
	s_setprio 0
	s_barrier
	s_mov_b32 m0, s38
	v_lshl_add_u64 v[172:173], v[172:173], 0, s[10:11]
	s_add_u32 s14, s14, 0x2b0080
	ds_read_b128 v[192:195], v145 offset:49152
	ds_read_b128 v[204:207], v145 offset:50176
	ds_read_b128 v[208:211], v145 offset:51200
	ds_read_b128 v[212:215], v145 offset:52224
	ds_read_b128 v[216:219], v145 offset:53248
	ds_read_b128 v[220:223], v145 offset:54272
	ds_read_b128 v[224:227], v145 offset:55296
	ds_read_b128 v[228:231], v145 offset:56320
	global_load_lds_dwordx4 v[172:173], off
	v_lshl_add_u64 v[172:173], v[196:197], 0, s[10:11]
	s_mov_b32 m0, s39
	s_addc_u32 s15, s15, 0
	global_load_lds_dwordx4 v[172:173], off
	v_lshl_add_u64 v[172:173], s[14:15], 0, v[132:133]
	s_mov_b32 m0, s40
	s_nop 0
	global_load_lds_dwordx4 v[172:173], off
	v_lshl_add_u64 v[172:173], s[14:15], 0, v[136:137]
	s_mov_b32 m0, s41
	s_nop 0
	global_load_lds_dwordx4 v[172:173], off
	v_lshl_add_u64 v[172:173], v[232:233], 0, s[10:11]
	s_mov_b32 m0, s26
	s_nop 0
	global_load_lds_dwordx4 v[172:173], off
	v_lshl_add_u64 v[172:173], v[234:235], 0, s[10:11]
	s_mov_b32 m0, s27
	s_nop 0
	global_load_lds_dwordx4 v[172:173], off
	s_waitcnt vmcnt(8)
	s_waitcnt lgkmcnt(0)
	s_barrier
	s_setprio 1
	s_waitcnt lgkmcnt(0)
	v_mfma_f32_16x16x32_bf16 v[62:65], v[150:153], v[192:195], v[62:65]
	v_mfma_f32_16x16x32_bf16 v[62:65], v[154:157], v[204:207], v[62:65]
	v_mfma_f32_16x16x32_bf16 v[54:57], v[154:157], v[212:215], v[54:57]
	v_mfma_f32_16x16x32_bf16 v[54:57], v[150:153], v[208:211], v[54:57]
	v_mfma_f32_16x16x32_bf16 v[38:41], v[150:153], v[216:219], v[38:41]
	v_mfma_f32_16x16x32_bf16 v[38:41], v[154:157], v[220:223], v[38:41]
	v_mfma_f32_16x16x32_bf16 v[22:25], v[154:157], v[228:231], v[22:25]
	v_mfma_f32_16x16x32_bf16 v[22:25], v[150:153], v[224:227], v[22:25]
	v_mfma_f32_16x16x32_bf16 v[18:21], v[158:161], v[224:227], v[18:21]
	v_mfma_f32_16x16x32_bf16 v[18:21], v[168:171], v[228:231], v[18:21]
	v_mfma_f32_16x16x32_bf16 v[34:37], v[168:171], v[220:223], v[34:37]
	v_mfma_f32_16x16x32_bf16 v[34:37], v[158:161], v[216:219], v[34:37]
	v_mfma_f32_16x16x32_bf16 v[50:53], v[158:161], v[208:211], v[50:53]
	v_mfma_f32_16x16x32_bf16 v[50:53], v[168:171], v[212:215], v[50:53]
	v_mfma_f32_16x16x32_bf16 v[58:61], v[168:171], v[204:207], v[58:61]
	v_mfma_f32_16x16x32_bf16 v[58:61], v[158:161], v[192:195], v[58:61]
	v_mfma_f32_16x16x32_bf16 v[46:49], v[176:179], v[192:195], v[46:49]
	v_mfma_f32_16x16x32_bf16 v[46:49], v[180:183], v[204:207], v[46:49]
	v_mfma_f32_16x16x32_bf16 v[30:33], v[180:183], v[212:215], v[30:33]
	v_mfma_f32_16x16x32_bf16 v[30:33], v[176:179], v[208:211], v[30:33]
	v_mfma_f32_16x16x32_bf16 v[14:17], v[176:179], v[216:219], v[14:17]
	v_mfma_f32_16x16x32_bf16 v[14:17], v[180:183], v[220:223], v[14:17]
	v_mfma_f32_16x16x32_bf16 v[6:9], v[180:183], v[228:231], v[6:9]
	v_mfma_f32_16x16x32_bf16 v[6:9], v[176:179], v[224:227], v[6:9]
	v_mfma_f32_16x16x32_bf16 v[2:5], v[184:187], v[224:227], v[2:5]
	v_mfma_f32_16x16x32_bf16 v[2:5], v[188:191], v[228:231], v[2:5]
	v_mfma_f32_16x16x32_bf16 v[10:13], v[188:191], v[220:223], v[10:13]
	v_mfma_f32_16x16x32_bf16 v[10:13], v[184:187], v[216:219], v[10:13]
	v_mfma_f32_16x16x32_bf16 v[26:29], v[184:187], v[208:211], v[26:29]
	v_mfma_f32_16x16x32_bf16 v[26:29], v[188:191], v[212:215], v[26:29]
	v_mfma_f32_16x16x32_bf16 v[42:45], v[188:191], v[204:207], v[42:45]
	v_mfma_f32_16x16x32_bf16 v[42:45], v[184:187], v[192:195], v[42:45]
	s_setprio 0
	s_barrier
	s_add_u32 s12, s12, 0x100
	s_addc_u32 s13, s13, 0
	s_cmp_ge_u32 s42, s19
	s_mov_b32 s15, s42
	s_cbranch_scc0 .LBB0_1432
	s_lshl_b32 s4, s18, 21
	v_readlane_b32 s0, v249, 29
	v_lshl_or_b32 v130, s20, 8, v148
	v_mov_b32_e32 v139, 0
	s_add_u32 s4, s0, s4
	v_readlane_b32 s0, v249, 31
	v_or_b32_e32 v130, s25, v130
	v_cvt_pk_bf16_f32 v70, v70, v71
	v_cvt_pk_bf16_f32 v71, v72, v73
	v_cvt_pk_bf16_f32 v72, v66, v67
	v_add_u32_e32 v66, 0x80, v138
	v_mov_b32_e32 v67, v139
	s_addc_u32 s5, s0, 0
	v_ashrrev_i32_e32 v131, 31, v130
	v_lshlrev_b64 v[132:133], 13, v[138:139]
	v_cvt_pk_bf16_f32 v110, v110, v111
	v_cvt_pk_bf16_f32 v111, v112, v113
	v_cvt_pk_bf16_f32 v112, v106, v107
	v_or_b32_e32 v106, 16, v138
	v_mov_b32_e32 v107, v139
	v_lshlrev_b64 v[66:67], 13, v[66:67]
	v_cvt_pk_bf16_f32 v46, v46, v47
	v_cvt_pk_bf16_f32 v47, v48, v49
	v_cvt_pk_bf16_f32 v48, v42, v43
	v_add_u32_e32 v42, 0x90, v138
	v_mov_b32_e32 v43, v139
	v_lshl_add_u64 v[132:133], s[4:5], 0, v[132:133]
	v_lshlrev_b64 v[130:131], 1, v[130:131]
	v_lshlrev_b64 v[106:107], 13, v[106:107]
	v_cvt_pk_bf16_f32 v94, v94, v95
	v_cvt_pk_bf16_f32 v95, v96, v97
	v_cvt_pk_bf16_f32 v96, v90, v91
	v_or_b32_e32 v90, 32, v138
	v_mov_b32_e32 v91, v139
	v_lshl_add_u64 v[66:67], s[4:5], 0, v[66:67]
	v_lshlrev_b64 v[42:43], 13, v[42:43]
	v_cvt_pk_bf16_f32 v30, v30, v31
	v_cvt_pk_bf16_f32 v31, v32, v33
	v_cvt_pk_bf16_f32 v32, v26, v27
	v_add_u32_e32 v26, 0xa0, v138
	v_mov_b32_e32 v27, v139
	v_lshl_add_u64 v[132:133], v[132:133], 0, v[130:131]
	v_cvt_pk_bf16_f32 v113, v108, v109
	v_lshl_add_u64 v[106:107], s[4:5], 0, v[106:107]
	v_lshlrev_b64 v[90:91], 13, v[90:91]
	v_cvt_pk_bf16_f32 v78, v78, v79
	v_cvt_pk_bf16_f32 v79, v80, v81
	v_cvt_pk_bf16_f32 v80, v74, v75
	v_or_b32_e32 v74, 48, v138
	v_mov_b32_e32 v75, v139
	v_lshl_add_u64 v[66:67], v[66:67], 0, v[130:131]
	v_cvt_pk_bf16_f32 v49, v44, v45
	v_lshl_add_u64 v[42:43], s[4:5], 0, v[42:43]
	v_lshlrev_b64 v[26:27], 13, v[26:27]
	v_add_u32_e32 v138, 0xb0, v138
	global_store_dwordx4 v[132:133], v[110:113], off offset:256
	v_cvt_pk_bf16_f32 v97, v92, v93
	v_lshl_add_u64 v[90:91], s[4:5], 0, v[90:91]
	v_lshl_add_u64 v[110:111], v[106:107], 0, v[130:131]
	v_lshlrev_b64 v[74:75], 13, v[74:75]
	global_store_dwordx4 v[66:67], v[46:49], off offset:256
	v_cvt_pk_bf16_f32 v33, v28, v29
	v_lshl_add_u64 v[26:27], s[4:5], 0, v[26:27]
	v_lshl_add_u64 v[46:47], v[42:43], 0, v[130:131]
	v_cvt_pk_bf16_f32 v14, v14, v15
	v_cvt_pk_bf16_f32 v15, v16, v17
	v_cvt_pk_bf16_f32 v16, v10, v11
	v_lshlrev_b64 v[10:11], 13, v[138:139]
	global_store_dwordx4 v[110:111], v[94:97], off offset:256
	v_cvt_pk_bf16_f32 v81, v76, v77
	v_lshl_add_u64 v[74:75], s[4:5], 0, v[74:75]
	v_lshl_add_u64 v[94:95], v[90:91], 0, v[130:131]
	global_store_dwordx4 v[46:47], v[30:33], off offset:256
	v_cvt_pk_bf16_f32 v17, v12, v13
	v_lshl_add_u64 v[10:11], s[4:5], 0, v[10:11]
	v_lshl_add_u64 v[30:31], v[26:27], 0, v[130:131]
	v_cvt_pk_bf16_f32 v126, v126, v127
	v_cvt_pk_bf16_f32 v127, v128, v129
	v_cvt_pk_bf16_f32 v128, v122, v123
	v_cvt_pk_bf16_f32 v129, v124, v125
	v_cvt_pk_bf16_f32 v106, v118, v119
	v_cvt_pk_bf16_f32 v107, v120, v121
	v_cvt_pk_bf16_f32 v108, v114, v115
	v_cvt_pk_bf16_f32 v109, v116, v117
	v_cvt_pk_bf16_f32 v90, v102, v103
	v_cvt_pk_bf16_f32 v91, v104, v105
	v_cvt_pk_bf16_f32 v92, v98, v99
	v_cvt_pk_bf16_f32 v93, v100, v101
	global_store_dwordx4 v[94:95], v[78:81], off offset:256
	v_cvt_pk_bf16_f32 v76, v82, v83
	v_cvt_pk_bf16_f32 v77, v84, v85
	v_lshl_add_u64 v[78:79], v[74:75], 0, v[130:131]
	v_cvt_pk_bf16_f32 v74, v86, v87
	v_cvt_pk_bf16_f32 v75, v88, v89
	v_cvt_pk_bf16_f32 v73, v68, v69
	v_cvt_pk_bf16_f32 v62, v62, v63
	v_cvt_pk_bf16_f32 v63, v64, v65
	v_cvt_pk_bf16_f32 v64, v58, v59
	v_cvt_pk_bf16_f32 v65, v60, v61
	v_cvt_pk_bf16_f32 v42, v54, v55
	v_cvt_pk_bf16_f32 v43, v56, v57
	v_cvt_pk_bf16_f32 v44, v50, v51
	v_cvt_pk_bf16_f32 v45, v52, v53
	v_cvt_pk_bf16_f32 v26, v38, v39
	v_cvt_pk_bf16_f32 v27, v40, v41
	v_cvt_pk_bf16_f32 v28, v34, v35
	v_cvt_pk_bf16_f32 v29, v36, v37
	global_store_dwordx4 v[30:31], v[14:17], off offset:256
	v_cvt_pk_bf16_f32 v12, v18, v19
	v_cvt_pk_bf16_f32 v13, v20, v21
	v_lshl_add_u64 v[14:15], v[10:11], 0, v[130:131]
	v_cvt_pk_bf16_f32 v10, v22, v23
	v_cvt_pk_bf16_f32 v11, v24, v25
	v_cvt_pk_bf16_f32 v6, v6, v7
	v_cvt_pk_bf16_f32 v7, v8, v9
	v_cvt_pk_bf16_f32 v8, v2, v3
	v_cvt_pk_bf16_f32 v9, v4, v5
	global_store_dwordx4 v[132:133], v[126:129], off
	global_store_dwordx4 v[110:111], v[106:109], off
	global_store_dwordx4 v[94:95], v[90:93], off
	global_store_dwordx4 v[78:79], v[74:77], off
	global_store_dwordx4 v[78:79], v[70:73], off offset:256
	global_store_dwordx4 v[66:67], v[62:65], off
	global_store_dwordx4 v[46:47], v[42:45], off
	global_store_dwordx4 v[30:31], v[26:29], off
	global_store_dwordx4 v[14:15], v[10:13], off
	global_store_dwordx4 v[14:15], v[6:9], off offset:256
	s_waitcnt vmcnt(0)
	s_cmpk_lt_u32 s3, 0x100
	s_cbranch_scc0 .LBB0_1435
	s_barrier

.LBB0_1565:
	ds_read_b128 v[130:133], v204
	ds_read_b128 v[134:137], v204 offset:1024
	ds_read_b128 v[138:141], v204 offset:2048
	ds_read_b128 v[142:145], v204 offset:3072
	ds_read_b128 v[146:149], v205
	ds_read_b128 v[150:153], v205 offset:1024
	ds_read_b128 v[154:157], v205 offset:2048
	ds_read_b128 v[158:161], v205 offset:3072
	s_add_u32 s8, s6, 0xfff00080
	s_addc_u32 s9, s7, -1
	s_cmp_eq_u32 s66, 60
	s_cselect_b32 s73, s41, s9
	s_cselect_b32 s72, s50, s8
	s_cselect_b32 s9, s13, s57
	s_cselect_b32 s8, s51, s56
	v_lshl_add_u64 v[196:197], s[6:7], 0, v[180:181]
	s_add_i32 m0, s42, 0xc000
	ds_read_b128 v[184:187], v206
	ds_read_b128 v[188:191], v206 offset:1024
	ds_read_b128 v[192:195], v206 offset:2048
	ds_read_b128 v[210:213], v206 offset:3072
	ds_read_b128 v[214:217], v206 offset:4096
	ds_read_b128 v[218:221], v206 offset:5120
	ds_read_b128 v[222:225], v206 offset:6144
	ds_read_b128 v[226:229], v206 offset:7168
	global_load_lds_dwordx4 v[196:197], off
	v_lshl_add_u64 v[196:197], s[6:7], 0, v[182:183]
	s_add_i32 m0, s42, 0xe000
	s_nop 0
	global_load_lds_dwordx4 v[196:197], off
	s_waitcnt vmcnt(8)
	s_waitcnt lgkmcnt(0)
	s_barrier
	s_setprio 1
	s_waitcnt lgkmcnt(0)
	v_mfma_f32_16x16x32_bf16 v[126:129], v[130:133], v[184:187], v[126:129]
	v_mfma_f32_16x16x32_bf16 v[126:129], v[134:137], v[188:191], v[126:129]
	v_mfma_f32_16x16x32_bf16 v[110:113], v[134:137], v[210:213], v[110:113]
	v_mfma_f32_16x16x32_bf16 v[110:113], v[130:133], v[192:195], v[110:113]
	v_mfma_f32_16x16x32_bf16 v[94:97], v[130:133], v[214:217], v[94:97]
	v_mfma_f32_16x16x32_bf16 v[94:97], v[134:137], v[218:221], v[94:97]
	v_mfma_f32_16x16x32_bf16 v[78:81], v[134:137], v[226:229], v[78:81]
	v_mfma_f32_16x16x32_bf16 v[78:81], v[130:133], v[222:225], v[78:81]
	v_mfma_f32_16x16x32_bf16 v[74:77], v[138:141], v[222:225], v[74:77]
	v_mfma_f32_16x16x32_bf16 v[74:77], v[142:145], v[226:229], v[74:77]
	v_mfma_f32_16x16x32_bf16 v[90:93], v[142:145], v[218:221], v[90:93]
	v_mfma_f32_16x16x32_bf16 v[90:93], v[138:141], v[214:217], v[90:93]
	v_mfma_f32_16x16x32_bf16 v[106:109], v[138:141], v[192:195], v[106:109]
	v_mfma_f32_16x16x32_bf16 v[106:109], v[142:145], v[210:213], v[106:109]
	v_mfma_f32_16x16x32_bf16 v[122:125], v[142:145], v[188:191], v[122:125]
	v_mfma_f32_16x16x32_bf16 v[122:125], v[138:141], v[184:187], v[122:125]
	v_mfma_f32_16x16x32_bf16 v[118:121], v[146:149], v[184:187], v[118:121]
	v_mfma_f32_16x16x32_bf16 v[118:121], v[150:153], v[188:191], v[118:121]
	v_mfma_f32_16x16x32_bf16 v[102:105], v[150:153], v[210:213], v[102:105]
	v_mfma_f32_16x16x32_bf16 v[102:105], v[146:149], v[192:195], v[102:105]
	v_mfma_f32_16x16x32_bf16 v[86:89], v[146:149], v[214:217], v[86:89]
	v_mfma_f32_16x16x32_bf16 v[86:89], v[150:153], v[218:221], v[86:89]
	v_mfma_f32_16x16x32_bf16 v[70:73], v[150:153], v[226:229], v[70:73]
	v_mfma_f32_16x16x32_bf16 v[70:73], v[146:149], v[222:225], v[70:73]
	v_mfma_f32_16x16x32_bf16 v[66:69], v[154:157], v[222:225], v[66:69]
	v_mfma_f32_16x16x32_bf16 v[66:69], v[158:161], v[226:229], v[66:69]
	v_mfma_f32_16x16x32_bf16 v[82:85], v[158:161], v[218:221], v[82:85]
	v_mfma_f32_16x16x32_bf16 v[82:85], v[154:157], v[214:217], v[82:85]
	v_mfma_f32_16x16x32_bf16 v[98:101], v[154:157], v[192:195], v[98:101]
	v_mfma_f32_16x16x32_bf16 v[98:101], v[158:161], v[210:213], v[98:101]
	v_mfma_f32_16x16x32_bf16 v[114:117], v[158:161], v[188:191], v[114:117]
	v_mfma_f32_16x16x32_bf16 v[114:117], v[154:157], v[184:187], v[114:117]
	s_setprio 0
	s_barrier
	s_add_i32 s67, s54, s35
	v_lshl_add_u64 v[196:197], s[8:9], 0, v[168:169]
	s_mov_b32 m0, s67
	ds_read_b128 v[184:187], v206 offset:16384
	ds_read_b128 v[188:191], v206 offset:17408
	ds_read_b128 v[192:195], v206 offset:18432
	ds_read_b128 v[210:213], v206 offset:19456
	ds_read_b128 v[214:217], v206 offset:20480
	ds_read_b128 v[218:221], v206 offset:21504
	ds_read_b128 v[222:225], v206 offset:22528
	ds_read_b128 v[226:229], v206 offset:23552
	global_load_lds_dwordx4 v[196:197], off
	s_add_i32 m0, s67, 0x2000
	s_add_u32 s68, s8, 0x100000
	v_lshl_add_u64 v[230:231], s[8:9], 0, v[170:171]
	s_addc_u32 s69, s9, 0
	s_add_i32 s67, s55, s35
	global_load_lds_dwordx4 v[230:231], off
	v_lshl_add_u64 v[232:233], s[68:69], 0, v[168:169]
	s_mov_b32 m0, s67
	v_lshl_add_u64 v[234:235], s[72:73], 0, v[170:171]
	global_load_lds_dwordx4 v[232:233], off
	v_lshl_add_u64 v[232:233], s[68:69], 0, v[170:171]
	s_add_i32 m0, s67, 0x2000
	s_nop 0
	global_load_lds_dwordx4 v[232:233], off
	v_lshl_add_u64 v[232:233], s[72:73], 0, v[168:169]
	s_mov_b32 m0, s42
	s_nop 0
	global_load_lds_dwordx4 v[232:233], off
	s_mov_b32 m0, s43
	s_nop 0
	global_load_lds_dwordx4 v[234:235], off
	s_waitcnt vmcnt(8)
	s_waitcnt lgkmcnt(0)
	s_barrier
	s_setprio 1
	s_waitcnt lgkmcnt(0)
	v_mfma_f32_16x16x32_bf16 v[62:65], v[130:133], v[184:187], v[62:65]
	v_mfma_f32_16x16x32_bf16 v[62:65], v[134:137], v[188:191], v[62:65]
	v_mfma_f32_16x16x32_bf16 v[46:49], v[134:137], v[210:213], v[46:49]
	v_mfma_f32_16x16x32_bf16 v[46:49], v[130:133], v[192:195], v[46:49]
	v_mfma_f32_16x16x32_bf16 v[30:33], v[130:133], v[214:217], v[30:33]
	v_mfma_f32_16x16x32_bf16 v[30:33], v[134:137], v[218:221], v[30:33]
	v_mfma_f32_16x16x32_bf16 v[14:17], v[134:137], v[226:229], v[14:17]
	v_mfma_f32_16x16x32_bf16 v[14:17], v[130:133], v[222:225], v[14:17]
	v_mfma_f32_16x16x32_bf16 v[10:13], v[138:141], v[222:225], v[10:13]
	v_mfma_f32_16x16x32_bf16 v[10:13], v[142:145], v[226:229], v[10:13]
	v_mfma_f32_16x16x32_bf16 v[26:29], v[142:145], v[218:221], v[26:29]
	v_mfma_f32_16x16x32_bf16 v[26:29], v[138:141], v[214:217], v[26:29]
	v_mfma_f32_16x16x32_bf16 v[42:45], v[138:141], v[192:195], v[42:45]
	v_mfma_f32_16x16x32_bf16 v[42:45], v[142:145], v[210:213], v[42:45]
	v_mfma_f32_16x16x32_bf16 v[58:61], v[142:145], v[188:191], v[58:61]
	v_mfma_f32_16x16x32_bf16 v[58:61], v[138:141], v[184:187], v[58:61]
	v_mfma_f32_16x16x32_bf16 v[54:57], v[146:149], v[184:187], v[54:57]
	v_mfma_f32_16x16x32_bf16 v[54:57], v[150:153], v[188:191], v[54:57]
	v_mfma_f32_16x16x32_bf16 v[38:41], v[150:153], v[210:213], v[38:41]
	v_mfma_f32_16x16x32_bf16 v[38:41], v[146:149], v[192:195], v[38:41]
	v_mfma_f32_16x16x32_bf16 v[22:25], v[146:149], v[214:217], v[22:25]
	v_mfma_f32_16x16x32_bf16 v[22:25], v[150:153], v[218:221], v[22:25]
	v_mfma_f32_16x16x32_bf16 v[6:9], v[150:153], v[226:229], v[6:9]
	v_mfma_f32_16x16x32_bf16 v[6:9], v[146:149], v[222:225], v[6:9]
	v_mfma_f32_16x16x32_bf16 v[2:5], v[154:157], v[222:225], v[2:5]
	v_mfma_f32_16x16x32_bf16 v[2:5], v[158:161], v[226:229], v[2:5]
	v_mfma_f32_16x16x32_bf16 v[18:21], v[158:161], v[218:221], v[18:21]
	v_mfma_f32_16x16x32_bf16 v[18:21], v[154:157], v[214:217], v[18:21]
	v_mfma_f32_16x16x32_bf16 v[34:37], v[154:157], v[192:195], v[34:37]
	v_mfma_f32_16x16x32_bf16 v[34:37], v[158:161], v[210:213], v[34:37]
	v_mfma_f32_16x16x32_bf16 v[50:53], v[158:161], v[188:191], v[50:53]
	v_mfma_f32_16x16x32_bf16 v[50:53], v[154:157], v[184:187], v[50:53]
	s_setprio 0
	s_barrier
	s_add_i32 s67, 0, 0x18000
	s_add_i32 s70, 0, 0x1c000
	v_add_u32_e32 v142, s67, v203
	v_add_u32_e32 v158, s70, v203
	ds_read_b128 v[130:133], v142
	ds_read_b128 v[134:137], v142 offset:1024
	ds_read_b128 v[138:141], v142 offset:2048
	ds_read_b128 v[142:145], v142 offset:3072
	ds_read_b128 v[146:149], v158
	ds_read_b128 v[150:153], v158 offset:1024
	ds_read_b128 v[154:157], v158 offset:2048
	ds_read_b128 v[158:161], v158 offset:3072
	s_add_u32 s68, s72, 0x100000
	s_addc_u32 s69, s73, 0
	s_mov_b32 m0, s44
	v_lshl_add_u64 v[236:237], s[68:69], 0, v[168:169]
	ds_read_b128 v[184:187], v206 offset:32768
	ds_read_b128 v[188:191], v206 offset:33792
	ds_read_b128 v[192:195], v206 offset:34816
	ds_read_b128 v[210:213], v206 offset:35840
	ds_read_b128 v[214:217], v206 offset:36864
	ds_read_b128 v[218:221], v206 offset:37888
	ds_read_b128 v[222:225], v206 offset:38912
	ds_read_b128 v[226:229], v206 offset:39936
	global_load_lds_dwordx4 v[236:237], off
	v_lshl_add_u64 v[236:237], s[68:69], 0, v[170:171]
	s_mov_b32 m0, s45
	s_nop 0
	global_load_lds_dwordx4 v[236:237], off
	s_waitcnt vmcnt(8)
	s_waitcnt lgkmcnt(0)
	s_barrier
	s_setprio 1
	s_waitcnt lgkmcnt(0)
	v_mfma_f32_16x16x32_bf16 v[126:129], v[130:133], v[184:187], v[126:129]
	v_mfma_f32_16x16x32_bf16 v[126:129], v[134:137], v[188:191], v[126:129]
	v_mfma_f32_16x16x32_bf16 v[110:113], v[134:137], v[210:213], v[110:113]
	v_mfma_f32_16x16x32_bf16 v[110:113], v[130:133], v[192:195], v[110:113]
	v_mfma_f32_16x16x32_bf16 v[94:97], v[130:133], v[214:217], v[94:97]
	v_mfma_f32_16x16x32_bf16 v[94:97], v[134:137], v[218:221], v[94:97]
	v_mfma_f32_16x16x32_bf16 v[78:81], v[134:137], v[226:229], v[78:81]
	v_mfma_f32_16x16x32_bf16 v[78:81], v[130:133], v[222:225], v[78:81]
	v_mfma_f32_16x16x32_bf16 v[74:77], v[138:141], v[222:225], v[74:77]
	v_mfma_f32_16x16x32_bf16 v[74:77], v[142:145], v[226:229], v[74:77]
	v_mfma_f32_16x16x32_bf16 v[90:93], v[142:145], v[218:221], v[90:93]
	v_mfma_f32_16x16x32_bf16 v[90:93], v[138:141], v[214:217], v[90:93]
	v_mfma_f32_16x16x32_bf16 v[106:109], v[138:141], v[192:195], v[106:109]
	v_mfma_f32_16x16x32_bf16 v[106:109], v[142:145], v[210:213], v[106:109]
	v_mfma_f32_16x16x32_bf16 v[122:125], v[142:145], v[188:191], v[122:125]
	v_mfma_f32_16x16x32_bf16 v[122:125], v[138:141], v[184:187], v[122:125]
	v_mfma_f32_16x16x32_bf16 v[118:121], v[146:149], v[184:187], v[118:121]
	v_mfma_f32_16x16x32_bf16 v[118:121], v[150:153], v[188:191], v[118:121]
	v_mfma_f32_16x16x32_bf16 v[102:105], v[150:153], v[210:213], v[102:105]
	v_mfma_f32_16x16x32_bf16 v[102:105], v[146:149], v[192:195], v[102:105]
	v_mfma_f32_16x16x32_bf16 v[86:89], v[146:149], v[214:217], v[86:89]
	v_mfma_f32_16x16x32_bf16 v[86:89], v[150:153], v[218:221], v[86:89]
	v_mfma_f32_16x16x32_bf16 v[70:73], v[150:153], v[226:229], v[70:73]
	v_mfma_f32_16x16x32_bf16 v[70:73], v[146:149], v[222:225], v[70:73]
	v_mfma_f32_16x16x32_bf16 v[66:69], v[154:157], v[222:225], v[66:69]
	v_mfma_f32_16x16x32_bf16 v[66:69], v[158:161], v[226:229], v[66:69]
	v_mfma_f32_16x16x32_bf16 v[82:85], v[158:161], v[218:221], v[82:85]
	v_mfma_f32_16x16x32_bf16 v[82:85], v[154:157], v[214:217], v[82:85]
	v_mfma_f32_16x16x32_bf16 v[98:101], v[154:157], v[192:195], v[98:101]
	v_mfma_f32_16x16x32_bf16 v[98:101], v[158:161], v[210:213], v[98:101]
	v_mfma_f32_16x16x32_bf16 v[114:117], v[158:161], v[188:191], v[114:117]
	v_mfma_f32_16x16x32_bf16 v[114:117], v[154:157], v[184:187], v[114:117]
	s_setprio 0
	s_barrier
	s_add_i32 s67, s67, s35
	v_lshl_add_u64 v[196:197], v[196:197], 0, s[22:23]
	s_mov_b32 m0, s67
	ds_read_b128 v[184:187], v206 offset:49152
	ds_read_b128 v[188:191], v206 offset:50176
	ds_read_b128 v[192:195], v206 offset:51200
	ds_read_b128 v[210:213], v206 offset:52224
	ds_read_b128 v[214:217], v206 offset:53248
	ds_read_b128 v[218:221], v206 offset:54272
	ds_read_b128 v[222:225], v206 offset:55296
	ds_read_b128 v[226:229], v206 offset:56320
	global_load_lds_dwordx4 v[196:197], off
	s_add_i32 m0, s67, 0x2000
	s_add_u32 s8, s8, 0x100080
	v_lshl_add_u64 v[196:197], v[230:231], 0, s[22:23]
	s_addc_u32 s9, s9, 0
	s_add_i32 s67, s70, s35
	global_load_lds_dwordx4 v[196:197], off
	v_lshl_add_u64 v[196:197], s[8:9], 0, v[168:169]
	s_mov_b32 m0, s67
	s_nop 0
	global_load_lds_dwordx4 v[196:197], off
	v_lshl_add_u64 v[196:197], s[8:9], 0, v[170:171]
	s_add_i32 m0, s67, 0x2000
	s_nop 0
	global_load_lds_dwordx4 v[196:197], off
	v_lshl_add_u64 v[196:197], v[232:233], 0, s[22:23]
	s_mov_b32 m0, s48
	s_nop 0
	global_load_lds_dwordx4 v[196:197], off
	v_lshl_add_u64 v[196:197], v[234:235], 0, s[22:23]
	s_mov_b32 m0, s49
	s_nop 0
	global_load_lds_dwordx4 v[196:197], off
	s_waitcnt vmcnt(8)
	s_waitcnt lgkmcnt(0)
	s_barrier
	s_setprio 1
	s_waitcnt lgkmcnt(0)
	v_mfma_f32_16x16x32_bf16 v[62:65], v[130:133], v[184:187], v[62:65]
	v_mfma_f32_16x16x32_bf16 v[62:65], v[134:137], v[188:191], v[62:65]
	v_mfma_f32_16x16x32_bf16 v[46:49], v[134:137], v[210:213], v[46:49]
	v_mfma_f32_16x16x32_bf16 v[46:49], v[130:133], v[192:195], v[46:49]
	v_mfma_f32_16x16x32_bf16 v[30:33], v[130:133], v[214:217], v[30:33]
	v_mfma_f32_16x16x32_bf16 v[30:33], v[134:137], v[218:221], v[30:33]
	v_mfma_f32_16x16x32_bf16 v[14:17], v[134:137], v[226:229], v[14:17]
	v_mfma_f32_16x16x32_bf16 v[14:17], v[130:133], v[222:225], v[14:17]
	v_mfma_f32_16x16x32_bf16 v[10:13], v[138:141], v[222:225], v[10:13]
	v_mfma_f32_16x16x32_bf16 v[10:13], v[142:145], v[226:229], v[10:13]
	v_mfma_f32_16x16x32_bf16 v[26:29], v[142:145], v[218:221], v[26:29]
	v_mfma_f32_16x16x32_bf16 v[26:29], v[138:141], v[214:217], v[26:29]
	v_mfma_f32_16x16x32_bf16 v[42:45], v[138:141], v[192:195], v[42:45]
	v_mfma_f32_16x16x32_bf16 v[42:45], v[142:145], v[210:213], v[42:45]
	v_mfma_f32_16x16x32_bf16 v[58:61], v[142:145], v[188:191], v[58:61]
	v_mfma_f32_16x16x32_bf16 v[58:61], v[138:141], v[184:187], v[58:61]
	v_mfma_f32_16x16x32_bf16 v[54:57], v[146:149], v[184:187], v[54:57]
	v_mfma_f32_16x16x32_bf16 v[54:57], v[150:153], v[188:191], v[54:57]
	v_mfma_f32_16x16x32_bf16 v[38:41], v[150:153], v[210:213], v[38:41]
	v_mfma_f32_16x16x32_bf16 v[38:41], v[146:149], v[192:195], v[38:41]
	v_mfma_f32_16x16x32_bf16 v[22:25], v[146:149], v[214:217], v[22:25]
	v_mfma_f32_16x16x32_bf16 v[22:25], v[150:153], v[218:221], v[22:25]
	v_mfma_f32_16x16x32_bf16 v[6:9], v[150:153], v[226:229], v[6:9]
	v_mfma_f32_16x16x32_bf16 v[6:9], v[146:149], v[222:225], v[6:9]
	v_mfma_f32_16x16x32_bf16 v[2:5], v[154:157], v[222:225], v[2:5]
	v_mfma_f32_16x16x32_bf16 v[2:5], v[158:161], v[226:229], v[2:5]
	v_mfma_f32_16x16x32_bf16 v[18:21], v[158:161], v[218:221], v[18:21]
	v_mfma_f32_16x16x32_bf16 v[18:21], v[154:157], v[214:217], v[18:21]
	v_mfma_f32_16x16x32_bf16 v[34:37], v[154:157], v[192:195], v[34:37]
	v_mfma_f32_16x16x32_bf16 v[34:37], v[158:161], v[210:213], v[34:37]
	v_mfma_f32_16x16x32_bf16 v[50:53], v[158:161], v[188:191], v[50:53]
	v_mfma_f32_16x16x32_bf16 v[50:53], v[154:157], v[184:187], v[50:53]
	s_setprio 0
	s_barrier
	s_add_i32 s66, s66, 2
	s_add_u32 s6, s6, 0x100
	s_addc_u32 s7, s7, 0
	s_add_u32 s56, s56, 0x100
	s_addc_u32 s57, s57, 0
	s_cmp_gt_u32 s66, 61
	s_cbranch_scc0 .LBB0_1565
	s_and_b64 vcc, exec, s[24:25]
	s_cbranch_vccz .LBB0_1568
	s_barrier

.LBB0_2230:
	ds_read_b128 v[142:145], v154
	ds_read_b128 v[158:161], v154 offset:1024
	ds_read_b128 v[168:171], v154 offset:2048
	ds_read_b128 v[176:179], v154 offset:3072
	ds_read_b128 v[180:183], v155
	ds_read_b128 v[184:187], v155 offset:1024
	ds_read_b128 v[188:191], v155 offset:2048
	ds_read_b128 v[192:195], v155 offset:3072
	s_add_u32 s24, s22, 0xfff00080
	s_addc_u32 s25, s23, -1
	s_cmp_eq_u32 s48, 60
	s_cselect_b32 s27, s19, s25
	s_cselect_b32 s26, s44, s24
	s_cselect_b32 s25, s7, s47
	s_cselect_b32 s24, s45, s46
	s_mov_b32 m0, s40
	v_lshl_add_u64 v[146:147], s[22:23], 0, v[138:139]
	ds_read_b128 v[204:207], v156
	ds_read_b128 v[208:211], v156 offset:1024
	ds_read_b128 v[212:215], v156 offset:2048
	ds_read_b128 v[216:219], v156 offset:3072
	ds_read_b128 v[220:223], v156 offset:4096
	ds_read_b128 v[224:227], v156 offset:5120
	ds_read_b128 v[228:231], v156 offset:6144
	ds_read_b128 v[232:235], v156 offset:7168
	global_load_lds_dwordx4 v[146:147], off
	v_lshl_add_u64 v[146:147], s[22:23], 0, v[140:141]
	s_mov_b32 m0, s41
	s_nop 0
	global_load_lds_dwordx4 v[146:147], off
	s_waitcnt vmcnt(8)
	s_waitcnt lgkmcnt(0)
	s_barrier
	s_setprio 1
	s_waitcnt lgkmcnt(0)
	v_mfma_f32_16x16x32_bf16 v[126:129], v[142:145], v[204:207], v[126:129]
	v_mfma_f32_16x16x32_bf16 v[126:129], v[158:161], v[208:211], v[126:129]
	v_mfma_f32_16x16x32_bf16 v[110:113], v[158:161], v[216:219], v[110:113]
	v_mfma_f32_16x16x32_bf16 v[110:113], v[142:145], v[212:215], v[110:113]
	v_mfma_f32_16x16x32_bf16 v[94:97], v[142:145], v[220:223], v[94:97]
	v_mfma_f32_16x16x32_bf16 v[94:97], v[158:161], v[224:227], v[94:97]
	v_mfma_f32_16x16x32_bf16 v[78:81], v[158:161], v[232:235], v[78:81]
	v_mfma_f32_16x16x32_bf16 v[78:81], v[142:145], v[228:231], v[78:81]
	v_mfma_f32_16x16x32_bf16 v[74:77], v[168:171], v[228:231], v[74:77]
	v_mfma_f32_16x16x32_bf16 v[74:77], v[176:179], v[232:235], v[74:77]
	v_mfma_f32_16x16x32_bf16 v[90:93], v[176:179], v[224:227], v[90:93]
	v_mfma_f32_16x16x32_bf16 v[90:93], v[168:171], v[220:223], v[90:93]
	v_mfma_f32_16x16x32_bf16 v[106:109], v[168:171], v[212:215], v[106:109]
	v_mfma_f32_16x16x32_bf16 v[106:109], v[176:179], v[216:219], v[106:109]
	v_mfma_f32_16x16x32_bf16 v[122:125], v[176:179], v[208:211], v[122:125]
	v_mfma_f32_16x16x32_bf16 v[122:125], v[168:171], v[204:207], v[122:125]
	v_mfma_f32_16x16x32_bf16 v[118:121], v[180:183], v[204:207], v[118:121]
	v_mfma_f32_16x16x32_bf16 v[118:121], v[184:187], v[208:211], v[118:121]
	v_mfma_f32_16x16x32_bf16 v[102:105], v[184:187], v[216:219], v[102:105]
	v_mfma_f32_16x16x32_bf16 v[102:105], v[180:183], v[212:215], v[102:105]
	v_mfma_f32_16x16x32_bf16 v[86:89], v[180:183], v[220:223], v[86:89]
	v_mfma_f32_16x16x32_bf16 v[86:89], v[184:187], v[224:227], v[86:89]
	v_mfma_f32_16x16x32_bf16 v[70:73], v[184:187], v[232:235], v[70:73]
	v_mfma_f32_16x16x32_bf16 v[70:73], v[180:183], v[228:231], v[70:73]
	v_mfma_f32_16x16x32_bf16 v[66:69], v[188:191], v[228:231], v[66:69]
	v_mfma_f32_16x16x32_bf16 v[66:69], v[192:195], v[232:235], v[66:69]
	v_mfma_f32_16x16x32_bf16 v[82:85], v[192:195], v[224:227], v[82:85]
	v_mfma_f32_16x16x32_bf16 v[82:85], v[188:191], v[220:223], v[82:85]
	v_mfma_f32_16x16x32_bf16 v[98:101], v[188:191], v[212:215], v[98:101]
	v_mfma_f32_16x16x32_bf16 v[98:101], v[192:195], v[216:219], v[98:101]
	v_mfma_f32_16x16x32_bf16 v[114:117], v[192:195], v[208:211], v[114:117]
	v_mfma_f32_16x16x32_bf16 v[114:117], v[188:191], v[204:207], v[114:117]
	s_setprio 0
	s_barrier
	s_add_i32 s49, s38, s28
	v_lshl_add_u64 v[146:147], s[24:25], 0, v[132:133]
	s_mov_b32 m0, s49
	ds_read_b128 v[204:207], v156 offset:16384
	ds_read_b128 v[208:211], v156 offset:17408
	ds_read_b128 v[212:215], v156 offset:18432
	ds_read_b128 v[216:219], v156 offset:19456
	ds_read_b128 v[220:223], v156 offset:20480
	ds_read_b128 v[224:227], v156 offset:21504
	ds_read_b128 v[228:231], v156 offset:22528
	ds_read_b128 v[232:235], v156 offset:23552
	global_load_lds_dwordx4 v[146:147], off
	s_add_i32 m0, s49, 0x2000
	s_add_u32 s50, s24, 0x100000
	v_lshl_add_u64 v[172:173], s[24:25], 0, v[136:137]
	s_addc_u32 s51, s25, 0
	s_add_i32 s49, s39, s28
	global_load_lds_dwordx4 v[172:173], off
	v_lshl_add_u64 v[196:197], s[50:51], 0, v[132:133]
	s_mov_b32 m0, s49
	v_lshl_add_u64 v[236:237], s[26:27], 0, v[134:135]
	global_load_lds_dwordx4 v[196:197], off
	v_lshl_add_u64 v[196:197], s[50:51], 0, v[136:137]
	s_add_i32 m0, s49, 0x2000
	s_nop 0
	global_load_lds_dwordx4 v[196:197], off
	v_lshl_add_u64 v[196:197], s[26:27], 0, v[130:131]
	s_mov_b32 m0, s30
	s_nop 0
	global_load_lds_dwordx4 v[196:197], off
	s_mov_b32 m0, s31
	s_nop 0
	global_load_lds_dwordx4 v[236:237], off
	s_waitcnt vmcnt(8)
	s_waitcnt lgkmcnt(0)
	s_barrier
	s_setprio 1
	s_waitcnt lgkmcnt(0)
	v_mfma_f32_16x16x32_bf16 v[62:65], v[142:145], v[204:207], v[62:65]
	v_mfma_f32_16x16x32_bf16 v[62:65], v[158:161], v[208:211], v[62:65]
	v_mfma_f32_16x16x32_bf16 v[46:49], v[158:161], v[216:219], v[46:49]
	v_mfma_f32_16x16x32_bf16 v[46:49], v[142:145], v[212:215], v[46:49]
	v_mfma_f32_16x16x32_bf16 v[30:33], v[142:145], v[220:223], v[30:33]
	v_mfma_f32_16x16x32_bf16 v[30:33], v[158:161], v[224:227], v[30:33]
	v_mfma_f32_16x16x32_bf16 v[14:17], v[158:161], v[232:235], v[14:17]
	v_mfma_f32_16x16x32_bf16 v[14:17], v[142:145], v[228:231], v[14:17]
	v_mfma_f32_16x16x32_bf16 v[10:13], v[168:171], v[228:231], v[10:13]
	v_mfma_f32_16x16x32_bf16 v[10:13], v[176:179], v[232:235], v[10:13]
	v_mfma_f32_16x16x32_bf16 v[26:29], v[176:179], v[224:227], v[26:29]
	v_mfma_f32_16x16x32_bf16 v[26:29], v[168:171], v[220:223], v[26:29]
	v_mfma_f32_16x16x32_bf16 v[42:45], v[168:171], v[212:215], v[42:45]
	v_mfma_f32_16x16x32_bf16 v[42:45], v[176:179], v[216:219], v[42:45]
	v_mfma_f32_16x16x32_bf16 v[58:61], v[176:179], v[208:211], v[58:61]
	v_mfma_f32_16x16x32_bf16 v[58:61], v[168:171], v[204:207], v[58:61]
	v_mfma_f32_16x16x32_bf16 v[54:57], v[180:183], v[204:207], v[54:57]
	v_mfma_f32_16x16x32_bf16 v[54:57], v[184:187], v[208:211], v[54:57]
	v_mfma_f32_16x16x32_bf16 v[38:41], v[184:187], v[216:219], v[38:41]
	v_mfma_f32_16x16x32_bf16 v[38:41], v[180:183], v[212:215], v[38:41]
	v_mfma_f32_16x16x32_bf16 v[22:25], v[180:183], v[220:223], v[22:25]
	v_mfma_f32_16x16x32_bf16 v[22:25], v[184:187], v[224:227], v[22:25]
	v_mfma_f32_16x16x32_bf16 v[6:9], v[184:187], v[232:235], v[6:9]
	v_mfma_f32_16x16x32_bf16 v[6:9], v[180:183], v[228:231], v[6:9]
	v_mfma_f32_16x16x32_bf16 v[2:5], v[188:191], v[228:231], v[2:5]
	v_mfma_f32_16x16x32_bf16 v[2:5], v[192:195], v[232:235], v[2:5]
	v_mfma_f32_16x16x32_bf16 v[18:21], v[192:195], v[224:227], v[18:21]
	v_mfma_f32_16x16x32_bf16 v[18:21], v[188:191], v[220:223], v[18:21]
	v_mfma_f32_16x16x32_bf16 v[34:37], v[188:191], v[212:215], v[34:37]
	v_mfma_f32_16x16x32_bf16 v[34:37], v[192:195], v[216:219], v[34:37]
	v_mfma_f32_16x16x32_bf16 v[50:53], v[192:195], v[208:211], v[50:53]
	v_mfma_f32_16x16x32_bf16 v[50:53], v[188:191], v[204:207], v[50:53]
	s_setprio 0
	s_barrier
	s_add_i32 s49, 0, 0x18000
	v_add_u32_e32 v157, s49, v152
	s_add_i32 s50, 0, 0x1c000
	ds_read_b128 v[142:145], v157
	ds_read_b128 v[158:161], v157 offset:1024
	ds_read_b128 v[168:171], v157 offset:2048
	ds_read_b128 v[176:179], v157 offset:3072
	v_add_u32_e32 v157, s50, v152
	ds_read_b128 v[180:183], v157
	ds_read_b128 v[184:187], v157 offset:1024
	ds_read_b128 v[188:191], v157 offset:2048
	ds_read_b128 v[192:195], v157 offset:3072
	s_add_u32 s26, s26, 0x100000
	s_addc_u32 s27, s27, 0
	s_mov_b32 m0, s33
	v_lshl_add_u64 v[238:239], s[26:27], 0, v[130:131]
	ds_read_b128 v[204:207], v156 offset:32768
	ds_read_b128 v[208:211], v156 offset:33792
	ds_read_b128 v[212:215], v156 offset:34816
	ds_read_b128 v[216:219], v156 offset:35840
	ds_read_b128 v[220:223], v156 offset:36864
	ds_read_b128 v[224:227], v156 offset:37888
	ds_read_b128 v[228:231], v156 offset:38912
	ds_read_b128 v[232:235], v156 offset:39936
	global_load_lds_dwordx4 v[238:239], off
	v_lshl_add_u64 v[238:239], s[26:27], 0, v[134:135]
	s_mov_b32 m0, s34
	s_nop 0
	global_load_lds_dwordx4 v[238:239], off
	s_waitcnt vmcnt(8)
	s_waitcnt lgkmcnt(0)
	s_barrier
	s_setprio 1
	s_waitcnt lgkmcnt(0)
	v_mfma_f32_16x16x32_bf16 v[126:129], v[142:145], v[204:207], v[126:129]
	v_mfma_f32_16x16x32_bf16 v[126:129], v[158:161], v[208:211], v[126:129]
	v_mfma_f32_16x16x32_bf16 v[110:113], v[158:161], v[216:219], v[110:113]
	v_mfma_f32_16x16x32_bf16 v[110:113], v[142:145], v[212:215], v[110:113]
	v_mfma_f32_16x16x32_bf16 v[94:97], v[142:145], v[220:223], v[94:97]
	v_mfma_f32_16x16x32_bf16 v[94:97], v[158:161], v[224:227], v[94:97]
	v_mfma_f32_16x16x32_bf16 v[78:81], v[158:161], v[232:235], v[78:81]
	v_mfma_f32_16x16x32_bf16 v[78:81], v[142:145], v[228:231], v[78:81]
	v_mfma_f32_16x16x32_bf16 v[74:77], v[168:171], v[228:231], v[74:77]
	v_mfma_f32_16x16x32_bf16 v[74:77], v[176:179], v[232:235], v[74:77]
	v_mfma_f32_16x16x32_bf16 v[90:93], v[176:179], v[224:227], v[90:93]
	v_mfma_f32_16x16x32_bf16 v[90:93], v[168:171], v[220:223], v[90:93]
	v_mfma_f32_16x16x32_bf16 v[106:109], v[168:171], v[212:215], v[106:109]
	v_mfma_f32_16x16x32_bf16 v[106:109], v[176:179], v[216:219], v[106:109]
	v_mfma_f32_16x16x32_bf16 v[122:125], v[176:179], v[208:211], v[122:125]
	v_mfma_f32_16x16x32_bf16 v[122:125], v[168:171], v[204:207], v[122:125]
	v_mfma_f32_16x16x32_bf16 v[118:121], v[180:183], v[204:207], v[118:121]
	v_mfma_f32_16x16x32_bf16 v[118:121], v[184:187], v[208:211], v[118:121]
	v_mfma_f32_16x16x32_bf16 v[102:105], v[184:187], v[216:219], v[102:105]
	v_mfma_f32_16x16x32_bf16 v[102:105], v[180:183], v[212:215], v[102:105]
	v_mfma_f32_16x16x32_bf16 v[86:89], v[180:183], v[220:223], v[86:89]
	v_mfma_f32_16x16x32_bf16 v[86:89], v[184:187], v[224:227], v[86:89]
	v_mfma_f32_16x16x32_bf16 v[70:73], v[184:187], v[232:235], v[70:73]
	v_mfma_f32_16x16x32_bf16 v[70:73], v[180:183], v[228:231], v[70:73]
	v_mfma_f32_16x16x32_bf16 v[66:69], v[188:191], v[228:231], v[66:69]
	v_mfma_f32_16x16x32_bf16 v[66:69], v[192:195], v[232:235], v[66:69]
	v_mfma_f32_16x16x32_bf16 v[82:85], v[192:195], v[224:227], v[82:85]
	v_mfma_f32_16x16x32_bf16 v[82:85], v[188:191], v[220:223], v[82:85]
	v_mfma_f32_16x16x32_bf16 v[98:101], v[188:191], v[212:215], v[98:101]
	v_mfma_f32_16x16x32_bf16 v[98:101], v[192:195], v[216:219], v[98:101]
	v_mfma_f32_16x16x32_bf16 v[114:117], v[192:195], v[208:211], v[114:117]
	v_mfma_f32_16x16x32_bf16 v[114:117], v[188:191], v[204:207], v[114:117]
	s_setprio 0
	s_barrier
	s_add_i32 s26, s49, s28
	v_lshl_add_u64 v[146:147], v[146:147], 0, s[14:15]
	s_mov_b32 m0, s26
	ds_read_b128 v[204:207], v156 offset:49152
	ds_read_b128 v[208:211], v156 offset:50176
	ds_read_b128 v[212:215], v156 offset:51200
	ds_read_b128 v[216:219], v156 offset:52224
	ds_read_b128 v[220:223], v156 offset:53248
	ds_read_b128 v[224:227], v156 offset:54272
	ds_read_b128 v[228:231], v156 offset:55296
	ds_read_b128 v[232:235], v156 offset:56320
	global_load_lds_dwordx4 v[146:147], off
	s_add_i32 m0, s26, 0x2000
	s_add_u32 s24, s24, 0x100080
	v_lshl_add_u64 v[146:147], v[172:173], 0, s[14:15]
	s_addc_u32 s25, s25, 0
	s_add_i32 s26, s50, s28
	global_load_lds_dwordx4 v[146:147], off
	v_lshl_add_u64 v[146:147], s[24:25], 0, v[132:133]
	s_mov_b32 m0, s26
	s_nop 0
	global_load_lds_dwordx4 v[146:147], off
	v_lshl_add_u64 v[146:147], s[24:25], 0, v[136:137]
	s_add_i32 m0, s26, 0x2000
	s_nop 0
	global_load_lds_dwordx4 v[146:147], off
	v_lshl_add_u64 v[146:147], v[196:197], 0, s[14:15]
	s_mov_b32 m0, s36
	s_nop 0
	global_load_lds_dwordx4 v[146:147], off
	v_lshl_add_u64 v[146:147], v[236:237], 0, s[14:15]
	s_mov_b32 m0, s37
	s_nop 0
	global_load_lds_dwordx4 v[146:147], off
	s_waitcnt vmcnt(8)
	s_waitcnt lgkmcnt(0)
	s_barrier
	s_setprio 1
	s_waitcnt lgkmcnt(0)
	v_mfma_f32_16x16x32_bf16 v[62:65], v[142:145], v[204:207], v[62:65]
	v_mfma_f32_16x16x32_bf16 v[62:65], v[158:161], v[208:211], v[62:65]
	v_mfma_f32_16x16x32_bf16 v[46:49], v[158:161], v[216:219], v[46:49]
	v_mfma_f32_16x16x32_bf16 v[46:49], v[142:145], v[212:215], v[46:49]
	v_mfma_f32_16x16x32_bf16 v[30:33], v[142:145], v[220:223], v[30:33]
	v_mfma_f32_16x16x32_bf16 v[30:33], v[158:161], v[224:227], v[30:33]
	v_mfma_f32_16x16x32_bf16 v[14:17], v[158:161], v[232:235], v[14:17]
	v_mfma_f32_16x16x32_bf16 v[14:17], v[142:145], v[228:231], v[14:17]
	v_mfma_f32_16x16x32_bf16 v[10:13], v[168:171], v[228:231], v[10:13]
	v_mfma_f32_16x16x32_bf16 v[10:13], v[176:179], v[232:235], v[10:13]
	v_mfma_f32_16x16x32_bf16 v[26:29], v[176:179], v[224:227], v[26:29]
	v_mfma_f32_16x16x32_bf16 v[26:29], v[168:171], v[220:223], v[26:29]
	v_mfma_f32_16x16x32_bf16 v[42:45], v[168:171], v[212:215], v[42:45]
	v_mfma_f32_16x16x32_bf16 v[42:45], v[176:179], v[216:219], v[42:45]
	v_mfma_f32_16x16x32_bf16 v[58:61], v[176:179], v[208:211], v[58:61]
	v_mfma_f32_16x16x32_bf16 v[58:61], v[168:171], v[204:207], v[58:61]
	v_mfma_f32_16x16x32_bf16 v[54:57], v[180:183], v[204:207], v[54:57]
	v_mfma_f32_16x16x32_bf16 v[54:57], v[184:187], v[208:211], v[54:57]
	v_mfma_f32_16x16x32_bf16 v[38:41], v[184:187], v[216:219], v[38:41]
	v_mfma_f32_16x16x32_bf16 v[38:41], v[180:183], v[212:215], v[38:41]
	v_mfma_f32_16x16x32_bf16 v[22:25], v[180:183], v[220:223], v[22:25]
	v_mfma_f32_16x16x32_bf16 v[22:25], v[184:187], v[224:227], v[22:25]
	v_mfma_f32_16x16x32_bf16 v[6:9], v[184:187], v[232:235], v[6:9]
	v_mfma_f32_16x16x32_bf16 v[6:9], v[180:183], v[228:231], v[6:9]
	v_mfma_f32_16x16x32_bf16 v[2:5], v[188:191], v[228:231], v[2:5]
	v_mfma_f32_16x16x32_bf16 v[2:5], v[192:195], v[232:235], v[2:5]
	v_mfma_f32_16x16x32_bf16 v[18:21], v[192:195], v[224:227], v[18:21]
	v_mfma_f32_16x16x32_bf16 v[18:21], v[188:191], v[220:223], v[18:21]
	v_mfma_f32_16x16x32_bf16 v[34:37], v[188:191], v[212:215], v[34:37]
	v_mfma_f32_16x16x32_bf16 v[34:37], v[192:195], v[216:219], v[34:37]
	v_mfma_f32_16x16x32_bf16 v[50:53], v[192:195], v[208:211], v[50:53]
	v_mfma_f32_16x16x32_bf16 v[50:53], v[188:191], v[204:207], v[50:53]
	s_setprio 0
	s_barrier
	s_add_i32 s48, s48, 2
	s_add_u32 s22, s22, 0x100
	s_addc_u32 s23, s23, 0
	s_add_u32 s46, s46, 0x100
	s_addc_u32 s47, s47, 0
	s_cmp_gt_u32 s48, 61
	s_cbranch_scc0 .LBB0_2230
	s_and_b64 vcc, exec, s[16:17]
	s_cbranch_vccz .LBB0_2233
	s_barrier

.LBB0_2240:
	s_add_i32 s20, s24, 0x100
	s_and_b64 s[18:19], s[18:19], exec
	s_cselect_b32 s19, 0, s20
	s_cselect_b32 s18, 0, 0
	s_add_u32 s20, s8, s19
	ds_read_b128 v[144:147], v139
	ds_read_b128 v[150:153], v139 offset:1024
	ds_read_b128 v[154:157], v139 offset:2048
	ds_read_b128 v[158:161], v139 offset:3072
	ds_read_b128 v[168:171], v140
	ds_read_b128 v[176:179], v140 offset:1024
	ds_read_b128 v[180:183], v140 offset:2048
	ds_read_b128 v[184:187], v140 offset:3072
	s_addc_u32 s21, s9, s18
	s_add_u32 s22, s10, s19
	s_addc_u32 s23, s11, s18
	s_add_u32 s28, s12, s24
	s_addc_u32 s29, s13, 0
	s_add_u32 s24, s22, 0x100000
	s_addc_u32 s25, s23, 0
	s_add_u32 s18, s20, 0x100000
	s_addc_u32 s19, s21, 0
	s_add_u32 s26, s22, 0x100080
	s_addc_u32 s27, s23, 0
	v_lshl_add_u64 v[172:173], s[28:29], 0, v[130:131]
	s_mov_b32 m0, s38
	v_lshl_add_u64 v[172:173], v[172:173], 0, s[14:15]
	ds_read_b128 v[188:191], v141
	ds_read_b128 v[192:195], v141 offset:1024
	ds_read_b128 v[204:207], v141 offset:2048
	ds_read_b128 v[208:211], v141 offset:3072
	ds_read_b128 v[212:215], v141 offset:4096
	ds_read_b128 v[216:219], v141 offset:5120
	ds_read_b128 v[220:223], v141 offset:6144
	ds_read_b128 v[224:227], v141 offset:7168
	global_load_lds_dwordx4 v[172:173], off
	v_lshl_add_u64 v[172:173], s[28:29], 0, v[134:135]
	v_lshl_add_u64 v[172:173], v[172:173], 0, s[14:15]
	s_mov_b32 m0, s39
	s_nop 0
	global_load_lds_dwordx4 v[172:173], off
	s_waitcnt vmcnt(8)
	s_waitcnt lgkmcnt(0)
	s_barrier
	s_setprio 1
	s_waitcnt lgkmcnt(0)
	v_mfma_f32_16x16x32_bf16 v[126:129], v[144:147], v[188:191], v[126:129]
	v_mfma_f32_16x16x32_bf16 v[126:129], v[150:153], v[192:195], v[126:129]
	v_mfma_f32_16x16x32_bf16 v[118:121], v[150:153], v[208:211], v[118:121]
	v_mfma_f32_16x16x32_bf16 v[118:121], v[144:147], v[204:207], v[118:121]
	v_mfma_f32_16x16x32_bf16 v[102:105], v[144:147], v[212:215], v[102:105]
	v_mfma_f32_16x16x32_bf16 v[102:105], v[150:153], v[216:219], v[102:105]
	v_mfma_f32_16x16x32_bf16 v[86:89], v[150:153], v[224:227], v[86:89]
	v_mfma_f32_16x16x32_bf16 v[86:89], v[144:147], v[220:223], v[86:89]
	v_mfma_f32_16x16x32_bf16 v[82:85], v[154:157], v[220:223], v[82:85]
	v_mfma_f32_16x16x32_bf16 v[82:85], v[158:161], v[224:227], v[82:85]
	v_mfma_f32_16x16x32_bf16 v[98:101], v[158:161], v[216:219], v[98:101]
	v_mfma_f32_16x16x32_bf16 v[98:101], v[154:157], v[212:215], v[98:101]
	v_mfma_f32_16x16x32_bf16 v[114:117], v[154:157], v[204:207], v[114:117]
	v_mfma_f32_16x16x32_bf16 v[114:117], v[158:161], v[208:211], v[114:117]
	v_mfma_f32_16x16x32_bf16 v[122:125], v[158:161], v[192:195], v[122:125]
	v_mfma_f32_16x16x32_bf16 v[122:125], v[154:157], v[188:191], v[122:125]
	v_mfma_f32_16x16x32_bf16 v[110:113], v[168:171], v[188:191], v[110:113]
	v_mfma_f32_16x16x32_bf16 v[110:113], v[176:179], v[192:195], v[110:113]
	v_mfma_f32_16x16x32_bf16 v[94:97], v[176:179], v[208:211], v[94:97]
	v_mfma_f32_16x16x32_bf16 v[94:97], v[168:171], v[204:207], v[94:97]
	v_mfma_f32_16x16x32_bf16 v[78:81], v[168:171], v[212:215], v[78:81]
	v_mfma_f32_16x16x32_bf16 v[78:81], v[176:179], v[216:219], v[78:81]
	v_mfma_f32_16x16x32_bf16 v[70:73], v[176:179], v[224:227], v[70:73]
	v_mfma_f32_16x16x32_bf16 v[70:73], v[168:171], v[220:223], v[70:73]
	v_mfma_f32_16x16x32_bf16 v[66:69], v[180:183], v[220:223], v[66:69]
	v_mfma_f32_16x16x32_bf16 v[66:69], v[184:187], v[224:227], v[66:69]
	v_mfma_f32_16x16x32_bf16 v[74:77], v[184:187], v[216:219], v[74:77]
	v_mfma_f32_16x16x32_bf16 v[74:77], v[180:183], v[212:215], v[74:77]
	v_mfma_f32_16x16x32_bf16 v[90:93], v[180:183], v[204:207], v[90:93]
	v_mfma_f32_16x16x32_bf16 v[90:93], v[184:187], v[208:211], v[90:93]
	v_mfma_f32_16x16x32_bf16 v[106:109], v[184:187], v[192:195], v[106:109]
	v_mfma_f32_16x16x32_bf16 v[106:109], v[180:183], v[188:191], v[106:109]
	s_setprio 0
	s_barrier
	s_mov_b32 m0, s40
	v_lshl_add_u64 v[172:173], s[22:23], 0, v[132:133]
	ds_read_b128 v[188:191], v141 offset:16384
	ds_read_b128 v[192:195], v141 offset:17408
	ds_read_b128 v[204:207], v141 offset:18432
	ds_read_b128 v[208:211], v141 offset:19456
	ds_read_b128 v[212:215], v141 offset:20480
	ds_read_b128 v[216:219], v141 offset:21504
	ds_read_b128 v[220:223], v141 offset:22528
	ds_read_b128 v[224:227], v141 offset:23552
	global_load_lds_dwordx4 v[172:173], off
	v_lshl_add_u64 v[196:197], s[22:23], 0, v[136:137]
	s_mov_b32 m0, s41
	v_lshl_add_u64 v[228:229], s[24:25], 0, v[132:133]
	global_load_lds_dwordx4 v[196:197], off
	s_mov_b32 m0, s42
	v_lshl_add_u64 v[230:231], s[20:21], 0, v[134:135]
	global_load_lds_dwordx4 v[228:229], off
	v_lshl_add_u64 v[228:229], s[24:25], 0, v[136:137]
	s_mov_b32 m0, s43
	s_nop 0
	global_load_lds_dwordx4 v[228:229], off
	v_lshl_add_u64 v[228:229], s[20:21], 0, v[130:131]
	s_mov_b32 m0, s7
	s_nop 0
	global_load_lds_dwordx4 v[228:229], off
	s_mov_b32 m0, s31
	s_nop 0
	global_load_lds_dwordx4 v[230:231], off
	s_waitcnt vmcnt(8)
	s_waitcnt lgkmcnt(0)
	s_barrier
	s_setprio 1
	s_waitcnt lgkmcnt(0)
	v_mfma_f32_16x16x32_bf16 v[62:65], v[144:147], v[188:191], v[62:65]
	v_mfma_f32_16x16x32_bf16 v[62:65], v[150:153], v[192:195], v[62:65]
	v_mfma_f32_16x16x32_bf16 v[54:57], v[150:153], v[208:211], v[54:57]
	v_mfma_f32_16x16x32_bf16 v[54:57], v[144:147], v[204:207], v[54:57]
	v_mfma_f32_16x16x32_bf16 v[38:41], v[144:147], v[212:215], v[38:41]
	v_mfma_f32_16x16x32_bf16 v[38:41], v[150:153], v[216:219], v[38:41]
	v_mfma_f32_16x16x32_bf16 v[22:25], v[150:153], v[224:227], v[22:25]
	v_mfma_f32_16x16x32_bf16 v[22:25], v[144:147], v[220:223], v[22:25]
	v_mfma_f32_16x16x32_bf16 v[18:21], v[154:157], v[220:223], v[18:21]
	v_mfma_f32_16x16x32_bf16 v[18:21], v[158:161], v[224:227], v[18:21]
	v_mfma_f32_16x16x32_bf16 v[34:37], v[158:161], v[216:219], v[34:37]
	v_mfma_f32_16x16x32_bf16 v[34:37], v[154:157], v[212:215], v[34:37]
	v_mfma_f32_16x16x32_bf16 v[50:53], v[154:157], v[204:207], v[50:53]
	v_mfma_f32_16x16x32_bf16 v[50:53], v[158:161], v[208:211], v[50:53]
	v_mfma_f32_16x16x32_bf16 v[58:61], v[158:161], v[192:195], v[58:61]
	v_mfma_f32_16x16x32_bf16 v[58:61], v[154:157], v[188:191], v[58:61]
	v_mfma_f32_16x16x32_bf16 v[46:49], v[168:171], v[188:191], v[46:49]
	v_mfma_f32_16x16x32_bf16 v[46:49], v[176:179], v[192:195], v[46:49]
	v_mfma_f32_16x16x32_bf16 v[30:33], v[176:179], v[208:211], v[30:33]
	v_mfma_f32_16x16x32_bf16 v[30:33], v[168:171], v[204:207], v[30:33]
	v_mfma_f32_16x16x32_bf16 v[14:17], v[168:171], v[212:215], v[14:17]
	v_mfma_f32_16x16x32_bf16 v[14:17], v[176:179], v[216:219], v[14:17]
	v_mfma_f32_16x16x32_bf16 v[6:9], v[176:179], v[224:227], v[6:9]
	v_mfma_f32_16x16x32_bf16 v[6:9], v[168:171], v[220:223], v[6:9]
	v_mfma_f32_16x16x32_bf16 v[2:5], v[180:183], v[220:223], v[2:5]
	v_mfma_f32_16x16x32_bf16 v[2:5], v[184:187], v[224:227], v[2:5]
	v_mfma_f32_16x16x32_bf16 v[10:13], v[184:187], v[216:219], v[10:13]
	v_mfma_f32_16x16x32_bf16 v[10:13], v[180:183], v[212:215], v[10:13]
	v_mfma_f32_16x16x32_bf16 v[26:29], v[180:183], v[204:207], v[26:29]
	v_mfma_f32_16x16x32_bf16 v[26:29], v[184:187], v[208:211], v[26:29]
	v_mfma_f32_16x16x32_bf16 v[42:45], v[184:187], v[192:195], v[42:45]
	v_mfma_f32_16x16x32_bf16 v[42:45], v[180:183], v[188:191], v[42:45]
	s_setprio 0
	s_barrier
	ds_read_b128 v[144:147], v142
	ds_read_b128 v[150:153], v142 offset:1024
	ds_read_b128 v[154:157], v142 offset:2048
	ds_read_b128 v[158:161], v142 offset:3072
	ds_read_b128 v[168:171], v143
	ds_read_b128 v[176:179], v143 offset:1024
	ds_read_b128 v[180:183], v143 offset:2048
	ds_read_b128 v[184:187], v143 offset:3072
	s_mov_b32 m0, s33
	v_lshl_add_u64 v[232:233], s[18:19], 0, v[130:131]
	ds_read_b128 v[188:191], v141 offset:32768
	ds_read_b128 v[192:195], v141 offset:33792
	ds_read_b128 v[204:207], v141 offset:34816
	ds_read_b128 v[208:211], v141 offset:35840
	ds_read_b128 v[212:215], v141 offset:36864
	ds_read_b128 v[216:219], v141 offset:37888
	ds_read_b128 v[220:223], v141 offset:38912
	ds_read_b128 v[224:227], v141 offset:39936
	global_load_lds_dwordx4 v[232:233], off
	v_lshl_add_u64 v[232:233], s[18:19], 0, v[134:135]
	s_mov_b32 m0, s34
	s_nop 0
	global_load_lds_dwordx4 v[232:233], off
	s_waitcnt vmcnt(8)
	s_waitcnt lgkmcnt(0)
	s_barrier
	s_setprio 1
	s_waitcnt lgkmcnt(0)
	v_mfma_f32_16x16x32_bf16 v[126:129], v[144:147], v[188:191], v[126:129]
	v_mfma_f32_16x16x32_bf16 v[126:129], v[150:153], v[192:195], v[126:129]
	v_mfma_f32_16x16x32_bf16 v[118:121], v[150:153], v[208:211], v[118:121]
	v_mfma_f32_16x16x32_bf16 v[118:121], v[144:147], v[204:207], v[118:121]
	v_mfma_f32_16x16x32_bf16 v[102:105], v[144:147], v[212:215], v[102:105]
	v_mfma_f32_16x16x32_bf16 v[102:105], v[150:153], v[216:219], v[102:105]
	v_mfma_f32_16x16x32_bf16 v[86:89], v[150:153], v[224:227], v[86:89]
	v_mfma_f32_16x16x32_bf16 v[86:89], v[144:147], v[220:223], v[86:89]
	v_mfma_f32_16x16x32_bf16 v[82:85], v[154:157], v[220:223], v[82:85]
	v_mfma_f32_16x16x32_bf16 v[82:85], v[158:161], v[224:227], v[82:85]
	v_mfma_f32_16x16x32_bf16 v[98:101], v[158:161], v[216:219], v[98:101]
	v_mfma_f32_16x16x32_bf16 v[98:101], v[154:157], v[212:215], v[98:101]
	v_mfma_f32_16x16x32_bf16 v[114:117], v[154:157], v[204:207], v[114:117]
	v_mfma_f32_16x16x32_bf16 v[114:117], v[158:161], v[208:211], v[114:117]
	v_mfma_f32_16x16x32_bf16 v[122:125], v[158:161], v[192:195], v[122:125]
	v_mfma_f32_16x16x32_bf16 v[122:125], v[154:157], v[188:191], v[122:125]
	v_mfma_f32_16x16x32_bf16 v[110:113], v[168:171], v[188:191], v[110:113]
	v_mfma_f32_16x16x32_bf16 v[110:113], v[176:179], v[192:195], v[110:113]
	v_mfma_f32_16x16x32_bf16 v[94:97], v[176:179], v[208:211], v[94:97]
	v_mfma_f32_16x16x32_bf16 v[94:97], v[168:171], v[204:207], v[94:97]
	v_mfma_f32_16x16x32_bf16 v[78:81], v[168:171], v[212:215], v[78:81]
	v_mfma_f32_16x16x32_bf16 v[78:81], v[176:179], v[216:219], v[78:81]
	v_mfma_f32_16x16x32_bf16 v[70:73], v[176:179], v[224:227], v[70:73]
	v_mfma_f32_16x16x32_bf16 v[70:73], v[168:171], v[220:223], v[70:73]
	v_mfma_f32_16x16x32_bf16 v[66:69], v[180:183], v[220:223], v[66:69]
	v_mfma_f32_16x16x32_bf16 v[66:69], v[184:187], v[224:227], v[66:69]
	v_mfma_f32_16x16x32_bf16 v[74:77], v[184:187], v[216:219], v[74:77]
	v_mfma_f32_16x16x32_bf16 v[74:77], v[180:183], v[212:215], v[74:77]
	v_mfma_f32_16x16x32_bf16 v[90:93], v[180:183], v[204:207], v[90:93]
	v_mfma_f32_16x16x32_bf16 v[90:93], v[184:187], v[208:211], v[90:93]
	v_mfma_f32_16x16x32_bf16 v[106:109], v[184:187], v[192:195], v[106:109]
	v_mfma_f32_16x16x32_bf16 v[106:109], v[180:183], v[188:191], v[106:109]
	s_setprio 0
	s_barrier
	s_mov_b32 m0, s44
	v_lshl_add_u64 v[172:173], v[172:173], 0, s[14:15]
	ds_read_b128 v[188:191], v141 offset:49152
	ds_read_b128 v[192:195], v141 offset:50176
	ds_read_b128 v[204:207], v141 offset:51200
	ds_read_b128 v[208:211], v141 offset:52224
	ds_read_b128 v[212:215], v141 offset:53248
	ds_read_b128 v[216:219], v141 offset:54272
	ds_read_b128 v[220:223], v141 offset:55296
	ds_read_b128 v[224:227], v141 offset:56320
	global_load_lds_dwordx4 v[172:173], off
	v_lshl_add_u64 v[172:173], v[196:197], 0, s[14:15]
	s_mov_b32 m0, s45
	s_nop 0
	global_load_lds_dwordx4 v[172:173], off
	v_lshl_add_u64 v[172:173], s[26:27], 0, v[132:133]
	s_mov_b32 m0, s46
	s_nop 0
	global_load_lds_dwordx4 v[172:173], off
	v_lshl_add_u64 v[172:173], s[26:27], 0, v[136:137]
	s_mov_b32 m0, s47
	s_nop 0
	global_load_lds_dwordx4 v[172:173], off
	v_lshl_add_u64 v[172:173], v[228:229], 0, s[14:15]
	s_mov_b32 m0, s36
	s_nop 0
	global_load_lds_dwordx4 v[172:173], off
	v_lshl_add_u64 v[172:173], v[230:231], 0, s[14:15]
	s_mov_b32 m0, s37
	s_nop 0
	global_load_lds_dwordx4 v[172:173], off
	s_waitcnt vmcnt(8)
	s_waitcnt lgkmcnt(0)
	s_barrier
	s_setprio 1
	s_waitcnt lgkmcnt(0)
	v_mfma_f32_16x16x32_bf16 v[62:65], v[144:147], v[188:191], v[62:65]
	v_mfma_f32_16x16x32_bf16 v[62:65], v[150:153], v[192:195], v[62:65]
	v_mfma_f32_16x16x32_bf16 v[54:57], v[150:153], v[208:211], v[54:57]
	v_mfma_f32_16x16x32_bf16 v[54:57], v[144:147], v[204:207], v[54:57]
	v_mfma_f32_16x16x32_bf16 v[38:41], v[144:147], v[212:215], v[38:41]
	v_mfma_f32_16x16x32_bf16 v[38:41], v[150:153], v[216:219], v[38:41]
	v_mfma_f32_16x16x32_bf16 v[22:25], v[150:153], v[224:227], v[22:25]
	v_mfma_f32_16x16x32_bf16 v[22:25], v[144:147], v[220:223], v[22:25]
	v_mfma_f32_16x16x32_bf16 v[18:21], v[154:157], v[220:223], v[18:21]
	v_mfma_f32_16x16x32_bf16 v[18:21], v[158:161], v[224:227], v[18:21]
	v_mfma_f32_16x16x32_bf16 v[34:37], v[158:161], v[216:219], v[34:37]
	v_mfma_f32_16x16x32_bf16 v[34:37], v[154:157], v[212:215], v[34:37]
	v_mfma_f32_16x16x32_bf16 v[50:53], v[154:157], v[204:207], v[50:53]
	v_mfma_f32_16x16x32_bf16 v[50:53], v[158:161], v[208:211], v[50:53]
	v_mfma_f32_16x16x32_bf16 v[58:61], v[158:161], v[192:195], v[58:61]
	v_mfma_f32_16x16x32_bf16 v[58:61], v[154:157], v[188:191], v[58:61]
	v_mfma_f32_16x16x32_bf16 v[46:49], v[168:171], v[188:191], v[46:49]
	v_mfma_f32_16x16x32_bf16 v[46:49], v[176:179], v[192:195], v[46:49]
	v_mfma_f32_16x16x32_bf16 v[30:33], v[176:179], v[208:211], v[30:33]
	v_mfma_f32_16x16x32_bf16 v[30:33], v[168:171], v[204:207], v[30:33]
	v_mfma_f32_16x16x32_bf16 v[14:17], v[168:171], v[212:215], v[14:17]
	v_mfma_f32_16x16x32_bf16 v[14:17], v[176:179], v[216:219], v[14:17]
	v_mfma_f32_16x16x32_bf16 v[6:9], v[176:179], v[224:227], v[6:9]
	v_mfma_f32_16x16x32_bf16 v[6:9], v[168:171], v[220:223], v[6:9]
	v_mfma_f32_16x16x32_bf16 v[2:5], v[180:183], v[220:223], v[2:5]
	v_mfma_f32_16x16x32_bf16 v[2:5], v[184:187], v[224:227], v[2:5]
	v_mfma_f32_16x16x32_bf16 v[10:13], v[184:187], v[216:219], v[10:13]
	v_mfma_f32_16x16x32_bf16 v[10:13], v[180:183], v[212:215], v[10:13]
	v_mfma_f32_16x16x32_bf16 v[26:29], v[180:183], v[204:207], v[26:29]
	v_mfma_f32_16x16x32_bf16 v[26:29], v[184:187], v[208:211], v[26:29]
	v_mfma_f32_16x16x32_bf16 v[42:45], v[184:187], v[192:195], v[42:45]
	v_mfma_f32_16x16x32_bf16 v[42:45], v[180:183], v[188:191], v[42:45]
	s_setprio 0
	s_barrier
	s_andn2_b64 vcc, exec, s[16:17]
	s_mov_b64 s[18:19], -1
	s_mov_b64 s[16:17], 0
	s_movk_i32 s24, 0x100
	s_cbranch_vccz .LBB0_2240
	s_lshl_b32 s7, s30, 21
	v_readlane_b32 s0, v249, 29
	v_lshl_or_b32 v130, s6, 8, v148
	v_mov_b32_e32 v139, 0
	s_add_u32 s8, s0, s7
	v_readlane_b32 s0, v249, 31
	v_or_b32_e32 v130, s35, v130
	v_cvt_pk_bf16_f32 v70, v70, v71
	v_cvt_pk_bf16_f32 v71, v72, v73
	v_cvt_pk_bf16_f32 v72, v66, v67
	v_add_u32_e32 v66, 0x80, v138
	v_mov_b32_e32 v67, v139
	s_addc_u32 s9, s0, 0
	v_ashrrev_i32_e32 v131, 31, v130
	v_lshlrev_b64 v[132:133], 13, v[138:139]
	v_cvt_pk_bf16_f32 v110, v110, v111
	v_cvt_pk_bf16_f32 v111, v112, v113
	v_cvt_pk_bf16_f32 v112, v106, v107
	v_or_b32_e32 v106, 16, v138
	v_mov_b32_e32 v107, v139
	v_lshlrev_b64 v[66:67], 13, v[66:67]
	v_cvt_pk_bf16_f32 v46, v46, v47
	v_cvt_pk_bf16_f32 v47, v48, v49
	v_cvt_pk_bf16_f32 v48, v42, v43
	v_add_u32_e32 v42, 0x90, v138
	v_mov_b32_e32 v43, v139
	v_lshl_add_u64 v[132:133], s[8:9], 0, v[132:133]
	v_lshlrev_b64 v[130:131], 1, v[130:131]
	v_lshlrev_b64 v[106:107], 13, v[106:107]
	v_cvt_pk_bf16_f32 v94, v94, v95
	v_cvt_pk_bf16_f32 v95, v96, v97
	v_cvt_pk_bf16_f32 v96, v90, v91
	v_or_b32_e32 v90, 32, v138
	v_mov_b32_e32 v91, v139
	v_lshl_add_u64 v[66:67], s[8:9], 0, v[66:67]
	v_lshlrev_b64 v[42:43], 13, v[42:43]
	v_cvt_pk_bf16_f32 v30, v30, v31
	v_cvt_pk_bf16_f32 v31, v32, v33
	v_cvt_pk_bf16_f32 v32, v26, v27
	v_add_u32_e32 v26, 0xa0, v138
	v_mov_b32_e32 v27, v139
	v_lshl_add_u64 v[132:133], v[132:133], 0, v[130:131]
	v_cvt_pk_bf16_f32 v113, v108, v109
	v_lshl_add_u64 v[106:107], s[8:9], 0, v[106:107]
	v_lshlrev_b64 v[90:91], 13, v[90:91]
	v_cvt_pk_bf16_f32 v78, v78, v79
	v_cvt_pk_bf16_f32 v79, v80, v81
	v_cvt_pk_bf16_f32 v80, v74, v75
	v_or_b32_e32 v74, 48, v138
	v_mov_b32_e32 v75, v139
	v_lshl_add_u64 v[66:67], v[66:67], 0, v[130:131]
	v_cvt_pk_bf16_f32 v49, v44, v45
	v_lshl_add_u64 v[42:43], s[8:9], 0, v[42:43]
	v_lshlrev_b64 v[26:27], 13, v[26:27]
	v_add_u32_e32 v138, 0xb0, v138
	global_store_dwordx4 v[132:133], v[110:113], off offset:256
	v_cvt_pk_bf16_f32 v97, v92, v93
	v_lshl_add_u64 v[90:91], s[8:9], 0, v[90:91]
	v_lshl_add_u64 v[110:111], v[106:107], 0, v[130:131]
	v_lshlrev_b64 v[74:75], 13, v[74:75]
	global_store_dwordx4 v[66:67], v[46:49], off offset:256
	v_cvt_pk_bf16_f32 v33, v28, v29
	v_lshl_add_u64 v[26:27], s[8:9], 0, v[26:27]
	v_lshl_add_u64 v[46:47], v[42:43], 0, v[130:131]
	v_cvt_pk_bf16_f32 v14, v14, v15
	v_cvt_pk_bf16_f32 v15, v16, v17
	v_cvt_pk_bf16_f32 v16, v10, v11
	v_lshlrev_b64 v[10:11], 13, v[138:139]
	global_store_dwordx4 v[110:111], v[94:97], off offset:256
	v_cvt_pk_bf16_f32 v81, v76, v77
	v_lshl_add_u64 v[74:75], s[8:9], 0, v[74:75]
	v_lshl_add_u64 v[94:95], v[90:91], 0, v[130:131]
	global_store_dwordx4 v[46:47], v[30:33], off offset:256
	v_cvt_pk_bf16_f32 v17, v12, v13
	v_lshl_add_u64 v[10:11], s[8:9], 0, v[10:11]
	v_lshl_add_u64 v[30:31], v[26:27], 0, v[130:131]
	v_cvt_pk_bf16_f32 v126, v126, v127
	v_cvt_pk_bf16_f32 v127, v128, v129
	v_cvt_pk_bf16_f32 v128, v122, v123
	v_cvt_pk_bf16_f32 v129, v124, v125
	v_cvt_pk_bf16_f32 v106, v118, v119
	v_cvt_pk_bf16_f32 v107, v120, v121
	v_cvt_pk_bf16_f32 v108, v114, v115
	v_cvt_pk_bf16_f32 v109, v116, v117
	v_cvt_pk_bf16_f32 v90, v102, v103
	v_cvt_pk_bf16_f32 v91, v104, v105
	v_cvt_pk_bf16_f32 v92, v98, v99
	v_cvt_pk_bf16_f32 v93, v100, v101
	global_store_dwordx4 v[94:95], v[78:81], off offset:256
	v_cvt_pk_bf16_f32 v76, v82, v83
	v_cvt_pk_bf16_f32 v77, v84, v85
	v_lshl_add_u64 v[78:79], v[74:75], 0, v[130:131]
	v_cvt_pk_bf16_f32 v74, v86, v87
	v_cvt_pk_bf16_f32 v75, v88, v89
	v_cvt_pk_bf16_f32 v73, v68, v69
	v_cvt_pk_bf16_f32 v62, v62, v63
	v_cvt_pk_bf16_f32 v63, v64, v65
	v_cvt_pk_bf16_f32 v64, v58, v59
	v_cvt_pk_bf16_f32 v65, v60, v61
	v_cvt_pk_bf16_f32 v42, v54, v55
	v_cvt_pk_bf16_f32 v43, v56, v57
	v_cvt_pk_bf16_f32 v44, v50, v51
	v_cvt_pk_bf16_f32 v45, v52, v53
	v_cvt_pk_bf16_f32 v26, v38, v39
	v_cvt_pk_bf16_f32 v27, v40, v41
	v_cvt_pk_bf16_f32 v28, v34, v35
	v_cvt_pk_bf16_f32 v29, v36, v37
	global_store_dwordx4 v[30:31], v[14:17], off offset:256
	v_cvt_pk_bf16_f32 v12, v18, v19
	v_cvt_pk_bf16_f32 v13, v20, v21
	v_lshl_add_u64 v[14:15], v[10:11], 0, v[130:131]
	v_cvt_pk_bf16_f32 v10, v22, v23
	v_cvt_pk_bf16_f32 v11, v24, v25
	v_cvt_pk_bf16_f32 v6, v6, v7
	v_cvt_pk_bf16_f32 v7, v8, v9
	v_cvt_pk_bf16_f32 v8, v2, v3
	v_cvt_pk_bf16_f32 v9, v4, v5
	global_store_dwordx4 v[132:133], v[126:129], off
	global_store_dwordx4 v[110:111], v[106:109], off
	global_store_dwordx4 v[94:95], v[90:93], off
	global_store_dwordx4 v[78:79], v[74:77], off
	global_store_dwordx4 v[78:79], v[70:73], off offset:256
	global_store_dwordx4 v[66:67], v[62:65], off
	global_store_dwordx4 v[46:47], v[42:45], off
	global_store_dwordx4 v[30:31], v[26:29], off
	global_store_dwordx4 v[14:15], v[10:13], off
	global_store_dwordx4 v[14:15], v[6:9], off offset:256
	s_waitcnt vmcnt(0)
	s_cmpk_lt_u32 s3, 0x100
	s_cbranch_scc0 .LBB0_2243
	s_barrier

.LBB0_2373:
	s_add_u32 s60, s20, 0xfff00000
	s_addc_u32 s61, s21, -1
	s_mov_b32 m0, s35
	ds_read_b128 v[142:145], v148
	global_load_lds_dwordx4 v130, s[60:61]
	s_mov_b32 m0, s36
	ds_read_b128 v[154:157], v148 offset:1024
	global_load_lds_dwordx4 v134, s[60:61]
	s_mov_b32 m0, s40
	ds_read_b128 v[158:161], v148 offset:2048
	global_load_lds_dwordx4 v138, s[20:21]
	s_mov_b32 m0, s41
	ds_read_b128 v[168:171], v148 offset:3072
	global_load_lds_dwordx4 v140, s[20:21]
	ds_read_b128 v[176:179], v149
	ds_read_b128 v[180:183], v149 offset:1024
	ds_read_b128 v[184:187], v149 offset:2048
	ds_read_b128 v[188:191], v149 offset:3072
	s_add_u32 s22, s20, 0xfff00080
	s_addc_u32 s23, s21, -1
	s_cmp_eq_u32 s57, 60
	s_cselect_b32 s25, s52, s23
	s_cselect_b32 s24, s53, s22
	s_cselect_b32 s23, s7, s56
	s_cselect_b32 s22, s54, s55
	ds_read_b128 v[192:195], v150
	ds_read_b128 v[204:207], v150 offset:1024
	ds_read_b128 v[208:211], v150 offset:2048
	ds_read_b128 v[212:215], v150 offset:3072
	ds_read_b128 v[216:219], v150 offset:4096
	ds_read_b128 v[220:223], v150 offset:5120
	ds_read_b128 v[224:227], v150 offset:6144
	ds_read_b128 v[228:231], v150 offset:7168
	s_waitcnt vmcnt(8)
	s_waitcnt lgkmcnt(0)
	s_barrier
	s_setprio 1
	s_waitcnt lgkmcnt(0)
	v_mfma_f32_16x16x32_bf16 v[126:129], v[142:145], v[192:195], v[126:129]
	v_mfma_f32_16x16x32_bf16 v[126:129], v[154:157], v[204:207], v[126:129]
	v_mfma_f32_16x16x32_bf16 v[110:113], v[154:157], v[212:215], v[110:113]
	v_mfma_f32_16x16x32_bf16 v[110:113], v[142:145], v[208:211], v[110:113]
	v_mfma_f32_16x16x32_bf16 v[94:97], v[142:145], v[216:219], v[94:97]
	v_mfma_f32_16x16x32_bf16 v[94:97], v[154:157], v[220:223], v[94:97]
	v_mfma_f32_16x16x32_bf16 v[78:81], v[154:157], v[228:231], v[78:81]
	v_mfma_f32_16x16x32_bf16 v[78:81], v[142:145], v[224:227], v[78:81]
	v_mfma_f32_16x16x32_bf16 v[74:77], v[158:161], v[224:227], v[74:77]
	v_mfma_f32_16x16x32_bf16 v[74:77], v[168:171], v[228:231], v[74:77]
	v_mfma_f32_16x16x32_bf16 v[90:93], v[168:171], v[220:223], v[90:93]
	v_mfma_f32_16x16x32_bf16 v[90:93], v[158:161], v[216:219], v[90:93]
	v_mfma_f32_16x16x32_bf16 v[106:109], v[158:161], v[208:211], v[106:109]
	v_mfma_f32_16x16x32_bf16 v[106:109], v[168:171], v[212:215], v[106:109]
	v_mfma_f32_16x16x32_bf16 v[122:125], v[168:171], v[204:207], v[122:125]
	v_mfma_f32_16x16x32_bf16 v[122:125], v[158:161], v[192:195], v[122:125]
	v_mfma_f32_16x16x32_bf16 v[118:121], v[176:179], v[192:195], v[118:121]
	v_mfma_f32_16x16x32_bf16 v[118:121], v[180:183], v[204:207], v[118:121]
	v_mfma_f32_16x16x32_bf16 v[102:105], v[180:183], v[212:215], v[102:105]
	v_mfma_f32_16x16x32_bf16 v[102:105], v[176:179], v[208:211], v[102:105]
	v_mfma_f32_16x16x32_bf16 v[86:89], v[176:179], v[216:219], v[86:89]
	v_mfma_f32_16x16x32_bf16 v[86:89], v[180:183], v[220:223], v[86:89]
	v_mfma_f32_16x16x32_bf16 v[70:73], v[180:183], v[228:231], v[70:73]
	v_mfma_f32_16x16x32_bf16 v[70:73], v[176:179], v[224:227], v[70:73]
	v_mfma_f32_16x16x32_bf16 v[66:69], v[184:187], v[224:227], v[66:69]
	v_mfma_f32_16x16x32_bf16 v[66:69], v[188:191], v[228:231], v[66:69]
	v_mfma_f32_16x16x32_bf16 v[82:85], v[188:191], v[220:223], v[82:85]
	v_mfma_f32_16x16x32_bf16 v[82:85], v[184:187], v[216:219], v[82:85]
	v_mfma_f32_16x16x32_bf16 v[98:101], v[184:187], v[208:211], v[98:101]
	v_mfma_f32_16x16x32_bf16 v[98:101], v[188:191], v[212:215], v[98:101]
	v_mfma_f32_16x16x32_bf16 v[114:117], v[188:191], v[204:207], v[114:117]
	v_mfma_f32_16x16x32_bf16 v[114:117], v[184:187], v[192:195], v[114:117]
	s_setprio 0
	s_barrier
	s_mov_b32 m0, s42
	s_add_u32 s60, s22, 0x100000
	global_load_lds_dwordx4 v132, s[22:23]
	s_mov_b32 m0, s43
	s_addc_u32 s61, s23, 0
	global_load_lds_dwordx4 v136, s[22:23]
	s_mov_b32 m0, s44
	ds_read_b128 v[192:195], v150 offset:16384
	global_load_lds_dwordx4 v132, s[60:61]
	s_mov_b32 m0, s45
	ds_read_b128 v[204:207], v150 offset:17408
	global_load_lds_dwordx4 v136, s[60:61]
	ds_read_b128 v[208:211], v150 offset:18432
	ds_read_b128 v[212:215], v150 offset:19456
	ds_read_b128 v[216:219], v150 offset:20480
	ds_read_b128 v[220:223], v150 offset:21504
	ds_read_b128 v[224:227], v150 offset:22528
	ds_read_b128 v[228:231], v150 offset:23552
	s_waitcnt vmcnt(6)
	s_waitcnt lgkmcnt(0)
	s_barrier
	s_setprio 1
	s_waitcnt lgkmcnt(0)
	v_mfma_f32_16x16x32_bf16 v[62:65], v[142:145], v[192:195], v[62:65]
	v_mfma_f32_16x16x32_bf16 v[62:65], v[154:157], v[204:207], v[62:65]
	v_mfma_f32_16x16x32_bf16 v[46:49], v[154:157], v[212:215], v[46:49]
	v_mfma_f32_16x16x32_bf16 v[46:49], v[142:145], v[208:211], v[46:49]
	v_mfma_f32_16x16x32_bf16 v[30:33], v[142:145], v[216:219], v[30:33]
	v_mfma_f32_16x16x32_bf16 v[30:33], v[154:157], v[220:223], v[30:33]
	v_mfma_f32_16x16x32_bf16 v[14:17], v[154:157], v[228:231], v[14:17]
	v_mfma_f32_16x16x32_bf16 v[14:17], v[142:145], v[224:227], v[14:17]
	v_mfma_f32_16x16x32_bf16 v[10:13], v[158:161], v[224:227], v[10:13]
	v_mfma_f32_16x16x32_bf16 v[10:13], v[168:171], v[228:231], v[10:13]
	v_mfma_f32_16x16x32_bf16 v[26:29], v[168:171], v[220:223], v[26:29]
	v_mfma_f32_16x16x32_bf16 v[26:29], v[158:161], v[216:219], v[26:29]
	v_mfma_f32_16x16x32_bf16 v[42:45], v[158:161], v[208:211], v[42:45]
	v_mfma_f32_16x16x32_bf16 v[42:45], v[168:171], v[212:215], v[42:45]
	v_mfma_f32_16x16x32_bf16 v[58:61], v[168:171], v[204:207], v[58:61]
	v_mfma_f32_16x16x32_bf16 v[58:61], v[158:161], v[192:195], v[58:61]
	v_mfma_f32_16x16x32_bf16 v[54:57], v[176:179], v[192:195], v[54:57]
	v_mfma_f32_16x16x32_bf16 v[54:57], v[180:183], v[204:207], v[54:57]
	v_mfma_f32_16x16x32_bf16 v[38:41], v[180:183], v[212:215], v[38:41]
	v_mfma_f32_16x16x32_bf16 v[38:41], v[176:179], v[208:211], v[38:41]
	v_mfma_f32_16x16x32_bf16 v[22:25], v[176:179], v[216:219], v[22:25]
	v_mfma_f32_16x16x32_bf16 v[22:25], v[180:183], v[220:223], v[22:25]
	v_mfma_f32_16x16x32_bf16 v[6:9], v[180:183], v[228:231], v[6:9]
	v_mfma_f32_16x16x32_bf16 v[6:9], v[176:179], v[224:227], v[6:9]
	v_mfma_f32_16x16x32_bf16 v[2:5], v[184:187], v[224:227], v[2:5]
	v_mfma_f32_16x16x32_bf16 v[2:5], v[188:191], v[228:231], v[2:5]
	v_mfma_f32_16x16x32_bf16 v[18:21], v[188:191], v[220:223], v[18:21]
	v_mfma_f32_16x16x32_bf16 v[18:21], v[184:187], v[216:219], v[18:21]
	v_mfma_f32_16x16x32_bf16 v[34:37], v[184:187], v[208:211], v[34:37]
	v_mfma_f32_16x16x32_bf16 v[34:37], v[188:191], v[212:215], v[34:37]
	v_mfma_f32_16x16x32_bf16 v[50:53], v[188:191], v[204:207], v[50:53]
	v_mfma_f32_16x16x32_bf16 v[50:53], v[184:187], v[192:195], v[50:53]
	s_setprio 0
	s_barrier
	s_mov_b32 m0, s29
	ds_read_b128 v[142:145], v151
	global_load_lds_dwordx4 v130, s[24:25]
	s_mov_b32 m0, s30
	ds_read_b128 v[154:157], v151 offset:1024
	global_load_lds_dwordx4 v134, s[24:25]
	s_add_u32 s24, s24, 0x100000
	s_addc_u32 s25, s25, 0
	s_mov_b32 m0, s31
	ds_read_b128 v[158:161], v151 offset:2048
	global_load_lds_dwordx4 v130, s[24:25]
	s_mov_b32 m0, s33
	ds_read_b128 v[168:171], v151 offset:3072
	global_load_lds_dwordx4 v134, s[24:25]
	ds_read_b128 v[176:179], v152
	ds_read_b128 v[180:183], v152 offset:1024
	ds_read_b128 v[184:187], v152 offset:2048
	ds_read_b128 v[188:191], v152 offset:3072
	ds_read_b128 v[192:195], v150 offset:32768
	ds_read_b128 v[204:207], v150 offset:33792
	ds_read_b128 v[208:211], v150 offset:34816
	ds_read_b128 v[212:215], v150 offset:35840
	ds_read_b128 v[216:219], v150 offset:36864
	ds_read_b128 v[220:223], v150 offset:37888
	ds_read_b128 v[224:227], v150 offset:38912
	ds_read_b128 v[228:231], v150 offset:39936
	s_waitcnt vmcnt(8)
	s_waitcnt lgkmcnt(0)
	s_barrier
	s_setprio 1
	s_waitcnt lgkmcnt(0)
	v_mfma_f32_16x16x32_bf16 v[126:129], v[142:145], v[192:195], v[126:129]
	v_mfma_f32_16x16x32_bf16 v[126:129], v[154:157], v[204:207], v[126:129]
	v_mfma_f32_16x16x32_bf16 v[110:113], v[154:157], v[212:215], v[110:113]
	v_mfma_f32_16x16x32_bf16 v[110:113], v[142:145], v[208:211], v[110:113]
	v_mfma_f32_16x16x32_bf16 v[94:97], v[142:145], v[216:219], v[94:97]
	v_mfma_f32_16x16x32_bf16 v[94:97], v[154:157], v[220:223], v[94:97]
	v_mfma_f32_16x16x32_bf16 v[78:81], v[154:157], v[228:231], v[78:81]
	v_mfma_f32_16x16x32_bf16 v[78:81], v[142:145], v[224:227], v[78:81]
	v_mfma_f32_16x16x32_bf16 v[74:77], v[158:161], v[224:227], v[74:77]
	v_mfma_f32_16x16x32_bf16 v[74:77], v[168:171], v[228:231], v[74:77]
	v_mfma_f32_16x16x32_bf16 v[90:93], v[168:171], v[220:223], v[90:93]
	v_mfma_f32_16x16x32_bf16 v[90:93], v[158:161], v[216:219], v[90:93]
	v_mfma_f32_16x16x32_bf16 v[106:109], v[158:161], v[208:211], v[106:109]
	v_mfma_f32_16x16x32_bf16 v[106:109], v[168:171], v[212:215], v[106:109]
	v_mfma_f32_16x16x32_bf16 v[122:125], v[168:171], v[204:207], v[122:125]
	v_mfma_f32_16x16x32_bf16 v[122:125], v[158:161], v[192:195], v[122:125]
	v_mfma_f32_16x16x32_bf16 v[118:121], v[176:179], v[192:195], v[118:121]
	v_mfma_f32_16x16x32_bf16 v[118:121], v[180:183], v[204:207], v[118:121]
	v_mfma_f32_16x16x32_bf16 v[102:105], v[180:183], v[212:215], v[102:105]
	v_mfma_f32_16x16x32_bf16 v[102:105], v[176:179], v[208:211], v[102:105]
	v_mfma_f32_16x16x32_bf16 v[86:89], v[176:179], v[216:219], v[86:89]
	v_mfma_f32_16x16x32_bf16 v[86:89], v[180:183], v[220:223], v[86:89]
	v_mfma_f32_16x16x32_bf16 v[70:73], v[180:183], v[228:231], v[70:73]
	v_mfma_f32_16x16x32_bf16 v[70:73], v[176:179], v[224:227], v[70:73]
	v_mfma_f32_16x16x32_bf16 v[66:69], v[184:187], v[224:227], v[66:69]
	v_mfma_f32_16x16x32_bf16 v[66:69], v[188:191], v[228:231], v[66:69]
	v_mfma_f32_16x16x32_bf16 v[82:85], v[188:191], v[220:223], v[82:85]
	v_mfma_f32_16x16x32_bf16 v[82:85], v[184:187], v[216:219], v[82:85]
	v_mfma_f32_16x16x32_bf16 v[98:101], v[184:187], v[208:211], v[98:101]
	v_mfma_f32_16x16x32_bf16 v[98:101], v[188:191], v[212:215], v[98:101]
	v_mfma_f32_16x16x32_bf16 v[114:117], v[188:191], v[204:207], v[114:117]
	v_mfma_f32_16x16x32_bf16 v[114:117], v[184:187], v[192:195], v[114:117]
	s_setprio 0
	s_barrier
	s_mov_b32 m0, s46
	s_add_u32 s22, s22, 0x80
	s_addc_u32 s23, s23, 0
	global_load_lds_dwordx4 v132, s[22:23]
	s_mov_b32 m0, s47
	ds_read_b128 v[192:195], v150 offset:49152
	global_load_lds_dwordx4 v136, s[22:23]
	s_mov_b32 m0, s48
	s_add_u32 s22, s22, 0x100000
	s_addc_u32 s23, s23, 0
	global_load_lds_dwordx4 v132, s[22:23]
	s_mov_b32 m0, s49
	ds_read_b128 v[204:207], v150 offset:50176
	global_load_lds_dwordx4 v136, s[22:23]
	ds_read_b128 v[208:211], v150 offset:51200
	ds_read_b128 v[212:215], v150 offset:52224
	ds_read_b128 v[216:219], v150 offset:53248
	ds_read_b128 v[220:223], v150 offset:54272
	ds_read_b128 v[224:227], v150 offset:55296
	ds_read_b128 v[228:231], v150 offset:56320
	s_waitcnt vmcnt(6)
	s_waitcnt lgkmcnt(0)
	s_barrier
	s_setprio 1
	s_waitcnt lgkmcnt(0)
	v_mfma_f32_16x16x32_bf16 v[62:65], v[142:145], v[192:195], v[62:65]
	v_mfma_f32_16x16x32_bf16 v[62:65], v[154:157], v[204:207], v[62:65]
	v_mfma_f32_16x16x32_bf16 v[46:49], v[154:157], v[212:215], v[46:49]
	v_mfma_f32_16x16x32_bf16 v[46:49], v[142:145], v[208:211], v[46:49]
	v_mfma_f32_16x16x32_bf16 v[30:33], v[142:145], v[216:219], v[30:33]
	v_mfma_f32_16x16x32_bf16 v[30:33], v[154:157], v[220:223], v[30:33]
	v_mfma_f32_16x16x32_bf16 v[14:17], v[154:157], v[228:231], v[14:17]
	v_mfma_f32_16x16x32_bf16 v[14:17], v[142:145], v[224:227], v[14:17]
	v_mfma_f32_16x16x32_bf16 v[10:13], v[158:161], v[224:227], v[10:13]
	v_mfma_f32_16x16x32_bf16 v[10:13], v[168:171], v[228:231], v[10:13]
	v_mfma_f32_16x16x32_bf16 v[26:29], v[168:171], v[220:223], v[26:29]
	v_mfma_f32_16x16x32_bf16 v[26:29], v[158:161], v[216:219], v[26:29]
	v_mfma_f32_16x16x32_bf16 v[42:45], v[158:161], v[208:211], v[42:45]
	v_mfma_f32_16x16x32_bf16 v[42:45], v[168:171], v[212:215], v[42:45]
	v_mfma_f32_16x16x32_bf16 v[58:61], v[168:171], v[204:207], v[58:61]
	v_mfma_f32_16x16x32_bf16 v[58:61], v[158:161], v[192:195], v[58:61]
	v_mfma_f32_16x16x32_bf16 v[54:57], v[176:179], v[192:195], v[54:57]
	v_mfma_f32_16x16x32_bf16 v[54:57], v[180:183], v[204:207], v[54:57]
	v_mfma_f32_16x16x32_bf16 v[38:41], v[180:183], v[212:215], v[38:41]
	v_mfma_f32_16x16x32_bf16 v[38:41], v[176:179], v[208:211], v[38:41]
	v_mfma_f32_16x16x32_bf16 v[22:25], v[176:179], v[216:219], v[22:25]
	v_mfma_f32_16x16x32_bf16 v[22:25], v[180:183], v[220:223], v[22:25]
	v_mfma_f32_16x16x32_bf16 v[6:9], v[180:183], v[228:231], v[6:9]
	v_mfma_f32_16x16x32_bf16 v[6:9], v[176:179], v[224:227], v[6:9]
	v_mfma_f32_16x16x32_bf16 v[2:5], v[184:187], v[224:227], v[2:5]
	v_mfma_f32_16x16x32_bf16 v[2:5], v[188:191], v[228:231], v[2:5]
	v_mfma_f32_16x16x32_bf16 v[18:21], v[188:191], v[220:223], v[18:21]
	v_mfma_f32_16x16x32_bf16 v[18:21], v[184:187], v[216:219], v[18:21]
	v_mfma_f32_16x16x32_bf16 v[34:37], v[184:187], v[208:211], v[34:37]
	v_mfma_f32_16x16x32_bf16 v[34:37], v[188:191], v[212:215], v[34:37]
	v_mfma_f32_16x16x32_bf16 v[50:53], v[188:191], v[204:207], v[50:53]
	v_mfma_f32_16x16x32_bf16 v[50:53], v[184:187], v[192:195], v[50:53]
	s_setprio 0
	s_barrier
	s_add_i32 s57, s57, 2
	s_add_u32 s20, s20, 0x100
	s_addc_u32 s21, s21, 0
	s_add_u32 s55, s55, 0x100
	s_addc_u32 s56, s56, 0
	s_cmp_gt_u32 s57, 61
	s_cbranch_scc0 .LBB0_2373
	s_and_b64 vcc, exec, s[16:17]
	s_cbranch_vccz .LBB0_2376
	s_barrier

.LBB0_2618:
	s_add_u32 s64, s28, 0xffd50000
	s_addc_u32 s65, s29, -1
	s_mov_b32 m0, s44
	ds_read_b128 v[142:145], v156
	global_load_lds_dwordx4 v130, s[64:65]
	s_mov_b32 m0, s45
	ds_read_b128 v[168:171], v156 offset:1024
	global_load_lds_dwordx4 v134, s[64:65]
	s_mov_b32 m0, s46
	ds_read_b128 v[172:175], v156 offset:2048
	global_load_lds_dwordx4 v138, s[28:29]
	s_mov_b32 m0, s47
	ds_read_b128 v[176:179], v156 offset:3072
	global_load_lds_dwordx4 v140, s[28:29]
	ds_read_b128 v[180:183], v157
	ds_read_b128 v[184:187], v157 offset:1024
	ds_read_b128 v[188:191], v157 offset:2048
	ds_read_b128 v[192:195], v157 offset:3072
	s_add_u32 s30, s28, 0xffd50080
	s_addc_u32 s31, s29, -1
	s_cmpk_eq_i32 s62, 0xa8
	s_cselect_b32 s35, s25, s31
	s_cselect_b32 s34, s24, s30
	s_cselect_b32 s31, s23, s61
	s_cselect_b32 s30, s22, s60
	ds_read_b128 v[196:199], v158
	ds_read_b128 v[200:203], v158 offset:1024
	ds_read_b128 v[204:207], v158 offset:2048
	ds_read_b128 v[208:211], v158 offset:3072
	ds_read_b128 v[212:215], v158 offset:4096
	ds_read_b128 v[216:219], v158 offset:5120
	ds_read_b128 v[220:223], v158 offset:6144
	ds_read_b128 v[224:227], v158 offset:7168
	s_waitcnt vmcnt(8)
	s_waitcnt lgkmcnt(0)
	s_barrier
	s_setprio 1
	s_waitcnt lgkmcnt(0)
	v_mfma_f32_16x16x32_bf16 v[126:129], v[142:145], v[196:199], v[126:129]
	v_mfma_f32_16x16x32_bf16 v[126:129], v[168:171], v[200:203], v[126:129]
	v_mfma_f32_16x16x32_bf16 v[110:113], v[168:171], v[208:211], v[110:113]
	v_mfma_f32_16x16x32_bf16 v[110:113], v[142:145], v[204:207], v[110:113]
	v_mfma_f32_16x16x32_bf16 v[94:97], v[142:145], v[212:215], v[94:97]
	v_mfma_f32_16x16x32_bf16 v[94:97], v[168:171], v[216:219], v[94:97]
	v_mfma_f32_16x16x32_bf16 v[78:81], v[168:171], v[224:227], v[78:81]
	v_mfma_f32_16x16x32_bf16 v[78:81], v[142:145], v[220:223], v[78:81]
	v_mfma_f32_16x16x32_bf16 v[74:77], v[172:175], v[220:223], v[74:77]
	v_mfma_f32_16x16x32_bf16 v[74:77], v[176:179], v[224:227], v[74:77]
	v_mfma_f32_16x16x32_bf16 v[90:93], v[176:179], v[216:219], v[90:93]
	v_mfma_f32_16x16x32_bf16 v[90:93], v[172:175], v[212:215], v[90:93]
	v_mfma_f32_16x16x32_bf16 v[106:109], v[172:175], v[204:207], v[106:109]
	v_mfma_f32_16x16x32_bf16 v[106:109], v[176:179], v[208:211], v[106:109]
	v_mfma_f32_16x16x32_bf16 v[122:125], v[176:179], v[200:203], v[122:125]
	v_mfma_f32_16x16x32_bf16 v[122:125], v[172:175], v[196:199], v[122:125]
	v_mfma_f32_16x16x32_bf16 v[118:121], v[180:183], v[196:199], v[118:121]
	v_mfma_f32_16x16x32_bf16 v[118:121], v[184:187], v[200:203], v[118:121]
	v_mfma_f32_16x16x32_bf16 v[102:105], v[184:187], v[208:211], v[102:105]
	v_mfma_f32_16x16x32_bf16 v[102:105], v[180:183], v[204:207], v[102:105]
	v_mfma_f32_16x16x32_bf16 v[86:89], v[180:183], v[212:215], v[86:89]
	v_mfma_f32_16x16x32_bf16 v[86:89], v[184:187], v[216:219], v[86:89]
	v_mfma_f32_16x16x32_bf16 v[70:73], v[184:187], v[224:227], v[70:73]
	v_mfma_f32_16x16x32_bf16 v[70:73], v[180:183], v[220:223], v[70:73]
	v_mfma_f32_16x16x32_bf16 v[66:69], v[188:191], v[220:223], v[66:69]
	v_mfma_f32_16x16x32_bf16 v[66:69], v[192:195], v[224:227], v[66:69]
	v_mfma_f32_16x16x32_bf16 v[82:85], v[192:195], v[216:219], v[82:85]
	v_mfma_f32_16x16x32_bf16 v[82:85], v[188:191], v[212:215], v[82:85]
	v_mfma_f32_16x16x32_bf16 v[98:101], v[188:191], v[204:207], v[98:101]
	v_mfma_f32_16x16x32_bf16 v[98:101], v[192:195], v[208:211], v[98:101]
	v_mfma_f32_16x16x32_bf16 v[114:117], v[192:195], v[200:203], v[114:117]
	v_mfma_f32_16x16x32_bf16 v[114:117], v[188:191], v[196:199], v[114:117]
	s_setprio 0
	s_barrier
	s_mov_b32 m0, s48
	s_add_u32 s64, s30, 0x2b0000
	global_load_lds_dwordx4 v132, s[30:31]
	s_mov_b32 m0, s49
	s_addc_u32 s65, s31, 0
	global_load_lds_dwordx4 v136, s[30:31]
	s_mov_b32 m0, s50
	ds_read_b128 v[196:199], v158 offset:16384
	global_load_lds_dwordx4 v132, s[64:65]
	s_mov_b32 m0, s51
	ds_read_b128 v[200:203], v158 offset:17408
	global_load_lds_dwordx4 v136, s[64:65]
	ds_read_b128 v[204:207], v158 offset:18432
	ds_read_b128 v[208:211], v158 offset:19456
	ds_read_b128 v[212:215], v158 offset:20480
	ds_read_b128 v[216:219], v158 offset:21504
	ds_read_b128 v[220:223], v158 offset:22528
	ds_read_b128 v[224:227], v158 offset:23552
	s_waitcnt vmcnt(6)
	s_waitcnt lgkmcnt(0)
	s_barrier
	s_setprio 1
	s_waitcnt lgkmcnt(0)
	v_mfma_f32_16x16x32_bf16 v[62:65], v[142:145], v[196:199], v[62:65]
	v_mfma_f32_16x16x32_bf16 v[62:65], v[168:171], v[200:203], v[62:65]
	v_mfma_f32_16x16x32_bf16 v[46:49], v[168:171], v[208:211], v[46:49]
	v_mfma_f32_16x16x32_bf16 v[46:49], v[142:145], v[204:207], v[46:49]
	v_mfma_f32_16x16x32_bf16 v[30:33], v[142:145], v[212:215], v[30:33]
	v_mfma_f32_16x16x32_bf16 v[30:33], v[168:171], v[216:219], v[30:33]
	v_mfma_f32_16x16x32_bf16 v[14:17], v[168:171], v[224:227], v[14:17]
	v_mfma_f32_16x16x32_bf16 v[14:17], v[142:145], v[220:223], v[14:17]
	v_mfma_f32_16x16x32_bf16 v[10:13], v[172:175], v[220:223], v[10:13]
	v_mfma_f32_16x16x32_bf16 v[10:13], v[176:179], v[224:227], v[10:13]
	v_mfma_f32_16x16x32_bf16 v[26:29], v[176:179], v[216:219], v[26:29]
	v_mfma_f32_16x16x32_bf16 v[26:29], v[172:175], v[212:215], v[26:29]
	v_mfma_f32_16x16x32_bf16 v[42:45], v[172:175], v[204:207], v[42:45]
	v_mfma_f32_16x16x32_bf16 v[42:45], v[176:179], v[208:211], v[42:45]
	v_mfma_f32_16x16x32_bf16 v[58:61], v[176:179], v[200:203], v[58:61]
	v_mfma_f32_16x16x32_bf16 v[58:61], v[172:175], v[196:199], v[58:61]
	v_mfma_f32_16x16x32_bf16 v[54:57], v[180:183], v[196:199], v[54:57]
	v_mfma_f32_16x16x32_bf16 v[54:57], v[184:187], v[200:203], v[54:57]
	v_mfma_f32_16x16x32_bf16 v[38:41], v[184:187], v[208:211], v[38:41]
	v_mfma_f32_16x16x32_bf16 v[38:41], v[180:183], v[204:207], v[38:41]
	v_mfma_f32_16x16x32_bf16 v[22:25], v[180:183], v[212:215], v[22:25]
	v_mfma_f32_16x16x32_bf16 v[22:25], v[184:187], v[216:219], v[22:25]
	v_mfma_f32_16x16x32_bf16 v[6:9], v[184:187], v[224:227], v[6:9]
	v_mfma_f32_16x16x32_bf16 v[6:9], v[180:183], v[220:223], v[6:9]
	v_mfma_f32_16x16x32_bf16 v[2:5], v[188:191], v[220:223], v[2:5]
	v_mfma_f32_16x16x32_bf16 v[2:5], v[192:195], v[224:227], v[2:5]
	v_mfma_f32_16x16x32_bf16 v[18:21], v[192:195], v[216:219], v[18:21]
	v_mfma_f32_16x16x32_bf16 v[18:21], v[188:191], v[212:215], v[18:21]
	v_mfma_f32_16x16x32_bf16 v[34:37], v[188:191], v[204:207], v[34:37]
	v_mfma_f32_16x16x32_bf16 v[34:37], v[192:195], v[208:211], v[34:37]
	v_mfma_f32_16x16x32_bf16 v[50:53], v[192:195], v[200:203], v[50:53]
	v_mfma_f32_16x16x32_bf16 v[50:53], v[188:191], v[196:199], v[50:53]
	s_setprio 0
	s_barrier
	s_mov_b32 m0, s39
	ds_read_b128 v[142:145], v159
	global_load_lds_dwordx4 v130, s[34:35]
	s_mov_b32 m0, s40
	ds_read_b128 v[168:171], v159 offset:1024
	global_load_lds_dwordx4 v134, s[34:35]
	s_add_u32 s34, s34, 0x2b0000
	s_addc_u32 s35, s35, 0
	s_mov_b32 m0, s41
	ds_read_b128 v[172:175], v159 offset:2048
	global_load_lds_dwordx4 v130, s[34:35]
	s_mov_b32 m0, s42
	ds_read_b128 v[176:179], v159 offset:3072
	global_load_lds_dwordx4 v134, s[34:35]
	ds_read_b128 v[180:183], v160
	ds_read_b128 v[184:187], v160 offset:1024
	ds_read_b128 v[188:191], v160 offset:2048
	ds_read_b128 v[192:195], v160 offset:3072
	ds_read_b128 v[196:199], v158 offset:32768
	ds_read_b128 v[200:203], v158 offset:33792
	ds_read_b128 v[204:207], v158 offset:34816
	ds_read_b128 v[208:211], v158 offset:35840
	ds_read_b128 v[212:215], v158 offset:36864
	ds_read_b128 v[216:219], v158 offset:37888
	ds_read_b128 v[220:223], v158 offset:38912
	ds_read_b128 v[224:227], v158 offset:39936
	s_waitcnt vmcnt(8)
	s_waitcnt lgkmcnt(0)
	s_barrier
	s_setprio 1
	s_waitcnt lgkmcnt(0)
	v_mfma_f32_16x16x32_bf16 v[126:129], v[142:145], v[196:199], v[126:129]
	v_mfma_f32_16x16x32_bf16 v[126:129], v[168:171], v[200:203], v[126:129]
	v_mfma_f32_16x16x32_bf16 v[110:113], v[168:171], v[208:211], v[110:113]
	v_mfma_f32_16x16x32_bf16 v[110:113], v[142:145], v[204:207], v[110:113]
	v_mfma_f32_16x16x32_bf16 v[94:97], v[142:145], v[212:215], v[94:97]
	v_mfma_f32_16x16x32_bf16 v[94:97], v[168:171], v[216:219], v[94:97]
	v_mfma_f32_16x16x32_bf16 v[78:81], v[168:171], v[224:227], v[78:81]
	v_mfma_f32_16x16x32_bf16 v[78:81], v[142:145], v[220:223], v[78:81]
	v_mfma_f32_16x16x32_bf16 v[74:77], v[172:175], v[220:223], v[74:77]
	v_mfma_f32_16x16x32_bf16 v[74:77], v[176:179], v[224:227], v[74:77]
	v_mfma_f32_16x16x32_bf16 v[90:93], v[176:179], v[216:219], v[90:93]
	v_mfma_f32_16x16x32_bf16 v[90:93], v[172:175], v[212:215], v[90:93]
	v_mfma_f32_16x16x32_bf16 v[106:109], v[172:175], v[204:207], v[106:109]
	v_mfma_f32_16x16x32_bf16 v[106:109], v[176:179], v[208:211], v[106:109]
	v_mfma_f32_16x16x32_bf16 v[122:125], v[176:179], v[200:203], v[122:125]
	v_mfma_f32_16x16x32_bf16 v[122:125], v[172:175], v[196:199], v[122:125]
	v_mfma_f32_16x16x32_bf16 v[118:121], v[180:183], v[196:199], v[118:121]
	v_mfma_f32_16x16x32_bf16 v[118:121], v[184:187], v[200:203], v[118:121]
	v_mfma_f32_16x16x32_bf16 v[102:105], v[184:187], v[208:211], v[102:105]
	v_mfma_f32_16x16x32_bf16 v[102:105], v[180:183], v[204:207], v[102:105]
	v_mfma_f32_16x16x32_bf16 v[86:89], v[180:183], v[212:215], v[86:89]
	v_mfma_f32_16x16x32_bf16 v[86:89], v[184:187], v[216:219], v[86:89]
	v_mfma_f32_16x16x32_bf16 v[70:73], v[184:187], v[224:227], v[70:73]
	v_mfma_f32_16x16x32_bf16 v[70:73], v[180:183], v[220:223], v[70:73]
	v_mfma_f32_16x16x32_bf16 v[66:69], v[188:191], v[220:223], v[66:69]
	v_mfma_f32_16x16x32_bf16 v[66:69], v[192:195], v[224:227], v[66:69]
	v_mfma_f32_16x16x32_bf16 v[82:85], v[192:195], v[216:219], v[82:85]
	v_mfma_f32_16x16x32_bf16 v[82:85], v[188:191], v[212:215], v[82:85]
	v_mfma_f32_16x16x32_bf16 v[98:101], v[188:191], v[204:207], v[98:101]
	v_mfma_f32_16x16x32_bf16 v[98:101], v[192:195], v[208:211], v[98:101]
	v_mfma_f32_16x16x32_bf16 v[114:117], v[192:195], v[200:203], v[114:117]
	v_mfma_f32_16x16x32_bf16 v[114:117], v[188:191], v[196:199], v[114:117]
	s_setprio 0
	s_barrier
	s_mov_b32 m0, s52
	s_add_u32 s30, s30, 0x80
	s_addc_u32 s31, s31, 0
	global_load_lds_dwordx4 v132, s[30:31]
	s_mov_b32 m0, s53
	ds_read_b128 v[196:199], v158 offset:49152
	global_load_lds_dwordx4 v136, s[30:31]
	s_mov_b32 m0, s54
	s_add_u32 s30, s30, 0x2b0000
	s_addc_u32 s31, s31, 0
	global_load_lds_dwordx4 v132, s[30:31]
	s_mov_b32 m0, s55
	ds_read_b128 v[200:203], v158 offset:50176
	global_load_lds_dwordx4 v136, s[30:31]
	ds_read_b128 v[204:207], v158 offset:51200
	ds_read_b128 v[208:211], v158 offset:52224
	ds_read_b128 v[212:215], v158 offset:53248
	ds_read_b128 v[216:219], v158 offset:54272
	ds_read_b128 v[220:223], v158 offset:55296
	ds_read_b128 v[224:227], v158 offset:56320
	s_waitcnt vmcnt(6)
	s_waitcnt lgkmcnt(0)
	s_barrier
	s_setprio 1
	s_waitcnt lgkmcnt(0)
	v_mfma_f32_16x16x32_bf16 v[62:65], v[142:145], v[196:199], v[62:65]
	v_mfma_f32_16x16x32_bf16 v[62:65], v[168:171], v[200:203], v[62:65]
	v_mfma_f32_16x16x32_bf16 v[46:49], v[168:171], v[208:211], v[46:49]
	v_mfma_f32_16x16x32_bf16 v[46:49], v[142:145], v[204:207], v[46:49]
	v_mfma_f32_16x16x32_bf16 v[30:33], v[142:145], v[212:215], v[30:33]
	v_mfma_f32_16x16x32_bf16 v[30:33], v[168:171], v[216:219], v[30:33]
	v_mfma_f32_16x16x32_bf16 v[14:17], v[168:171], v[224:227], v[14:17]
	v_mfma_f32_16x16x32_bf16 v[14:17], v[142:145], v[220:223], v[14:17]
	v_mfma_f32_16x16x32_bf16 v[10:13], v[172:175], v[220:223], v[10:13]
	v_mfma_f32_16x16x32_bf16 v[10:13], v[176:179], v[224:227], v[10:13]
	v_mfma_f32_16x16x32_bf16 v[26:29], v[176:179], v[216:219], v[26:29]
	v_mfma_f32_16x16x32_bf16 v[26:29], v[172:175], v[212:215], v[26:29]
	v_mfma_f32_16x16x32_bf16 v[42:45], v[172:175], v[204:207], v[42:45]
	v_mfma_f32_16x16x32_bf16 v[42:45], v[176:179], v[208:211], v[42:45]
	v_mfma_f32_16x16x32_bf16 v[58:61], v[176:179], v[200:203], v[58:61]
	v_mfma_f32_16x16x32_bf16 v[58:61], v[172:175], v[196:199], v[58:61]
	v_mfma_f32_16x16x32_bf16 v[54:57], v[180:183], v[196:199], v[54:57]
	v_mfma_f32_16x16x32_bf16 v[54:57], v[184:187], v[200:203], v[54:57]
	v_mfma_f32_16x16x32_bf16 v[38:41], v[184:187], v[208:211], v[38:41]
	v_mfma_f32_16x16x32_bf16 v[38:41], v[180:183], v[204:207], v[38:41]
	v_mfma_f32_16x16x32_bf16 v[22:25], v[180:183], v[212:215], v[22:25]
	v_mfma_f32_16x16x32_bf16 v[22:25], v[184:187], v[216:219], v[22:25]
	v_mfma_f32_16x16x32_bf16 v[6:9], v[184:187], v[224:227], v[6:9]
	v_mfma_f32_16x16x32_bf16 v[6:9], v[180:183], v[220:223], v[6:9]
	v_mfma_f32_16x16x32_bf16 v[2:5], v[188:191], v[220:223], v[2:5]
	v_mfma_f32_16x16x32_bf16 v[2:5], v[192:195], v[224:227], v[2:5]
	v_mfma_f32_16x16x32_bf16 v[18:21], v[192:195], v[216:219], v[18:21]
	v_mfma_f32_16x16x32_bf16 v[18:21], v[188:191], v[212:215], v[18:21]
	v_mfma_f32_16x16x32_bf16 v[34:37], v[188:191], v[204:207], v[34:37]
	v_mfma_f32_16x16x32_bf16 v[34:37], v[192:195], v[208:211], v[34:37]
	v_mfma_f32_16x16x32_bf16 v[50:53], v[192:195], v[200:203], v[50:53]
	v_mfma_f32_16x16x32_bf16 v[50:53], v[188:191], v[196:199], v[50:53]
	s_setprio 0
	s_barrier
	s_add_i32 s62, s62, 2
	s_add_u32 s28, s28, 0x100
	s_addc_u32 s29, s29, 0
	s_add_u32 s60, s60, 0x100
	s_addc_u32 s61, s61, 0
	s_cmpk_gt_u32 s62, 0xa9
	s_cbranch_scc0 .LBB0_2618
	s_and_b64 vcc, exec, s[12:13]
	s_cbranch_vccz .LBB0_2621
	s_barrier

.LBB0_2632:
	ds_read_b128 v[150:153], v1
	ds_read_b128 v[154:157], v1 offset:1024
	ds_read_b128 v[158:161], v1 offset:2048
	ds_read_b128 v[166:169], v1 offset:3072
	ds_read_b128 v[170:173], v139
	ds_read_b128 v[174:177], v139 offset:1024
	ds_read_b128 v[178:181], v139 offset:2048
	ds_read_b128 v[182:185], v139 offset:3072
	s_add_i32 s38, s13, 2
	s_add_u32 s12, s10, 0xc2050080
	s_addc_u32 s14, s11, -1
	s_cmp_lg_u32 s26, s13
	s_cselect_b32 s12, s12, 0
	s_cselect_b32 s13, s14, 0
	s_add_u32 s14, s4, s12
	s_addc_u32 s15, s5, s13
	s_add_u32 s12, s6, s12
	s_addc_u32 s13, s7, s13
	s_mov_b32 m0, s27
	v_lshl_add_u64 v[162:163], v[140:141], 0, s[10:11]
	ds_read_b128 v[186:189], v144
	ds_read_b128 v[190:193], v144 offset:1024
	ds_read_b128 v[194:197], v144 offset:2048
	ds_read_b128 v[198:201], v144 offset:3072
	ds_read_b128 v[202:205], v144 offset:4096
	ds_read_b128 v[206:209], v144 offset:5120
	ds_read_b128 v[210:213], v144 offset:6144
	ds_read_b128 v[214:217], v144 offset:7168
	global_load_lds_dwordx4 v[162:163], off
	v_lshl_add_u64 v[162:163], v[142:143], 0, s[10:11]
	s_mov_b32 m0, s28
	s_nop 0
	global_load_lds_dwordx4 v[162:163], off
	s_waitcnt vmcnt(8)
	s_waitcnt lgkmcnt(0)
	s_barrier
	s_setprio 1
	s_waitcnt lgkmcnt(0)
	v_mfma_f32_16x16x32_bf16 v[126:129], v[150:153], v[186:189], v[126:129]
	v_mfma_f32_16x16x32_bf16 v[126:129], v[154:157], v[190:193], v[126:129]
	v_mfma_f32_16x16x32_bf16 v[118:121], v[154:157], v[198:201], v[118:121]
	v_mfma_f32_16x16x32_bf16 v[118:121], v[150:153], v[194:197], v[118:121]
	v_mfma_f32_16x16x32_bf16 v[102:105], v[150:153], v[202:205], v[102:105]
	v_mfma_f32_16x16x32_bf16 v[102:105], v[154:157], v[206:209], v[102:105]
	v_mfma_f32_16x16x32_bf16 v[86:89], v[154:157], v[214:217], v[86:89]
	v_mfma_f32_16x16x32_bf16 v[86:89], v[150:153], v[210:213], v[86:89]
	v_mfma_f32_16x16x32_bf16 v[82:85], v[158:161], v[210:213], v[82:85]
	v_mfma_f32_16x16x32_bf16 v[82:85], v[166:169], v[214:217], v[82:85]
	v_mfma_f32_16x16x32_bf16 v[98:101], v[166:169], v[206:209], v[98:101]
	v_mfma_f32_16x16x32_bf16 v[98:101], v[158:161], v[202:205], v[98:101]
	v_mfma_f32_16x16x32_bf16 v[114:117], v[158:161], v[194:197], v[114:117]
	v_mfma_f32_16x16x32_bf16 v[114:117], v[166:169], v[198:201], v[114:117]
	v_mfma_f32_16x16x32_bf16 v[122:125], v[166:169], v[190:193], v[122:125]
	v_mfma_f32_16x16x32_bf16 v[122:125], v[158:161], v[186:189], v[122:125]
	v_mfma_f32_16x16x32_bf16 v[110:113], v[170:173], v[186:189], v[110:113]
	v_mfma_f32_16x16x32_bf16 v[110:113], v[174:177], v[190:193], v[110:113]
	v_mfma_f32_16x16x32_bf16 v[94:97], v[174:177], v[198:201], v[94:97]
	v_mfma_f32_16x16x32_bf16 v[94:97], v[170:173], v[194:197], v[94:97]
	v_mfma_f32_16x16x32_bf16 v[78:81], v[170:173], v[202:205], v[78:81]
	v_mfma_f32_16x16x32_bf16 v[78:81], v[174:177], v[206:209], v[78:81]
	v_mfma_f32_16x16x32_bf16 v[70:73], v[174:177], v[214:217], v[70:73]
	v_mfma_f32_16x16x32_bf16 v[70:73], v[170:173], v[210:213], v[70:73]
	v_mfma_f32_16x16x32_bf16 v[66:69], v[178:181], v[210:213], v[66:69]
	v_mfma_f32_16x16x32_bf16 v[66:69], v[182:185], v[214:217], v[66:69]
	v_mfma_f32_16x16x32_bf16 v[74:77], v[182:185], v[206:209], v[74:77]
	v_mfma_f32_16x16x32_bf16 v[74:77], v[178:181], v[202:205], v[74:77]
	v_mfma_f32_16x16x32_bf16 v[90:93], v[178:181], v[194:197], v[90:93]
	v_mfma_f32_16x16x32_bf16 v[90:93], v[182:185], v[198:201], v[90:93]
	v_mfma_f32_16x16x32_bf16 v[106:109], v[182:185], v[190:193], v[106:109]
	v_mfma_f32_16x16x32_bf16 v[106:109], v[178:181], v[186:189], v[106:109]
	s_setprio 0
	s_barrier
	s_mov_b32 m0, s29
	v_lshl_add_u64 v[162:163], s[12:13], 0, v[132:133]
	s_add_u32 s40, s12, 0x2b0000
	ds_read_b128 v[186:189], v144 offset:16384
	ds_read_b128 v[190:193], v144 offset:17408
	ds_read_b128 v[194:197], v144 offset:18432
	ds_read_b128 v[198:201], v144 offset:19456
	ds_read_b128 v[202:205], v144 offset:20480
	ds_read_b128 v[206:209], v144 offset:21504
	ds_read_b128 v[210:213], v144 offset:22528
	ds_read_b128 v[214:217], v144 offset:23552
	global_load_lds_dwordx4 v[162:163], off
	v_lshl_add_u64 v[218:219], s[12:13], 0, v[136:137]
	s_mov_b32 m0, s30
	s_addc_u32 s41, s13, 0
	global_load_lds_dwordx4 v[218:219], off
	v_lshl_add_u64 v[220:221], s[40:41], 0, v[132:133]
	s_mov_b32 m0, s31
	v_lshl_add_u64 v[222:223], s[14:15], 0, v[134:135]
	global_load_lds_dwordx4 v[220:221], off
	v_lshl_add_u64 v[220:221], s[40:41], 0, v[136:137]
	s_mov_b32 m0, s33
	s_nop 0
	global_load_lds_dwordx4 v[220:221], off
	v_lshl_add_u64 v[220:221], s[14:15], 0, v[130:131]
	s_mov_b32 m0, s19
	s_nop 0
	global_load_lds_dwordx4 v[220:221], off
	s_mov_b32 m0, s20
	s_nop 0
	global_load_lds_dwordx4 v[222:223], off
	s_waitcnt vmcnt(8)
	s_waitcnt lgkmcnt(0)
	s_barrier
	s_setprio 1
	s_waitcnt lgkmcnt(0)
	v_mfma_f32_16x16x32_bf16 v[62:65], v[150:153], v[186:189], v[62:65]
	v_mfma_f32_16x16x32_bf16 v[62:65], v[154:157], v[190:193], v[62:65]
	v_mfma_f32_16x16x32_bf16 v[54:57], v[154:157], v[198:201], v[54:57]
	v_mfma_f32_16x16x32_bf16 v[54:57], v[150:153], v[194:197], v[54:57]
	v_mfma_f32_16x16x32_bf16 v[38:41], v[150:153], v[202:205], v[38:41]
	v_mfma_f32_16x16x32_bf16 v[38:41], v[154:157], v[206:209], v[38:41]
	v_mfma_f32_16x16x32_bf16 v[22:25], v[154:157], v[214:217], v[22:25]
	v_mfma_f32_16x16x32_bf16 v[22:25], v[150:153], v[210:213], v[22:25]
	v_mfma_f32_16x16x32_bf16 v[18:21], v[158:161], v[210:213], v[18:21]
	v_mfma_f32_16x16x32_bf16 v[18:21], v[166:169], v[214:217], v[18:21]
	v_mfma_f32_16x16x32_bf16 v[34:37], v[166:169], v[206:209], v[34:37]
	v_mfma_f32_16x16x32_bf16 v[34:37], v[158:161], v[202:205], v[34:37]
	v_mfma_f32_16x16x32_bf16 v[50:53], v[158:161], v[194:197], v[50:53]
	v_mfma_f32_16x16x32_bf16 v[50:53], v[166:169], v[198:201], v[50:53]
	v_mfma_f32_16x16x32_bf16 v[58:61], v[166:169], v[190:193], v[58:61]
	v_mfma_f32_16x16x32_bf16 v[58:61], v[158:161], v[186:189], v[58:61]
	v_mfma_f32_16x16x32_bf16 v[46:49], v[170:173], v[186:189], v[46:49]
	v_mfma_f32_16x16x32_bf16 v[46:49], v[174:177], v[190:193], v[46:49]
	v_mfma_f32_16x16x32_bf16 v[30:33], v[174:177], v[198:201], v[30:33]
	v_mfma_f32_16x16x32_bf16 v[30:33], v[170:173], v[194:197], v[30:33]
	v_mfma_f32_16x16x32_bf16 v[14:17], v[170:173], v[202:205], v[14:17]
	v_mfma_f32_16x16x32_bf16 v[14:17], v[174:177], v[206:209], v[14:17]
	v_mfma_f32_16x16x32_bf16 v[6:9], v[174:177], v[214:217], v[6:9]
	v_mfma_f32_16x16x32_bf16 v[6:9], v[170:173], v[210:213], v[6:9]
	v_mfma_f32_16x16x32_bf16 v[2:5], v[178:181], v[210:213], v[2:5]
	v_mfma_f32_16x16x32_bf16 v[2:5], v[182:185], v[214:217], v[2:5]
	v_mfma_f32_16x16x32_bf16 v[10:13], v[182:185], v[206:209], v[10:13]
	v_mfma_f32_16x16x32_bf16 v[10:13], v[178:181], v[202:205], v[10:13]
	v_mfma_f32_16x16x32_bf16 v[26:29], v[178:181], v[194:197], v[26:29]
	v_mfma_f32_16x16x32_bf16 v[26:29], v[182:185], v[198:201], v[26:29]
	v_mfma_f32_16x16x32_bf16 v[42:45], v[182:185], v[190:193], v[42:45]
	v_mfma_f32_16x16x32_bf16 v[42:45], v[178:181], v[186:189], v[42:45]
	s_setprio 0
	s_barrier
	ds_read_b128 v[150:153], v145
	ds_read_b128 v[154:157], v145 offset:1024
	ds_read_b128 v[158:161], v145 offset:2048
	ds_read_b128 v[166:169], v145 offset:3072
	ds_read_b128 v[170:173], v146
	ds_read_b128 v[174:177], v146 offset:1024
	ds_read_b128 v[178:181], v146 offset:2048
	ds_read_b128 v[182:185], v146 offset:3072
	s_add_u32 s14, s14, 0x2b0000
	s_addc_u32 s15, s15, 0
	s_mov_b32 m0, s21
	v_lshl_add_u64 v[224:225], s[14:15], 0, v[130:131]
	ds_read_b128 v[186:189], v144 offset:32768
	ds_read_b128 v[190:193], v144 offset:33792
	ds_read_b128 v[194:197], v144 offset:34816
	ds_read_b128 v[198:201], v144 offset:35840
	ds_read_b128 v[202:205], v144 offset:36864
	ds_read_b128 v[206:209], v144 offset:37888
	ds_read_b128 v[210:213], v144 offset:38912
	ds_read_b128 v[214:217], v144 offset:39936
	global_load_lds_dwordx4 v[224:225], off
	v_lshl_add_u64 v[224:225], s[14:15], 0, v[134:135]
	s_mov_b32 m0, s22
	s_nop 0
	global_load_lds_dwordx4 v[224:225], off
	s_waitcnt vmcnt(8)
	s_waitcnt lgkmcnt(0)
	s_barrier
	s_setprio 1
	s_waitcnt lgkmcnt(0)
	v_mfma_f32_16x16x32_bf16 v[126:129], v[150:153], v[186:189], v[126:129]
	v_mfma_f32_16x16x32_bf16 v[126:129], v[154:157], v[190:193], v[126:129]
	v_mfma_f32_16x16x32_bf16 v[118:121], v[154:157], v[198:201], v[118:121]
	v_mfma_f32_16x16x32_bf16 v[118:121], v[150:153], v[194:197], v[118:121]
	v_mfma_f32_16x16x32_bf16 v[102:105], v[150:153], v[202:205], v[102:105]
	v_mfma_f32_16x16x32_bf16 v[102:105], v[154:157], v[206:209], v[102:105]
	v_mfma_f32_16x16x32_bf16 v[86:89], v[154:157], v[214:217], v[86:89]
	v_mfma_f32_16x16x32_bf16 v[86:89], v[150:153], v[210:213], v[86:89]
	v_mfma_f32_16x16x32_bf16 v[82:85], v[158:161], v[210:213], v[82:85]
	v_mfma_f32_16x16x32_bf16 v[82:85], v[166:169], v[214:217], v[82:85]
	v_mfma_f32_16x16x32_bf16 v[98:101], v[166:169], v[206:209], v[98:101]
	v_mfma_f32_16x16x32_bf16 v[98:101], v[158:161], v[202:205], v[98:101]
	v_mfma_f32_16x16x32_bf16 v[114:117], v[158:161], v[194:197], v[114:117]
	v_mfma_f32_16x16x32_bf16 v[114:117], v[166:169], v[198:201], v[114:117]
	v_mfma_f32_16x16x32_bf16 v[122:125], v[166:169], v[190:193], v[122:125]
	v_mfma_f32_16x16x32_bf16 v[122:125], v[158:161], v[186:189], v[122:125]
	v_mfma_f32_16x16x32_bf16 v[110:113], v[170:173], v[186:189], v[110:113]
	v_mfma_f32_16x16x32_bf16 v[110:113], v[174:177], v[190:193], v[110:113]
	v_mfma_f32_16x16x32_bf16 v[94:97], v[174:177], v[198:201], v[94:97]
	v_mfma_f32_16x16x32_bf16 v[94:97], v[170:173], v[194:197], v[94:97]
	v_mfma_f32_16x16x32_bf16 v[78:81], v[170:173], v[202:205], v[78:81]
	v_mfma_f32_16x16x32_bf16 v[78:81], v[174:177], v[206:209], v[78:81]
	v_mfma_f32_16x16x32_bf16 v[70:73], v[174:177], v[214:217], v[70:73]
	v_mfma_f32_16x16x32_bf16 v[70:73], v[170:173], v[210:213], v[70:73]
	v_mfma_f32_16x16x32_bf16 v[66:69], v[178:181], v[210:213], v[66:69]
	v_mfma_f32_16x16x32_bf16 v[66:69], v[182:185], v[214:217], v[66:69]
	v_mfma_f32_16x16x32_bf16 v[74:77], v[182:185], v[206:209], v[74:77]
	v_mfma_f32_16x16x32_bf16 v[74:77], v[178:181], v[202:205], v[74:77]
	v_mfma_f32_16x16x32_bf16 v[90:93], v[178:181], v[194:197], v[90:93]
	v_mfma_f32_16x16x32_bf16 v[90:93], v[182:185], v[198:201], v[90:93]
	v_mfma_f32_16x16x32_bf16 v[106:109], v[182:185], v[190:193], v[106:109]
	v_mfma_f32_16x16x32_bf16 v[106:109], v[178:181], v[186:189], v[106:109]
	s_setprio 0
	s_barrier
	s_mov_b32 m0, s34
	v_lshl_add_u64 v[162:163], v[162:163], 0, s[8:9]
	s_add_u32 s12, s12, 0x2b0080
	ds_read_b128 v[186:189], v144 offset:49152
	ds_read_b128 v[190:193], v144 offset:50176
	ds_read_b128 v[194:197], v144 offset:51200
	ds_read_b128 v[198:201], v144 offset:52224
	ds_read_b128 v[202:205], v144 offset:53248
	ds_read_b128 v[206:209], v144 offset:54272
	ds_read_b128 v[210:213], v144 offset:55296
	ds_read_b128 v[214:217], v144 offset:56320
	global_load_lds_dwordx4 v[162:163], off
	v_lshl_add_u64 v[162:163], v[218:219], 0, s[8:9]
	s_mov_b32 m0, s35
	s_addc_u32 s13, s13, 0
	global_load_lds_dwordx4 v[162:163], off
	v_lshl_add_u64 v[162:163], s[12:13], 0, v[132:133]
	s_mov_b32 m0, s36
	s_nop 0
	global_load_lds_dwordx4 v[162:163], off
	v_lshl_add_u64 v[162:163], s[12:13], 0, v[136:137]
	s_mov_b32 m0, s37
	s_nop 0
	global_load_lds_dwordx4 v[162:163], off
	v_lshl_add_u64 v[162:163], v[220:221], 0, s[8:9]
	s_mov_b32 m0, s24
	s_nop 0
	global_load_lds_dwordx4 v[162:163], off
	v_lshl_add_u64 v[162:163], v[222:223], 0, s[8:9]
	s_mov_b32 m0, s25
	s_nop 0
	global_load_lds_dwordx4 v[162:163], off
	s_waitcnt vmcnt(8)
	s_waitcnt lgkmcnt(0)
	s_barrier
	s_setprio 1
	s_waitcnt lgkmcnt(0)
	v_mfma_f32_16x16x32_bf16 v[62:65], v[150:153], v[186:189], v[62:65]
	v_mfma_f32_16x16x32_bf16 v[62:65], v[154:157], v[190:193], v[62:65]
	v_mfma_f32_16x16x32_bf16 v[54:57], v[154:157], v[198:201], v[54:57]
	v_mfma_f32_16x16x32_bf16 v[54:57], v[150:153], v[194:197], v[54:57]
	v_mfma_f32_16x16x32_bf16 v[38:41], v[150:153], v[202:205], v[38:41]
	v_mfma_f32_16x16x32_bf16 v[38:41], v[154:157], v[206:209], v[38:41]
	v_mfma_f32_16x16x32_bf16 v[22:25], v[154:157], v[214:217], v[22:25]
	v_mfma_f32_16x16x32_bf16 v[22:25], v[150:153], v[210:213], v[22:25]
	v_mfma_f32_16x16x32_bf16 v[18:21], v[158:161], v[210:213], v[18:21]
	v_mfma_f32_16x16x32_bf16 v[18:21], v[166:169], v[214:217], v[18:21]
	v_mfma_f32_16x16x32_bf16 v[34:37], v[166:169], v[206:209], v[34:37]
	v_mfma_f32_16x16x32_bf16 v[34:37], v[158:161], v[202:205], v[34:37]
	v_mfma_f32_16x16x32_bf16 v[50:53], v[158:161], v[194:197], v[50:53]
	v_mfma_f32_16x16x32_bf16 v[50:53], v[166:169], v[198:201], v[50:53]
	v_mfma_f32_16x16x32_bf16 v[58:61], v[166:169], v[190:193], v[58:61]
	v_mfma_f32_16x16x32_bf16 v[58:61], v[158:161], v[186:189], v[58:61]
	v_mfma_f32_16x16x32_bf16 v[46:49], v[170:173], v[186:189], v[46:49]
	v_mfma_f32_16x16x32_bf16 v[46:49], v[174:177], v[190:193], v[46:49]
	v_mfma_f32_16x16x32_bf16 v[30:33], v[174:177], v[198:201], v[30:33]
	v_mfma_f32_16x16x32_bf16 v[30:33], v[170:173], v[194:197], v[30:33]
	v_mfma_f32_16x16x32_bf16 v[14:17], v[170:173], v[202:205], v[14:17]
	v_mfma_f32_16x16x32_bf16 v[14:17], v[174:177], v[206:209], v[14:17]
	v_mfma_f32_16x16x32_bf16 v[6:9], v[174:177], v[214:217], v[6:9]
	v_mfma_f32_16x16x32_bf16 v[6:9], v[170:173], v[210:213], v[6:9]
	v_mfma_f32_16x16x32_bf16 v[2:5], v[178:181], v[210:213], v[2:5]
	v_mfma_f32_16x16x32_bf16 v[2:5], v[182:185], v[214:217], v[2:5]
	v_mfma_f32_16x16x32_bf16 v[10:13], v[182:185], v[206:209], v[10:13]
	v_mfma_f32_16x16x32_bf16 v[10:13], v[178:181], v[202:205], v[10:13]
	v_mfma_f32_16x16x32_bf16 v[26:29], v[178:181], v[194:197], v[26:29]
	v_mfma_f32_16x16x32_bf16 v[26:29], v[182:185], v[198:201], v[26:29]
	v_mfma_f32_16x16x32_bf16 v[42:45], v[182:185], v[190:193], v[42:45]
	v_mfma_f32_16x16x32_bf16 v[42:45], v[178:181], v[186:189], v[42:45]
	s_setprio 0
	s_barrier
	s_add_u32 s10, s10, 0x100
	s_addc_u32 s11, s11, 0
	s_cmp_ge_u32 s38, s17
	s_mov_b32 s13, s38
	s_cbranch_scc0 .LBB0_2632
	s_lshl_b32 s4, s16, 21
	v_readlane_b32 s2, v249, 29
	v_lshl_or_b32 v1, s18, 8, v148
	v_mov_b32_e32 v139, 0
	s_add_u32 s4, s2, s4
	v_readlane_b32 s2, v249, 31
	v_or_b32_e32 v130, s23, v1
	v_cvt_pk_bf16_f32 v70, v70, v71
	v_cvt_pk_bf16_f32 v71, v72, v73
	v_cvt_pk_bf16_f32 v72, v66, v67
	v_add_u32_e32 v66, 0x80, v138
	v_mov_b32_e32 v67, v139
	s_addc_u32 s5, s2, 0
	v_ashrrev_i32_e32 v131, 31, v130
	v_lshlrev_b64 v[132:133], 13, v[138:139]
	v_cvt_pk_bf16_f32 v110, v110, v111
	v_cvt_pk_bf16_f32 v111, v112, v113
	v_cvt_pk_bf16_f32 v112, v106, v107
	v_or_b32_e32 v106, 16, v138
	v_mov_b32_e32 v107, v139
	v_lshlrev_b64 v[66:67], 13, v[66:67]
	v_cvt_pk_bf16_f32 v46, v46, v47
	v_cvt_pk_bf16_f32 v47, v48, v49
	v_cvt_pk_bf16_f32 v48, v42, v43
	v_add_u32_e32 v42, 0x90, v138
	v_mov_b32_e32 v43, v139
	v_lshl_add_u64 v[132:133], s[4:5], 0, v[132:133]
	v_lshlrev_b64 v[130:131], 1, v[130:131]
	v_lshlrev_b64 v[106:107], 13, v[106:107]
	v_cvt_pk_bf16_f32 v94, v94, v95
	v_cvt_pk_bf16_f32 v95, v96, v97
	v_cvt_pk_bf16_f32 v96, v90, v91
	v_or_b32_e32 v90, 32, v138
	v_mov_b32_e32 v91, v139
	v_lshl_add_u64 v[66:67], s[4:5], 0, v[66:67]
	v_lshlrev_b64 v[42:43], 13, v[42:43]
	v_cvt_pk_bf16_f32 v30, v30, v31
	v_cvt_pk_bf16_f32 v31, v32, v33
	v_cvt_pk_bf16_f32 v32, v26, v27
	v_add_u32_e32 v26, 0xa0, v138
	v_mov_b32_e32 v27, v139
	v_lshl_add_u64 v[132:133], v[132:133], 0, v[130:131]
	v_cvt_pk_bf16_f32 v113, v108, v109
	v_lshl_add_u64 v[106:107], s[4:5], 0, v[106:107]
	v_lshlrev_b64 v[90:91], 13, v[90:91]
	v_cvt_pk_bf16_f32 v78, v78, v79
	v_cvt_pk_bf16_f32 v79, v80, v81
	v_cvt_pk_bf16_f32 v80, v74, v75
	v_or_b32_e32 v74, 48, v138
	v_mov_b32_e32 v75, v139
	v_lshl_add_u64 v[66:67], v[66:67], 0, v[130:131]
	v_cvt_pk_bf16_f32 v49, v44, v45
	v_lshl_add_u64 v[42:43], s[4:5], 0, v[42:43]
	v_lshlrev_b64 v[26:27], 13, v[26:27]
	v_add_u32_e32 v138, 0xb0, v138
	global_store_dwordx4 v[132:133], v[110:113], off offset:256
	v_cvt_pk_bf16_f32 v97, v92, v93
	v_lshl_add_u64 v[90:91], s[4:5], 0, v[90:91]
	v_lshl_add_u64 v[110:111], v[106:107], 0, v[130:131]
	v_lshlrev_b64 v[74:75], 13, v[74:75]
	global_store_dwordx4 v[66:67], v[46:49], off offset:256
	v_cvt_pk_bf16_f32 v33, v28, v29
	v_lshl_add_u64 v[26:27], s[4:5], 0, v[26:27]
	v_lshl_add_u64 v[46:47], v[42:43], 0, v[130:131]
	v_cvt_pk_bf16_f32 v14, v14, v15
	v_cvt_pk_bf16_f32 v15, v16, v17
	v_cvt_pk_bf16_f32 v16, v10, v11
	v_lshlrev_b64 v[10:11], 13, v[138:139]
	global_store_dwordx4 v[110:111], v[94:97], off offset:256
	v_cvt_pk_bf16_f32 v81, v76, v77
	v_lshl_add_u64 v[74:75], s[4:5], 0, v[74:75]
	v_lshl_add_u64 v[94:95], v[90:91], 0, v[130:131]
	global_store_dwordx4 v[46:47], v[30:33], off offset:256
	v_cvt_pk_bf16_f32 v17, v12, v13
	v_lshl_add_u64 v[10:11], s[4:5], 0, v[10:11]
	v_lshl_add_u64 v[30:31], v[26:27], 0, v[130:131]
	v_cvt_pk_bf16_f32 v126, v126, v127
	v_cvt_pk_bf16_f32 v127, v128, v129
	v_cvt_pk_bf16_f32 v128, v122, v123
	v_cvt_pk_bf16_f32 v129, v124, v125
	v_cvt_pk_bf16_f32 v106, v118, v119
	v_cvt_pk_bf16_f32 v107, v120, v121
	v_cvt_pk_bf16_f32 v108, v114, v115
	v_cvt_pk_bf16_f32 v109, v116, v117
	v_cvt_pk_bf16_f32 v90, v102, v103
	v_cvt_pk_bf16_f32 v91, v104, v105
	v_cvt_pk_bf16_f32 v92, v98, v99
	v_cvt_pk_bf16_f32 v93, v100, v101
	global_store_dwordx4 v[94:95], v[78:81], off offset:256
	v_cvt_pk_bf16_f32 v76, v82, v83
	v_cvt_pk_bf16_f32 v77, v84, v85
	v_lshl_add_u64 v[78:79], v[74:75], 0, v[130:131]
	v_cvt_pk_bf16_f32 v74, v86, v87
	v_cvt_pk_bf16_f32 v75, v88, v89
	v_cvt_pk_bf16_f32 v73, v68, v69
	v_cvt_pk_bf16_f32 v62, v62, v63
	v_cvt_pk_bf16_f32 v63, v64, v65
	v_cvt_pk_bf16_f32 v64, v58, v59
	v_cvt_pk_bf16_f32 v65, v60, v61
	v_cvt_pk_bf16_f32 v42, v54, v55
	v_cvt_pk_bf16_f32 v43, v56, v57
	v_cvt_pk_bf16_f32 v44, v50, v51
	v_cvt_pk_bf16_f32 v45, v52, v53
	v_cvt_pk_bf16_f32 v26, v38, v39
	v_cvt_pk_bf16_f32 v27, v40, v41
	v_cvt_pk_bf16_f32 v28, v34, v35
	v_cvt_pk_bf16_f32 v29, v36, v37
	global_store_dwordx4 v[30:31], v[14:17], off offset:256
	v_cvt_pk_bf16_f32 v12, v18, v19
	v_cvt_pk_bf16_f32 v13, v20, v21
	v_lshl_add_u64 v[14:15], v[10:11], 0, v[130:131]
	v_cvt_pk_bf16_f32 v10, v22, v23
	v_cvt_pk_bf16_f32 v11, v24, v25
	v_cvt_pk_bf16_f32 v6, v6, v7
	v_cvt_pk_bf16_f32 v7, v8, v9
	v_cvt_pk_bf16_f32 v8, v2, v3
	v_cvt_pk_bf16_f32 v9, v4, v5
	global_store_dwordx4 v[132:133], v[126:129], off
	global_store_dwordx4 v[110:111], v[106:109], off
	global_store_dwordx4 v[94:95], v[90:93], off
	global_store_dwordx4 v[78:79], v[74:77], off
	global_store_dwordx4 v[78:79], v[70:73], off offset:256
	global_store_dwordx4 v[66:67], v[62:65], off
	global_store_dwordx4 v[46:47], v[42:45], off
	global_store_dwordx4 v[30:31], v[26:29], off
	global_store_dwordx4 v[14:15], v[10:13], off
	global_store_dwordx4 v[14:15], v[6:9], off offset:256
	s_waitcnt vmcnt(0)
	s_cmpk_lt_u32 s3, 0x100
	s_cbranch_scc0 .LBB0_2635
	s_barrier
